# K-loop MFMA segments: removed no-op setprio 0/1 pair and redundant lgkmcnt(0) after the barrier
# speedup vs baseline: 1.0756x; 1.0050x over previous
.LBB0_137:
	ds_read_b128 v[146:149], v178
	ds_read_b128 v[150:153], v178 offset:1024
	ds_read_b128 v[154:157], v178 offset:2048
	ds_read_b128 v[158:161], v178 offset:3072
	ds_read_b128 v[182:185], v179
	ds_read_b128 v[186:189], v179 offset:1024
	ds_read_b128 v[190:193], v179 offset:2048
	ds_read_b128 v[194:197], v179 offset:3072
	s_add_u32 s30, s28, 0xfffc0080
	s_addc_u32 s31, s29, -1
	s_cmp_eq_u32 s72, 12
	s_cselect_b32 s35, s21, s31
	s_cselect_b32 s34, s68, s30
	s_cselect_b32 s31, s19, s71
	s_cselect_b32 s30, s69, s70
	v_lshl_add_u64 v[162:163], s[28:29], 0, v[138:139]
	s_add_i32 m0, s27, 0xc000
	ds_read_b128 v[198:201], v180
	ds_read_b128 v[202:205], v180 offset:1024
	ds_read_b128 v[206:209], v180 offset:2048
	ds_read_b128 v[210:213], v180 offset:3072
	ds_read_b128 v[214:217], v180 offset:4096
	ds_read_b128 v[218:221], v180 offset:5120
	ds_read_b128 v[222:225], v180 offset:6144
	ds_read_b128 v[226:229], v180 offset:7168
	global_load_lds_dwordx4 v[162:163], off
	v_lshl_add_u64 v[162:163], s[28:29], 0, v[140:141]
	s_add_i32 m0, s27, 0xe000
	s_nop 0
	global_load_lds_dwordx4 v[162:163], off
	s_waitcnt vmcnt(8)
	s_waitcnt lgkmcnt(0)
	s_barrier
	s_setprio 1
	v_mfma_i32_16x16x64_i8 v[126:129], v[146:149], v[198:201], v[126:129]
	v_mfma_i32_16x16x64_i8 v[118:121], v[154:157], v[198:201], v[118:121]
	v_mfma_i32_16x16x64_i8 v[110:113], v[146:149], v[206:209], v[110:113]
	v_mfma_i32_16x16x64_i8 v[102:105], v[154:157], v[206:209], v[102:105]
	v_mfma_i32_16x16x64_i8 v[94:97], v[146:149], v[214:217], v[94:97]
	v_mfma_i32_16x16x64_i8 v[86:89], v[154:157], v[214:217], v[86:89]
	v_mfma_i32_16x16x64_i8 v[78:81], v[146:149], v[222:225], v[78:81]
	v_mfma_i32_16x16x64_i8 v[70:73], v[154:157], v[222:225], v[70:73]
	v_mfma_i32_16x16x64_i8 v[126:129], v[150:153], v[202:205], v[126:129]
	v_mfma_i32_16x16x64_i8 v[118:121], v[158:161], v[202:205], v[118:121]
	v_mfma_i32_16x16x64_i8 v[110:113], v[150:153], v[210:213], v[110:113]
	v_mfma_i32_16x16x64_i8 v[102:105], v[158:161], v[210:213], v[102:105]
	v_mfma_i32_16x16x64_i8 v[94:97], v[150:153], v[218:221], v[94:97]
	v_mfma_i32_16x16x64_i8 v[86:89], v[158:161], v[218:221], v[86:89]
	v_mfma_i32_16x16x64_i8 v[78:81], v[150:153], v[226:229], v[78:81]
	v_mfma_i32_16x16x64_i8 v[70:73], v[158:161], v[226:229], v[70:73]
	v_mfma_i32_16x16x64_i8 v[122:125], v[182:185], v[198:201], v[122:125]
	v_mfma_i32_16x16x64_i8 v[114:117], v[190:193], v[198:201], v[114:117]
	v_mfma_i32_16x16x64_i8 v[106:109], v[182:185], v[206:209], v[106:109]
	v_mfma_i32_16x16x64_i8 v[98:101], v[190:193], v[206:209], v[98:101]
	v_mfma_i32_16x16x64_i8 v[90:93], v[182:185], v[214:217], v[90:93]
	v_mfma_i32_16x16x64_i8 v[82:85], v[190:193], v[214:217], v[82:85]
	v_mfma_i32_16x16x64_i8 v[74:77], v[182:185], v[222:225], v[74:77]
	v_mfma_i32_16x16x64_i8 v[66:69], v[190:193], v[222:225], v[66:69]
	v_mfma_i32_16x16x64_i8 v[122:125], v[186:189], v[202:205], v[122:125]
	v_mfma_i32_16x16x64_i8 v[114:117], v[194:197], v[202:205], v[114:117]
	v_mfma_i32_16x16x64_i8 v[106:109], v[186:189], v[210:213], v[106:109]
	v_mfma_i32_16x16x64_i8 v[98:101], v[194:197], v[210:213], v[98:101]
	v_mfma_i32_16x16x64_i8 v[90:93], v[186:189], v[218:221], v[90:93]
	v_mfma_i32_16x16x64_i8 v[82:85], v[194:197], v[218:221], v[82:85]
	v_mfma_i32_16x16x64_i8 v[74:77], v[186:189], v[226:229], v[74:77]
	v_mfma_i32_16x16x64_i8 v[66:69], v[194:197], v[226:229], v[66:69]
	s_setprio 0
	s_barrier
	s_add_i32 s73, s46, s38
	v_lshl_add_u64 v[162:163], s[30:31], 0, v[134:135]
	s_mov_b32 m0, s73
	ds_read_b128 v[198:201], v180 offset:16384
	ds_read_b128 v[202:205], v180 offset:17408
	ds_read_b128 v[206:209], v180 offset:18432
	ds_read_b128 v[210:213], v180 offset:19456
	ds_read_b128 v[214:217], v180 offset:20480
	ds_read_b128 v[218:221], v180 offset:21504
	ds_read_b128 v[222:225], v180 offset:22528
	ds_read_b128 v[226:229], v180 offset:23552
	global_load_lds_dwordx4 v[162:163], off
	s_add_i32 m0, s73, 0x2000
	s_add_u32 s74, s30, 0x40000
	v_lshl_add_u64 v[230:231], s[30:31], 0, v[130:131]
	s_addc_u32 s75, s31, 0
	s_add_i32 s73, s47, s38
	global_load_lds_dwordx4 v[230:231], off
	v_lshl_add_u64 v[232:233], s[74:75], 0, v[134:135]
	s_mov_b32 m0, s73
	v_lshl_add_u64 v[234:235], s[34:35], 0, v[132:133]
	global_load_lds_dwordx4 v[232:233], off
	v_lshl_add_u64 v[232:233], s[74:75], 0, v[130:131]
	s_add_i32 m0, s73, 0x2000
	s_nop 0
	global_load_lds_dwordx4 v[232:233], off
	v_lshl_add_u64 v[232:233], s[34:35], 0, v[136:137]
	s_mov_b32 m0, s27
	s_nop 0
	global_load_lds_dwordx4 v[232:233], off
	s_mov_b32 m0, s40
	s_nop 0
	global_load_lds_dwordx4 v[234:235], off
	s_waitcnt vmcnt(8)
	s_waitcnt lgkmcnt(0)
	s_barrier
	s_setprio 1
	v_mfma_i32_16x16x64_i8 v[62:65], v[146:149], v[198:201], v[62:65]
	v_mfma_i32_16x16x64_i8 v[54:57], v[154:157], v[198:201], v[54:57]
	v_mfma_i32_16x16x64_i8 v[46:49], v[146:149], v[206:209], v[46:49]
	v_mfma_i32_16x16x64_i8 v[38:41], v[154:157], v[206:209], v[38:41]
	v_mfma_i32_16x16x64_i8 v[30:33], v[146:149], v[214:217], v[30:33]
	v_mfma_i32_16x16x64_i8 v[22:25], v[154:157], v[214:217], v[22:25]
	v_mfma_i32_16x16x64_i8 v[14:17], v[146:149], v[222:225], v[14:17]
	v_mfma_i32_16x16x64_i8 v[6:9], v[154:157], v[222:225], v[6:9]
	v_mfma_i32_16x16x64_i8 v[62:65], v[150:153], v[202:205], v[62:65]
	v_mfma_i32_16x16x64_i8 v[54:57], v[158:161], v[202:205], v[54:57]
	v_mfma_i32_16x16x64_i8 v[46:49], v[150:153], v[210:213], v[46:49]
	v_mfma_i32_16x16x64_i8 v[38:41], v[158:161], v[210:213], v[38:41]
	v_mfma_i32_16x16x64_i8 v[30:33], v[150:153], v[218:221], v[30:33]
	v_mfma_i32_16x16x64_i8 v[22:25], v[158:161], v[218:221], v[22:25]
	v_mfma_i32_16x16x64_i8 v[14:17], v[150:153], v[226:229], v[14:17]
	v_mfma_i32_16x16x64_i8 v[6:9], v[158:161], v[226:229], v[6:9]
	v_mfma_i32_16x16x64_i8 v[58:61], v[182:185], v[198:201], v[58:61]
	v_mfma_i32_16x16x64_i8 v[50:53], v[190:193], v[198:201], v[50:53]
	v_mfma_i32_16x16x64_i8 v[42:45], v[182:185], v[206:209], v[42:45]
	v_mfma_i32_16x16x64_i8 v[34:37], v[190:193], v[206:209], v[34:37]
	v_mfma_i32_16x16x64_i8 v[26:29], v[182:185], v[214:217], v[26:29]
	v_mfma_i32_16x16x64_i8 v[18:21], v[190:193], v[214:217], v[18:21]
	v_mfma_i32_16x16x64_i8 v[10:13], v[182:185], v[222:225], v[10:13]
	v_mfma_i32_16x16x64_i8 v[2:5], v[190:193], v[222:225], v[2:5]
	v_mfma_i32_16x16x64_i8 v[58:61], v[186:189], v[202:205], v[58:61]
	v_mfma_i32_16x16x64_i8 v[50:53], v[194:197], v[202:205], v[50:53]
	v_mfma_i32_16x16x64_i8 v[42:45], v[186:189], v[210:213], v[42:45]
	v_mfma_i32_16x16x64_i8 v[34:37], v[194:197], v[210:213], v[34:37]
	v_mfma_i32_16x16x64_i8 v[26:29], v[186:189], v[218:221], v[26:29]
	v_mfma_i32_16x16x64_i8 v[18:21], v[194:197], v[218:221], v[18:21]
	v_mfma_i32_16x16x64_i8 v[10:13], v[186:189], v[226:229], v[10:13]
	v_mfma_i32_16x16x64_i8 v[2:5], v[194:197], v[226:229], v[2:5]
	s_setprio 0
	s_barrier
	s_add_i32 s73, 0, 0x18000
	v_add_u32_e32 v158, s73, v169
	ds_read_b128 v[146:149], v158
	ds_read_b128 v[150:153], v158 offset:1024
	ds_read_b128 v[154:157], v158 offset:2048
	ds_read_b128 v[158:161], v158 offset:3072
	ds_read_b128 v[182:185], v181
	ds_read_b128 v[186:189], v181 offset:1024
	ds_read_b128 v[190:193], v181 offset:2048
	ds_read_b128 v[194:197], v181 offset:3072
	s_add_u32 s34, s34, 0x40000
	s_addc_u32 s35, s35, 0
	s_mov_b32 m0, s41
	v_lshl_add_u64 v[236:237], s[34:35], 0, v[136:137]
	ds_read_b128 v[198:201], v180 offset:32768
	ds_read_b128 v[202:205], v180 offset:33792
	ds_read_b128 v[206:209], v180 offset:34816
	ds_read_b128 v[210:213], v180 offset:35840
	ds_read_b128 v[214:217], v180 offset:36864
	ds_read_b128 v[218:221], v180 offset:37888
	ds_read_b128 v[222:225], v180 offset:38912
	ds_read_b128 v[226:229], v180 offset:39936
	global_load_lds_dwordx4 v[236:237], off
	v_lshl_add_u64 v[236:237], s[34:35], 0, v[132:133]
	s_mov_b32 m0, s42
	s_nop 0
	global_load_lds_dwordx4 v[236:237], off
	s_waitcnt vmcnt(8)
	s_waitcnt lgkmcnt(0)
	s_barrier
	s_setprio 1
	v_mfma_i32_16x16x64_i8 v[126:129], v[146:149], v[198:201], v[126:129]
	v_mfma_i32_16x16x64_i8 v[118:121], v[154:157], v[198:201], v[118:121]
	v_mfma_i32_16x16x64_i8 v[110:113], v[146:149], v[206:209], v[110:113]
	v_mfma_i32_16x16x64_i8 v[102:105], v[154:157], v[206:209], v[102:105]
	v_mfma_i32_16x16x64_i8 v[94:97], v[146:149], v[214:217], v[94:97]
	v_mfma_i32_16x16x64_i8 v[86:89], v[154:157], v[214:217], v[86:89]
	v_mfma_i32_16x16x64_i8 v[78:81], v[146:149], v[222:225], v[78:81]
	v_mfma_i32_16x16x64_i8 v[70:73], v[154:157], v[222:225], v[70:73]
	v_mfma_i32_16x16x64_i8 v[126:129], v[150:153], v[202:205], v[126:129]
	v_mfma_i32_16x16x64_i8 v[118:121], v[158:161], v[202:205], v[118:121]
	v_mfma_i32_16x16x64_i8 v[110:113], v[150:153], v[210:213], v[110:113]
	v_mfma_i32_16x16x64_i8 v[102:105], v[158:161], v[210:213], v[102:105]
	v_mfma_i32_16x16x64_i8 v[94:97], v[150:153], v[218:221], v[94:97]
	v_mfma_i32_16x16x64_i8 v[86:89], v[158:161], v[218:221], v[86:89]
	v_mfma_i32_16x16x64_i8 v[78:81], v[150:153], v[226:229], v[78:81]
	v_mfma_i32_16x16x64_i8 v[70:73], v[158:161], v[226:229], v[70:73]
	v_mfma_i32_16x16x64_i8 v[122:125], v[182:185], v[198:201], v[122:125]
	v_mfma_i32_16x16x64_i8 v[114:117], v[190:193], v[198:201], v[114:117]
	v_mfma_i32_16x16x64_i8 v[106:109], v[182:185], v[206:209], v[106:109]
	v_mfma_i32_16x16x64_i8 v[98:101], v[190:193], v[206:209], v[98:101]
	v_mfma_i32_16x16x64_i8 v[90:93], v[182:185], v[214:217], v[90:93]
	v_mfma_i32_16x16x64_i8 v[82:85], v[190:193], v[214:217], v[82:85]
	v_mfma_i32_16x16x64_i8 v[74:77], v[182:185], v[222:225], v[74:77]
	v_mfma_i32_16x16x64_i8 v[66:69], v[190:193], v[222:225], v[66:69]
	v_mfma_i32_16x16x64_i8 v[122:125], v[186:189], v[202:205], v[122:125]
	v_mfma_i32_16x16x64_i8 v[114:117], v[194:197], v[202:205], v[114:117]
	v_mfma_i32_16x16x64_i8 v[106:109], v[186:189], v[210:213], v[106:109]
	v_mfma_i32_16x16x64_i8 v[98:101], v[194:197], v[210:213], v[98:101]
	v_mfma_i32_16x16x64_i8 v[90:93], v[186:189], v[218:221], v[90:93]
	v_mfma_i32_16x16x64_i8 v[82:85], v[194:197], v[218:221], v[82:85]
	v_mfma_i32_16x16x64_i8 v[74:77], v[186:189], v[226:229], v[74:77]
	v_mfma_i32_16x16x64_i8 v[66:69], v[194:197], v[226:229], v[66:69]
	s_setprio 0
	s_barrier
	s_add_i32 s34, s73, s38
	v_lshl_add_u64 v[162:163], v[162:163], 0, s[10:11]
	s_mov_b32 m0, s34
	ds_read_b128 v[198:201], v180 offset:49152
	ds_read_b128 v[202:205], v180 offset:50176
	ds_read_b128 v[206:209], v180 offset:51200
	ds_read_b128 v[210:213], v180 offset:52224
	ds_read_b128 v[214:217], v180 offset:53248
	ds_read_b128 v[218:221], v180 offset:54272
	ds_read_b128 v[222:225], v180 offset:55296
	ds_read_b128 v[226:229], v180 offset:56320
	global_load_lds_dwordx4 v[162:163], off
	s_add_i32 m0, s34, 0x2000
	s_add_u32 s30, s30, 0x40080
	v_lshl_add_u64 v[162:163], v[230:231], 0, s[10:11]
	s_addc_u32 s31, s31, 0
	s_add_i32 s34, s63, s38
	global_load_lds_dwordx4 v[162:163], off
	v_lshl_add_u64 v[162:163], s[30:31], 0, v[134:135]
	s_mov_b32 m0, s34
	s_nop 0
	global_load_lds_dwordx4 v[162:163], off
	v_lshl_add_u64 v[162:163], s[30:31], 0, v[130:131]
	s_add_i32 m0, s34, 0x2000
	s_nop 0
	global_load_lds_dwordx4 v[162:163], off
	v_lshl_add_u64 v[162:163], v[232:233], 0, s[10:11]
	s_mov_b32 m0, s43
	s_nop 0
	global_load_lds_dwordx4 v[162:163], off
	v_lshl_add_u64 v[162:163], v[234:235], 0, s[10:11]
	s_mov_b32 m0, s44
	s_nop 0
	global_load_lds_dwordx4 v[162:163], off
	s_waitcnt vmcnt(8)
	s_waitcnt lgkmcnt(0)
	s_barrier
	s_setprio 1
	v_mfma_i32_16x16x64_i8 v[62:65], v[146:149], v[198:201], v[62:65]
	v_mfma_i32_16x16x64_i8 v[54:57], v[154:157], v[198:201], v[54:57]
	v_mfma_i32_16x16x64_i8 v[46:49], v[146:149], v[206:209], v[46:49]
	v_mfma_i32_16x16x64_i8 v[38:41], v[154:157], v[206:209], v[38:41]
	v_mfma_i32_16x16x64_i8 v[30:33], v[146:149], v[214:217], v[30:33]
	v_mfma_i32_16x16x64_i8 v[22:25], v[154:157], v[214:217], v[22:25]
	v_mfma_i32_16x16x64_i8 v[14:17], v[146:149], v[222:225], v[14:17]
	v_mfma_i32_16x16x64_i8 v[6:9], v[154:157], v[222:225], v[6:9]
	v_mfma_i32_16x16x64_i8 v[62:65], v[150:153], v[202:205], v[62:65]
	v_mfma_i32_16x16x64_i8 v[54:57], v[158:161], v[202:205], v[54:57]
	v_mfma_i32_16x16x64_i8 v[46:49], v[150:153], v[210:213], v[46:49]
	v_mfma_i32_16x16x64_i8 v[38:41], v[158:161], v[210:213], v[38:41]
	v_mfma_i32_16x16x64_i8 v[30:33], v[150:153], v[218:221], v[30:33]
	v_mfma_i32_16x16x64_i8 v[22:25], v[158:161], v[218:221], v[22:25]
	v_mfma_i32_16x16x64_i8 v[14:17], v[150:153], v[226:229], v[14:17]
	v_mfma_i32_16x16x64_i8 v[6:9], v[158:161], v[226:229], v[6:9]
	v_mfma_i32_16x16x64_i8 v[58:61], v[182:185], v[198:201], v[58:61]
	v_mfma_i32_16x16x64_i8 v[50:53], v[190:193], v[198:201], v[50:53]
	v_mfma_i32_16x16x64_i8 v[42:45], v[182:185], v[206:209], v[42:45]
	v_mfma_i32_16x16x64_i8 v[34:37], v[190:193], v[206:209], v[34:37]
	v_mfma_i32_16x16x64_i8 v[26:29], v[182:185], v[214:217], v[26:29]
	v_mfma_i32_16x16x64_i8 v[18:21], v[190:193], v[214:217], v[18:21]
	v_mfma_i32_16x16x64_i8 v[10:13], v[182:185], v[222:225], v[10:13]
	v_mfma_i32_16x16x64_i8 v[2:5], v[190:193], v[222:225], v[2:5]
	v_mfma_i32_16x16x64_i8 v[58:61], v[186:189], v[202:205], v[58:61]
	v_mfma_i32_16x16x64_i8 v[50:53], v[194:197], v[202:205], v[50:53]
	v_mfma_i32_16x16x64_i8 v[42:45], v[186:189], v[210:213], v[42:45]
	v_mfma_i32_16x16x64_i8 v[34:37], v[194:197], v[210:213], v[34:37]
	v_mfma_i32_16x16x64_i8 v[26:29], v[186:189], v[218:221], v[26:29]
	v_mfma_i32_16x16x64_i8 v[18:21], v[194:197], v[218:221], v[18:21]
	v_mfma_i32_16x16x64_i8 v[10:13], v[186:189], v[226:229], v[10:13]
	v_mfma_i32_16x16x64_i8 v[2:5], v[194:197], v[226:229], v[2:5]
	s_setprio 0
	s_barrier
	s_add_i32 s72, s72, 2
	s_add_u32 s28, s28, 0x100
	s_addc_u32 s29, s29, 0
	s_add_u32 s70, s70, 0x100
	s_addc_u32 s71, s71, 0
	s_cmp_gt_u32 s72, 13
	s_cbranch_scc0 .LBB0_137
	s_and_b64 vcc, exec, s[14:15]
	s_cbranch_vccz .LBB0_140
	s_barrier

.LBB0_246:
	ds_read_b128 v[154:157], v149
	ds_read_b128 v[158:161], v149 offset:1024
	ds_read_b128 v[162:165], v149 offset:2048
	ds_read_b128 v[170:173], v149 offset:3072
	ds_read_b128 v[174:177], v150
	ds_read_b128 v[178:181], v150 offset:1024
	ds_read_b128 v[182:185], v150 offset:2048
	ds_read_b128 v[186:189], v150 offset:3072
	s_add_u32 s20, s18, 0xffea0080
	s_addc_u32 s21, s19, -1
	s_cmpk_eq_i32 s46, 0x54
	s_cselect_b32 s23, s7, s21
	s_cselect_b32 s22, s6, s20
	s_cselect_b32 s21, s17, s45
	s_cselect_b32 s20, s16, s44
	v_lshl_add_u64 v[146:147], s[18:19], 0, v[138:139]
	s_add_i32 m0, s26, 0xc000
	ds_read_b128 v[190:193], v151
	ds_read_b128 v[194:197], v151 offset:1024
	ds_read_b128 v[198:201], v151 offset:2048
	ds_read_b128 v[202:205], v151 offset:3072
	ds_read_b128 v[206:209], v151 offset:4096
	ds_read_b128 v[210:213], v151 offset:5120
	ds_read_b128 v[214:217], v151 offset:6144
	ds_read_b128 v[218:221], v151 offset:7168
	global_load_lds_dwordx4 v[146:147], off
	v_lshl_add_u64 v[146:147], s[18:19], 0, v[140:141]
	s_add_i32 m0, s26, 0xe000
	s_nop 0
	global_load_lds_dwordx4 v[146:147], off
	s_waitcnt vmcnt(8)
	s_waitcnt lgkmcnt(0)
	s_barrier
	s_setprio 1
	v_mfma_f32_16x16x32_bf16 v[126:129], v[154:157], v[190:193], v[126:129]
	v_mfma_f32_16x16x32_bf16 v[122:125], v[162:165], v[190:193], v[122:125]
	v_mfma_f32_16x16x32_bf16 v[118:121], v[154:157], v[198:201], v[118:121]
	v_mfma_f32_16x16x32_bf16 v[110:113], v[162:165], v[198:201], v[110:113]
	v_mfma_f32_16x16x32_bf16 v[102:105], v[154:157], v[206:209], v[102:105]
	v_mfma_f32_16x16x32_bf16 v[94:97], v[162:165], v[206:209], v[94:97]
	v_mfma_f32_16x16x32_bf16 v[86:89], v[154:157], v[214:217], v[86:89]
	v_mfma_f32_16x16x32_bf16 v[78:81], v[162:165], v[214:217], v[78:81]
	v_mfma_f32_16x16x32_bf16 v[126:129], v[158:161], v[194:197], v[126:129]
	v_mfma_f32_16x16x32_bf16 v[122:125], v[170:173], v[194:197], v[122:125]
	v_mfma_f32_16x16x32_bf16 v[118:121], v[158:161], v[202:205], v[118:121]
	v_mfma_f32_16x16x32_bf16 v[110:113], v[170:173], v[202:205], v[110:113]
	v_mfma_f32_16x16x32_bf16 v[102:105], v[158:161], v[210:213], v[102:105]
	v_mfma_f32_16x16x32_bf16 v[94:97], v[170:173], v[210:213], v[94:97]
	v_mfma_f32_16x16x32_bf16 v[86:89], v[158:161], v[218:221], v[86:89]
	v_mfma_f32_16x16x32_bf16 v[78:81], v[170:173], v[218:221], v[78:81]
	v_mfma_f32_16x16x32_bf16 v[114:117], v[174:177], v[190:193], v[114:117]
	v_mfma_f32_16x16x32_bf16 v[106:109], v[182:185], v[190:193], v[106:109]
	v_mfma_f32_16x16x32_bf16 v[98:101], v[174:177], v[198:201], v[98:101]
	v_mfma_f32_16x16x32_bf16 v[90:93], v[182:185], v[198:201], v[90:93]
	v_mfma_f32_16x16x32_bf16 v[82:85], v[174:177], v[206:209], v[82:85]
	v_mfma_f32_16x16x32_bf16 v[74:77], v[182:185], v[206:209], v[74:77]
	v_mfma_f32_16x16x32_bf16 v[70:73], v[174:177], v[214:217], v[70:73]
	v_mfma_f32_16x16x32_bf16 v[66:69], v[182:185], v[214:217], v[66:69]
	v_mfma_f32_16x16x32_bf16 v[114:117], v[178:181], v[194:197], v[114:117]
	v_mfma_f32_16x16x32_bf16 v[106:109], v[186:189], v[194:197], v[106:109]
	v_mfma_f32_16x16x32_bf16 v[98:101], v[178:181], v[202:205], v[98:101]
	v_mfma_f32_16x16x32_bf16 v[90:93], v[186:189], v[202:205], v[90:93]
	v_mfma_f32_16x16x32_bf16 v[82:85], v[178:181], v[210:213], v[82:85]
	v_mfma_f32_16x16x32_bf16 v[74:77], v[186:189], v[210:213], v[74:77]
	v_mfma_f32_16x16x32_bf16 v[70:73], v[178:181], v[218:221], v[70:73]
	v_mfma_f32_16x16x32_bf16 v[66:69], v[186:189], v[218:221], v[66:69]
	s_setprio 0
	s_barrier
	s_add_i32 s47, s36, s25
	v_lshl_add_u64 v[146:147], s[20:21], 0, v[132:133]
	s_mov_b32 m0, s47
	ds_read_b128 v[190:193], v151 offset:16384
	ds_read_b128 v[194:197], v151 offset:17408
	ds_read_b128 v[198:201], v151 offset:18432
	ds_read_b128 v[202:205], v151 offset:19456
	ds_read_b128 v[206:209], v151 offset:20480
	ds_read_b128 v[210:213], v151 offset:21504
	ds_read_b128 v[214:217], v151 offset:22528
	ds_read_b128 v[218:221], v151 offset:23552
	global_load_lds_dwordx4 v[146:147], off
	s_add_i32 m0, s47, 0x2000
	s_add_u32 s66, s20, 0x160000
	v_lshl_add_u64 v[222:223], s[20:21], 0, v[136:137]
	s_addc_u32 s67, s21, 0
	s_add_i32 s47, s37, s25
	global_load_lds_dwordx4 v[222:223], off
	v_lshl_add_u64 v[224:225], s[66:67], 0, v[132:133]
	s_mov_b32 m0, s47
	v_lshl_add_u64 v[226:227], s[22:23], 0, v[134:135]
	global_load_lds_dwordx4 v[224:225], off
	v_lshl_add_u64 v[224:225], s[66:67], 0, v[136:137]
	s_add_i32 m0, s47, 0x2000
	s_nop 0
	global_load_lds_dwordx4 v[224:225], off
	v_lshl_add_u64 v[224:225], s[22:23], 0, v[130:131]
	s_mov_b32 m0, s26
	s_nop 0
	global_load_lds_dwordx4 v[224:225], off
	s_mov_b32 m0, s27
	s_nop 0
	global_load_lds_dwordx4 v[226:227], off
	s_waitcnt vmcnt(8)
	s_waitcnt lgkmcnt(0)
	s_barrier
	s_setprio 1
	v_mfma_f32_16x16x32_bf16 v[62:65], v[154:157], v[190:193], v[62:65]
	v_mfma_f32_16x16x32_bf16 v[58:61], v[162:165], v[190:193], v[58:61]
	v_mfma_f32_16x16x32_bf16 v[54:57], v[154:157], v[198:201], v[54:57]
	v_mfma_f32_16x16x32_bf16 v[46:49], v[162:165], v[198:201], v[46:49]
	v_mfma_f32_16x16x32_bf16 v[38:41], v[154:157], v[206:209], v[38:41]
	v_mfma_f32_16x16x32_bf16 v[30:33], v[162:165], v[206:209], v[30:33]
	v_mfma_f32_16x16x32_bf16 v[22:25], v[154:157], v[214:217], v[22:25]
	v_mfma_f32_16x16x32_bf16 v[14:17], v[162:165], v[214:217], v[14:17]
	v_mfma_f32_16x16x32_bf16 v[62:65], v[158:161], v[194:197], v[62:65]
	v_mfma_f32_16x16x32_bf16 v[58:61], v[170:173], v[194:197], v[58:61]
	v_mfma_f32_16x16x32_bf16 v[54:57], v[158:161], v[202:205], v[54:57]
	v_mfma_f32_16x16x32_bf16 v[46:49], v[170:173], v[202:205], v[46:49]
	v_mfma_f32_16x16x32_bf16 v[38:41], v[158:161], v[210:213], v[38:41]
	v_mfma_f32_16x16x32_bf16 v[30:33], v[170:173], v[210:213], v[30:33]
	v_mfma_f32_16x16x32_bf16 v[22:25], v[158:161], v[218:221], v[22:25]
	v_mfma_f32_16x16x32_bf16 v[14:17], v[170:173], v[218:221], v[14:17]
	v_mfma_f32_16x16x32_bf16 v[50:53], v[174:177], v[190:193], v[50:53]
	v_mfma_f32_16x16x32_bf16 v[42:45], v[182:185], v[190:193], v[42:45]
	v_mfma_f32_16x16x32_bf16 v[34:37], v[174:177], v[198:201], v[34:37]
	v_mfma_f32_16x16x32_bf16 v[26:29], v[182:185], v[198:201], v[26:29]
	v_mfma_f32_16x16x32_bf16 v[18:21], v[174:177], v[206:209], v[18:21]
	v_mfma_f32_16x16x32_bf16 v[10:13], v[182:185], v[206:209], v[10:13]
	v_mfma_f32_16x16x32_bf16 v[6:9], v[174:177], v[214:217], v[6:9]
	v_mfma_f32_16x16x32_bf16 v[2:5], v[182:185], v[214:217], v[2:5]
	v_mfma_f32_16x16x32_bf16 v[50:53], v[178:181], v[194:197], v[50:53]
	v_mfma_f32_16x16x32_bf16 v[42:45], v[186:189], v[194:197], v[42:45]
	v_mfma_f32_16x16x32_bf16 v[34:37], v[178:181], v[202:205], v[34:37]
	v_mfma_f32_16x16x32_bf16 v[26:29], v[186:189], v[202:205], v[26:29]
	v_mfma_f32_16x16x32_bf16 v[18:21], v[178:181], v[210:213], v[18:21]
	v_mfma_f32_16x16x32_bf16 v[10:13], v[186:189], v[210:213], v[10:13]
	v_mfma_f32_16x16x32_bf16 v[6:9], v[178:181], v[218:221], v[6:9]
	v_mfma_f32_16x16x32_bf16 v[2:5], v[186:189], v[218:221], v[2:5]
	s_setprio 0
	s_barrier
	ds_read_b128 v[154:157], v152
	ds_read_b128 v[158:161], v152 offset:1024
	ds_read_b128 v[162:165], v152 offset:2048
	ds_read_b128 v[170:173], v152 offset:3072
	ds_read_b128 v[174:177], v153
	ds_read_b128 v[178:181], v153 offset:1024
	ds_read_b128 v[182:185], v153 offset:2048
	ds_read_b128 v[186:189], v153 offset:3072
	s_add_u32 s22, s22, 0x160000
	s_addc_u32 s23, s23, 0
	s_mov_b32 m0, s28
	v_lshl_add_u64 v[228:229], s[22:23], 0, v[130:131]
	ds_read_b128 v[190:193], v151 offset:32768
	ds_read_b128 v[194:197], v151 offset:33792
	ds_read_b128 v[198:201], v151 offset:34816
	ds_read_b128 v[202:205], v151 offset:35840
	ds_read_b128 v[206:209], v151 offset:36864
	ds_read_b128 v[210:213], v151 offset:37888
	ds_read_b128 v[214:217], v151 offset:38912
	ds_read_b128 v[218:221], v151 offset:39936
	global_load_lds_dwordx4 v[228:229], off
	v_lshl_add_u64 v[228:229], s[22:23], 0, v[134:135]
	s_mov_b32 m0, s29
	s_nop 0
	global_load_lds_dwordx4 v[228:229], off
	s_waitcnt vmcnt(8)
	s_waitcnt lgkmcnt(0)
	s_barrier
	s_setprio 1
	v_mfma_f32_16x16x32_bf16 v[126:129], v[154:157], v[190:193], v[126:129]
	v_mfma_f32_16x16x32_bf16 v[122:125], v[162:165], v[190:193], v[122:125]
	v_mfma_f32_16x16x32_bf16 v[118:121], v[154:157], v[198:201], v[118:121]
	v_mfma_f32_16x16x32_bf16 v[110:113], v[162:165], v[198:201], v[110:113]
	v_mfma_f32_16x16x32_bf16 v[102:105], v[154:157], v[206:209], v[102:105]
	v_mfma_f32_16x16x32_bf16 v[94:97], v[162:165], v[206:209], v[94:97]
	v_mfma_f32_16x16x32_bf16 v[86:89], v[154:157], v[214:217], v[86:89]
	v_mfma_f32_16x16x32_bf16 v[78:81], v[162:165], v[214:217], v[78:81]
	v_mfma_f32_16x16x32_bf16 v[126:129], v[158:161], v[194:197], v[126:129]
	v_mfma_f32_16x16x32_bf16 v[122:125], v[170:173], v[194:197], v[122:125]
	v_mfma_f32_16x16x32_bf16 v[118:121], v[158:161], v[202:205], v[118:121]
	v_mfma_f32_16x16x32_bf16 v[110:113], v[170:173], v[202:205], v[110:113]
	v_mfma_f32_16x16x32_bf16 v[102:105], v[158:161], v[210:213], v[102:105]
	v_mfma_f32_16x16x32_bf16 v[94:97], v[170:173], v[210:213], v[94:97]
	v_mfma_f32_16x16x32_bf16 v[86:89], v[158:161], v[218:221], v[86:89]
	v_mfma_f32_16x16x32_bf16 v[78:81], v[170:173], v[218:221], v[78:81]
	v_mfma_f32_16x16x32_bf16 v[114:117], v[174:177], v[190:193], v[114:117]
	v_mfma_f32_16x16x32_bf16 v[106:109], v[182:185], v[190:193], v[106:109]
	v_mfma_f32_16x16x32_bf16 v[98:101], v[174:177], v[198:201], v[98:101]
	v_mfma_f32_16x16x32_bf16 v[90:93], v[182:185], v[198:201], v[90:93]
	v_mfma_f32_16x16x32_bf16 v[82:85], v[174:177], v[206:209], v[82:85]
	v_mfma_f32_16x16x32_bf16 v[74:77], v[182:185], v[206:209], v[74:77]
	v_mfma_f32_16x16x32_bf16 v[70:73], v[174:177], v[214:217], v[70:73]
	v_mfma_f32_16x16x32_bf16 v[66:69], v[182:185], v[214:217], v[66:69]
	v_mfma_f32_16x16x32_bf16 v[114:117], v[178:181], v[194:197], v[114:117]
	v_mfma_f32_16x16x32_bf16 v[106:109], v[186:189], v[194:197], v[106:109]
	v_mfma_f32_16x16x32_bf16 v[98:101], v[178:181], v[202:205], v[98:101]
	v_mfma_f32_16x16x32_bf16 v[90:93], v[186:189], v[202:205], v[90:93]
	v_mfma_f32_16x16x32_bf16 v[82:85], v[178:181], v[210:213], v[82:85]
	v_mfma_f32_16x16x32_bf16 v[74:77], v[186:189], v[210:213], v[74:77]
	v_mfma_f32_16x16x32_bf16 v[70:73], v[178:181], v[218:221], v[70:73]
	v_mfma_f32_16x16x32_bf16 v[66:69], v[186:189], v[218:221], v[66:69]
	s_setprio 0
	s_barrier
	s_add_i32 s22, s38, s25
	v_lshl_add_u64 v[146:147], v[146:147], 0, s[8:9]
	s_mov_b32 m0, s22
	ds_read_b128 v[190:193], v151 offset:49152
	ds_read_b128 v[194:197], v151 offset:50176
	ds_read_b128 v[198:201], v151 offset:51200
	ds_read_b128 v[202:205], v151 offset:52224
	ds_read_b128 v[206:209], v151 offset:53248
	ds_read_b128 v[210:213], v151 offset:54272
	ds_read_b128 v[214:217], v151 offset:55296
	ds_read_b128 v[218:221], v151 offset:56320
	global_load_lds_dwordx4 v[146:147], off
	s_add_i32 m0, s22, 0x2000
	s_add_u32 s20, s20, 0x160080
	v_lshl_add_u64 v[146:147], v[222:223], 0, s[8:9]
	s_addc_u32 s21, s21, 0
	s_add_i32 s22, s39, s25
	global_load_lds_dwordx4 v[146:147], off
	v_lshl_add_u64 v[146:147], s[20:21], 0, v[132:133]
	s_mov_b32 m0, s22
	s_nop 0
	global_load_lds_dwordx4 v[146:147], off
	v_lshl_add_u64 v[146:147], s[20:21], 0, v[136:137]
	s_add_i32 m0, s22, 0x2000
	s_nop 0
	global_load_lds_dwordx4 v[146:147], off
	v_lshl_add_u64 v[146:147], v[224:225], 0, s[8:9]
	s_mov_b32 m0, s30
	s_nop 0
	global_load_lds_dwordx4 v[146:147], off
	v_lshl_add_u64 v[146:147], v[226:227], 0, s[8:9]
	s_mov_b32 m0, s31
	s_nop 0
	global_load_lds_dwordx4 v[146:147], off
	s_waitcnt vmcnt(8)
	s_waitcnt lgkmcnt(0)
	s_barrier
	s_setprio 1
	v_mfma_f32_16x16x32_bf16 v[62:65], v[154:157], v[190:193], v[62:65]
	v_mfma_f32_16x16x32_bf16 v[58:61], v[162:165], v[190:193], v[58:61]
	v_mfma_f32_16x16x32_bf16 v[54:57], v[154:157], v[198:201], v[54:57]
	v_mfma_f32_16x16x32_bf16 v[46:49], v[162:165], v[198:201], v[46:49]
	v_mfma_f32_16x16x32_bf16 v[38:41], v[154:157], v[206:209], v[38:41]
	v_mfma_f32_16x16x32_bf16 v[30:33], v[162:165], v[206:209], v[30:33]
	v_mfma_f32_16x16x32_bf16 v[22:25], v[154:157], v[214:217], v[22:25]
	v_mfma_f32_16x16x32_bf16 v[14:17], v[162:165], v[214:217], v[14:17]
	v_mfma_f32_16x16x32_bf16 v[62:65], v[158:161], v[194:197], v[62:65]
	v_mfma_f32_16x16x32_bf16 v[58:61], v[170:173], v[194:197], v[58:61]
	v_mfma_f32_16x16x32_bf16 v[54:57], v[158:161], v[202:205], v[54:57]
	v_mfma_f32_16x16x32_bf16 v[46:49], v[170:173], v[202:205], v[46:49]
	v_mfma_f32_16x16x32_bf16 v[38:41], v[158:161], v[210:213], v[38:41]
	v_mfma_f32_16x16x32_bf16 v[30:33], v[170:173], v[210:213], v[30:33]
	v_mfma_f32_16x16x32_bf16 v[22:25], v[158:161], v[218:221], v[22:25]
	v_mfma_f32_16x16x32_bf16 v[14:17], v[170:173], v[218:221], v[14:17]
	v_mfma_f32_16x16x32_bf16 v[50:53], v[174:177], v[190:193], v[50:53]
	v_mfma_f32_16x16x32_bf16 v[42:45], v[182:185], v[190:193], v[42:45]
	v_mfma_f32_16x16x32_bf16 v[34:37], v[174:177], v[198:201], v[34:37]
	v_mfma_f32_16x16x32_bf16 v[26:29], v[182:185], v[198:201], v[26:29]
	v_mfma_f32_16x16x32_bf16 v[18:21], v[174:177], v[206:209], v[18:21]
	v_mfma_f32_16x16x32_bf16 v[10:13], v[182:185], v[206:209], v[10:13]
	v_mfma_f32_16x16x32_bf16 v[6:9], v[174:177], v[214:217], v[6:9]
	v_mfma_f32_16x16x32_bf16 v[2:5], v[182:185], v[214:217], v[2:5]
	v_mfma_f32_16x16x32_bf16 v[50:53], v[178:181], v[194:197], v[50:53]
	v_mfma_f32_16x16x32_bf16 v[42:45], v[186:189], v[194:197], v[42:45]
	v_mfma_f32_16x16x32_bf16 v[34:37], v[178:181], v[202:205], v[34:37]
	v_mfma_f32_16x16x32_bf16 v[26:29], v[186:189], v[202:205], v[26:29]
	v_mfma_f32_16x16x32_bf16 v[18:21], v[178:181], v[210:213], v[18:21]
	v_mfma_f32_16x16x32_bf16 v[10:13], v[186:189], v[210:213], v[10:13]
	v_mfma_f32_16x16x32_bf16 v[6:9], v[178:181], v[218:221], v[6:9]
	v_mfma_f32_16x16x32_bf16 v[2:5], v[186:189], v[218:221], v[2:5]
	s_setprio 0
	s_barrier
	s_add_i32 s46, s46, 2
	s_add_u32 s18, s18, 0x100
	s_addc_u32 s19, s19, 0
	s_add_u32 s44, s44, 0x100
	s_addc_u32 s45, s45, 0
	s_cmpk_gt_u32 s46, 0x55
	s_cbranch_scc0 .LBB0_246
	s_and_b64 vcc, exec, s[14:15]
	s_cbranch_vccz .LBB0_249
	s_barrier

.LBB0_388:
	ds_read_b128 v[146:149], v154
	ds_read_b128 v[160:163], v154 offset:1024
	ds_read_b128 v[170:173], v154 offset:2048
	ds_read_b128 v[174:177], v154 offset:3072
	ds_read_b128 v[178:181], v155
	ds_read_b128 v[182:185], v155 offset:1024
	ds_read_b128 v[186:189], v155 offset:2048
	ds_read_b128 v[190:193], v155 offset:3072
	s_add_u32 s24, s22, 0xfff80080
	s_addc_u32 s25, s23, -1
	s_cmp_eq_u32 s71, 28
	s_cselect_b32 s27, s15, s25
	s_cselect_b32 s26, s67, s24
	s_cselect_b32 s25, s13, s70
	s_cselect_b32 s24, s68, s69
	v_lshl_add_u64 v[164:165], s[22:23], 0, v[138:139]
	s_add_i32 m0, s21, 0xc000
	ds_read_b128 v[194:197], v156
	ds_read_b128 v[198:201], v156 offset:1024
	ds_read_b128 v[202:205], v156 offset:2048
	ds_read_b128 v[206:209], v156 offset:3072
	ds_read_b128 v[210:213], v156 offset:4096
	ds_read_b128 v[214:217], v156 offset:5120
	ds_read_b128 v[218:221], v156 offset:6144
	ds_read_b128 v[222:225], v156 offset:7168
	global_load_lds_dwordx4 v[164:165], off
	v_lshl_add_u64 v[164:165], s[22:23], 0, v[140:141]
	s_add_i32 m0, s21, 0xe000
	s_nop 0
	global_load_lds_dwordx4 v[164:165], off
	s_waitcnt vmcnt(8)
	s_waitcnt lgkmcnt(0)
	s_barrier
	s_setprio 1
	v_mfma_f32_16x16x32_bf16 v[126:129], v[146:149], v[194:197], v[126:129]
	v_mfma_f32_16x16x32_bf16 v[122:125], v[170:173], v[194:197], v[122:125]
	v_mfma_f32_16x16x32_bf16 v[118:121], v[146:149], v[202:205], v[118:121]
	v_mfma_f32_16x16x32_bf16 v[110:113], v[170:173], v[202:205], v[110:113]
	v_mfma_f32_16x16x32_bf16 v[102:105], v[146:149], v[210:213], v[102:105]
	v_mfma_f32_16x16x32_bf16 v[94:97], v[170:173], v[210:213], v[94:97]
	v_mfma_f32_16x16x32_bf16 v[86:89], v[146:149], v[218:221], v[86:89]
	v_mfma_f32_16x16x32_bf16 v[78:81], v[170:173], v[218:221], v[78:81]
	v_mfma_f32_16x16x32_bf16 v[126:129], v[160:163], v[198:201], v[126:129]
	v_mfma_f32_16x16x32_bf16 v[122:125], v[174:177], v[198:201], v[122:125]
	v_mfma_f32_16x16x32_bf16 v[118:121], v[160:163], v[206:209], v[118:121]
	v_mfma_f32_16x16x32_bf16 v[110:113], v[174:177], v[206:209], v[110:113]
	v_mfma_f32_16x16x32_bf16 v[102:105], v[160:163], v[214:217], v[102:105]
	v_mfma_f32_16x16x32_bf16 v[94:97], v[174:177], v[214:217], v[94:97]
	v_mfma_f32_16x16x32_bf16 v[86:89], v[160:163], v[222:225], v[86:89]
	v_mfma_f32_16x16x32_bf16 v[78:81], v[174:177], v[222:225], v[78:81]
	v_mfma_f32_16x16x32_bf16 v[114:117], v[178:181], v[194:197], v[114:117]
	v_mfma_f32_16x16x32_bf16 v[106:109], v[186:189], v[194:197], v[106:109]
	v_mfma_f32_16x16x32_bf16 v[98:101], v[178:181], v[202:205], v[98:101]
	v_mfma_f32_16x16x32_bf16 v[90:93], v[186:189], v[202:205], v[90:93]
	v_mfma_f32_16x16x32_bf16 v[82:85], v[178:181], v[210:213], v[82:85]
	v_mfma_f32_16x16x32_bf16 v[74:77], v[186:189], v[210:213], v[74:77]
	v_mfma_f32_16x16x32_bf16 v[70:73], v[178:181], v[218:221], v[70:73]
	v_mfma_f32_16x16x32_bf16 v[66:69], v[186:189], v[218:221], v[66:69]
	v_mfma_f32_16x16x32_bf16 v[114:117], v[182:185], v[198:201], v[114:117]
	v_mfma_f32_16x16x32_bf16 v[106:109], v[190:193], v[198:201], v[106:109]
	v_mfma_f32_16x16x32_bf16 v[98:101], v[182:185], v[206:209], v[98:101]
	v_mfma_f32_16x16x32_bf16 v[90:93], v[190:193], v[206:209], v[90:93]
	v_mfma_f32_16x16x32_bf16 v[82:85], v[182:185], v[214:217], v[82:85]
	v_mfma_f32_16x16x32_bf16 v[74:77], v[190:193], v[214:217], v[74:77]
	v_mfma_f32_16x16x32_bf16 v[70:73], v[182:185], v[222:225], v[70:73]
	v_mfma_f32_16x16x32_bf16 v[66:69], v[190:193], v[222:225], v[66:69]
	s_setprio 0
	s_barrier
	s_add_i32 s72, s41, s30
	v_lshl_add_u64 v[164:165], s[24:25], 0, v[134:135]
	s_mov_b32 m0, s72
	ds_read_b128 v[194:197], v156 offset:16384
	ds_read_b128 v[198:201], v156 offset:17408
	ds_read_b128 v[202:205], v156 offset:18432
	ds_read_b128 v[206:209], v156 offset:19456
	ds_read_b128 v[210:213], v156 offset:20480
	ds_read_b128 v[214:217], v156 offset:21504
	ds_read_b128 v[218:221], v156 offset:22528
	ds_read_b128 v[222:225], v156 offset:23552
	global_load_lds_dwordx4 v[164:165], off
	s_add_i32 m0, s72, 0x2000
	s_add_u32 s72, s24, 0x80000
	v_lshl_add_u64 v[226:227], s[24:25], 0, v[130:131]
	s_addc_u32 s73, s25, 0
	s_add_i32 s74, s46, s30
	global_load_lds_dwordx4 v[226:227], off
	v_lshl_add_u64 v[228:229], s[72:73], 0, v[134:135]
	s_mov_b32 m0, s74
	v_lshl_add_u64 v[230:231], s[26:27], 0, v[132:133]
	global_load_lds_dwordx4 v[228:229], off
	v_lshl_add_u64 v[228:229], s[72:73], 0, v[130:131]
	s_add_i32 m0, s74, 0x2000
	s_nop 0
	global_load_lds_dwordx4 v[228:229], off
	v_lshl_add_u64 v[228:229], s[26:27], 0, v[136:137]
	s_mov_b32 m0, s21
	s_nop 0
	global_load_lds_dwordx4 v[228:229], off
	s_mov_b32 m0, s34
	s_nop 0
	global_load_lds_dwordx4 v[230:231], off
	s_waitcnt vmcnt(8)
	s_waitcnt lgkmcnt(0)
	s_barrier
	s_setprio 1
	v_mfma_f32_16x16x32_bf16 v[62:65], v[146:149], v[194:197], v[62:65]
	v_mfma_f32_16x16x32_bf16 v[58:61], v[170:173], v[194:197], v[58:61]
	v_mfma_f32_16x16x32_bf16 v[54:57], v[146:149], v[202:205], v[54:57]
	v_mfma_f32_16x16x32_bf16 v[46:49], v[170:173], v[202:205], v[46:49]
	v_mfma_f32_16x16x32_bf16 v[38:41], v[146:149], v[210:213], v[38:41]
	v_mfma_f32_16x16x32_bf16 v[30:33], v[170:173], v[210:213], v[30:33]
	v_mfma_f32_16x16x32_bf16 v[22:25], v[146:149], v[218:221], v[22:25]
	v_mfma_f32_16x16x32_bf16 v[14:17], v[170:173], v[218:221], v[14:17]
	v_mfma_f32_16x16x32_bf16 v[62:65], v[160:163], v[198:201], v[62:65]
	v_mfma_f32_16x16x32_bf16 v[58:61], v[174:177], v[198:201], v[58:61]
	v_mfma_f32_16x16x32_bf16 v[54:57], v[160:163], v[206:209], v[54:57]
	v_mfma_f32_16x16x32_bf16 v[46:49], v[174:177], v[206:209], v[46:49]
	v_mfma_f32_16x16x32_bf16 v[38:41], v[160:163], v[214:217], v[38:41]
	v_mfma_f32_16x16x32_bf16 v[30:33], v[174:177], v[214:217], v[30:33]
	v_mfma_f32_16x16x32_bf16 v[22:25], v[160:163], v[222:225], v[22:25]
	v_mfma_f32_16x16x32_bf16 v[14:17], v[174:177], v[222:225], v[14:17]
	v_mfma_f32_16x16x32_bf16 v[50:53], v[178:181], v[194:197], v[50:53]
	v_mfma_f32_16x16x32_bf16 v[42:45], v[186:189], v[194:197], v[42:45]
	v_mfma_f32_16x16x32_bf16 v[34:37], v[178:181], v[202:205], v[34:37]
	v_mfma_f32_16x16x32_bf16 v[26:29], v[186:189], v[202:205], v[26:29]
	v_mfma_f32_16x16x32_bf16 v[18:21], v[178:181], v[210:213], v[18:21]
	v_mfma_f32_16x16x32_bf16 v[10:13], v[186:189], v[210:213], v[10:13]
	v_mfma_f32_16x16x32_bf16 v[6:9], v[178:181], v[218:221], v[6:9]
	v_mfma_f32_16x16x32_bf16 v[2:5], v[186:189], v[218:221], v[2:5]
	v_mfma_f32_16x16x32_bf16 v[50:53], v[182:185], v[198:201], v[50:53]
	v_mfma_f32_16x16x32_bf16 v[42:45], v[190:193], v[198:201], v[42:45]
	v_mfma_f32_16x16x32_bf16 v[34:37], v[182:185], v[206:209], v[34:37]
	v_mfma_f32_16x16x32_bf16 v[26:29], v[190:193], v[206:209], v[26:29]
	v_mfma_f32_16x16x32_bf16 v[18:21], v[182:185], v[214:217], v[18:21]
	v_mfma_f32_16x16x32_bf16 v[10:13], v[190:193], v[214:217], v[10:13]
	v_mfma_f32_16x16x32_bf16 v[6:9], v[182:185], v[222:225], v[6:9]
	v_mfma_f32_16x16x32_bf16 v[2:5], v[190:193], v[222:225], v[2:5]
	s_setprio 0
	s_barrier
	ds_read_b128 v[146:149], v157
	ds_read_b128 v[160:163], v157 offset:1024
	ds_read_b128 v[170:173], v157 offset:2048
	ds_read_b128 v[174:177], v157 offset:3072
	ds_read_b128 v[178:181], v158
	ds_read_b128 v[182:185], v158 offset:1024
	ds_read_b128 v[186:189], v158 offset:2048
	ds_read_b128 v[190:193], v158 offset:3072
	s_add_u32 s26, s26, 0x80000
	s_addc_u32 s27, s27, 0
	s_mov_b32 m0, s35
	v_lshl_add_u64 v[232:233], s[26:27], 0, v[136:137]
	ds_read_b128 v[194:197], v156 offset:32768
	ds_read_b128 v[198:201], v156 offset:33792
	ds_read_b128 v[202:205], v156 offset:34816
	ds_read_b128 v[206:209], v156 offset:35840
	ds_read_b128 v[210:213], v156 offset:36864
	ds_read_b128 v[214:217], v156 offset:37888
	ds_read_b128 v[218:221], v156 offset:38912
	ds_read_b128 v[222:225], v156 offset:39936
	global_load_lds_dwordx4 v[232:233], off
	v_lshl_add_u64 v[232:233], s[26:27], 0, v[132:133]
	s_mov_b32 m0, s36
	s_nop 0
	global_load_lds_dwordx4 v[232:233], off
	s_waitcnt vmcnt(8)
	s_waitcnt lgkmcnt(0)
	s_barrier
	s_setprio 1
	v_mfma_f32_16x16x32_bf16 v[126:129], v[146:149], v[194:197], v[126:129]
	v_mfma_f32_16x16x32_bf16 v[122:125], v[170:173], v[194:197], v[122:125]
	v_mfma_f32_16x16x32_bf16 v[118:121], v[146:149], v[202:205], v[118:121]
	v_mfma_f32_16x16x32_bf16 v[110:113], v[170:173], v[202:205], v[110:113]
	v_mfma_f32_16x16x32_bf16 v[102:105], v[146:149], v[210:213], v[102:105]
	v_mfma_f32_16x16x32_bf16 v[94:97], v[170:173], v[210:213], v[94:97]
	v_mfma_f32_16x16x32_bf16 v[86:89], v[146:149], v[218:221], v[86:89]
	v_mfma_f32_16x16x32_bf16 v[78:81], v[170:173], v[218:221], v[78:81]
	v_mfma_f32_16x16x32_bf16 v[126:129], v[160:163], v[198:201], v[126:129]
	v_mfma_f32_16x16x32_bf16 v[122:125], v[174:177], v[198:201], v[122:125]
	v_mfma_f32_16x16x32_bf16 v[118:121], v[160:163], v[206:209], v[118:121]
	v_mfma_f32_16x16x32_bf16 v[110:113], v[174:177], v[206:209], v[110:113]
	v_mfma_f32_16x16x32_bf16 v[102:105], v[160:163], v[214:217], v[102:105]
	v_mfma_f32_16x16x32_bf16 v[94:97], v[174:177], v[214:217], v[94:97]
	v_mfma_f32_16x16x32_bf16 v[86:89], v[160:163], v[222:225], v[86:89]
	v_mfma_f32_16x16x32_bf16 v[78:81], v[174:177], v[222:225], v[78:81]
	v_mfma_f32_16x16x32_bf16 v[114:117], v[178:181], v[194:197], v[114:117]
	v_mfma_f32_16x16x32_bf16 v[106:109], v[186:189], v[194:197], v[106:109]
	v_mfma_f32_16x16x32_bf16 v[98:101], v[178:181], v[202:205], v[98:101]
	v_mfma_f32_16x16x32_bf16 v[90:93], v[186:189], v[202:205], v[90:93]
	v_mfma_f32_16x16x32_bf16 v[82:85], v[178:181], v[210:213], v[82:85]
	v_mfma_f32_16x16x32_bf16 v[74:77], v[186:189], v[210:213], v[74:77]
	v_mfma_f32_16x16x32_bf16 v[70:73], v[178:181], v[218:221], v[70:73]
	v_mfma_f32_16x16x32_bf16 v[66:69], v[186:189], v[218:221], v[66:69]
	v_mfma_f32_16x16x32_bf16 v[114:117], v[182:185], v[198:201], v[114:117]
	v_mfma_f32_16x16x32_bf16 v[106:109], v[190:193], v[198:201], v[106:109]
	v_mfma_f32_16x16x32_bf16 v[98:101], v[182:185], v[206:209], v[98:101]
	v_mfma_f32_16x16x32_bf16 v[90:93], v[190:193], v[206:209], v[90:93]
	v_mfma_f32_16x16x32_bf16 v[82:85], v[182:185], v[214:217], v[82:85]
	v_mfma_f32_16x16x32_bf16 v[74:77], v[190:193], v[214:217], v[74:77]
	v_mfma_f32_16x16x32_bf16 v[70:73], v[182:185], v[222:225], v[70:73]
	v_mfma_f32_16x16x32_bf16 v[66:69], v[190:193], v[222:225], v[66:69]
	s_setprio 0
	s_barrier
	s_add_i32 s26, s47, s30
	v_lshl_add_u64 v[164:165], v[164:165], 0, s[6:7]
	s_mov_b32 m0, s26
	ds_read_b128 v[194:197], v156 offset:49152
	ds_read_b128 v[198:201], v156 offset:50176
	ds_read_b128 v[202:205], v156 offset:51200
	ds_read_b128 v[206:209], v156 offset:52224
	ds_read_b128 v[210:213], v156 offset:53248
	ds_read_b128 v[214:217], v156 offset:54272
	ds_read_b128 v[218:221], v156 offset:55296
	ds_read_b128 v[222:225], v156 offset:56320
	global_load_lds_dwordx4 v[164:165], off
	s_add_i32 m0, s26, 0x2000
	s_add_u32 s24, s24, 0x80080
	v_lshl_add_u64 v[164:165], v[226:227], 0, s[6:7]
	s_addc_u32 s25, s25, 0
	s_add_i32 s26, s63, s30
	global_load_lds_dwordx4 v[164:165], off
	v_lshl_add_u64 v[164:165], s[24:25], 0, v[134:135]
	s_mov_b32 m0, s26
	s_nop 0
	global_load_lds_dwordx4 v[164:165], off
	v_lshl_add_u64 v[164:165], s[24:25], 0, v[130:131]
	s_add_i32 m0, s26, 0x2000
	s_nop 0
	global_load_lds_dwordx4 v[164:165], off
	v_lshl_add_u64 v[164:165], v[228:229], 0, s[6:7]
	s_mov_b32 m0, s37
	s_nop 0
	global_load_lds_dwordx4 v[164:165], off
	v_lshl_add_u64 v[164:165], v[230:231], 0, s[6:7]
	s_mov_b32 m0, s38
	s_nop 0
	global_load_lds_dwordx4 v[164:165], off
	s_waitcnt vmcnt(8)
	s_waitcnt lgkmcnt(0)
	s_barrier
	s_setprio 1
	v_mfma_f32_16x16x32_bf16 v[62:65], v[146:149], v[194:197], v[62:65]
	v_mfma_f32_16x16x32_bf16 v[58:61], v[170:173], v[194:197], v[58:61]
	v_mfma_f32_16x16x32_bf16 v[54:57], v[146:149], v[202:205], v[54:57]
	v_mfma_f32_16x16x32_bf16 v[46:49], v[170:173], v[202:205], v[46:49]
	v_mfma_f32_16x16x32_bf16 v[38:41], v[146:149], v[210:213], v[38:41]
	v_mfma_f32_16x16x32_bf16 v[30:33], v[170:173], v[210:213], v[30:33]
	v_mfma_f32_16x16x32_bf16 v[22:25], v[146:149], v[218:221], v[22:25]
	v_mfma_f32_16x16x32_bf16 v[14:17], v[170:173], v[218:221], v[14:17]
	v_mfma_f32_16x16x32_bf16 v[62:65], v[160:163], v[198:201], v[62:65]
	v_mfma_f32_16x16x32_bf16 v[58:61], v[174:177], v[198:201], v[58:61]
	v_mfma_f32_16x16x32_bf16 v[54:57], v[160:163], v[206:209], v[54:57]
	v_mfma_f32_16x16x32_bf16 v[46:49], v[174:177], v[206:209], v[46:49]
	v_mfma_f32_16x16x32_bf16 v[38:41], v[160:163], v[214:217], v[38:41]
	v_mfma_f32_16x16x32_bf16 v[30:33], v[174:177], v[214:217], v[30:33]
	v_mfma_f32_16x16x32_bf16 v[22:25], v[160:163], v[222:225], v[22:25]
	v_mfma_f32_16x16x32_bf16 v[14:17], v[174:177], v[222:225], v[14:17]
	v_mfma_f32_16x16x32_bf16 v[50:53], v[178:181], v[194:197], v[50:53]
	v_mfma_f32_16x16x32_bf16 v[42:45], v[186:189], v[194:197], v[42:45]
	v_mfma_f32_16x16x32_bf16 v[34:37], v[178:181], v[202:205], v[34:37]
	v_mfma_f32_16x16x32_bf16 v[26:29], v[186:189], v[202:205], v[26:29]
	v_mfma_f32_16x16x32_bf16 v[18:21], v[178:181], v[210:213], v[18:21]
	v_mfma_f32_16x16x32_bf16 v[10:13], v[186:189], v[210:213], v[10:13]
	v_mfma_f32_16x16x32_bf16 v[6:9], v[178:181], v[218:221], v[6:9]
	v_mfma_f32_16x16x32_bf16 v[2:5], v[186:189], v[218:221], v[2:5]
	v_mfma_f32_16x16x32_bf16 v[50:53], v[182:185], v[198:201], v[50:53]
	v_mfma_f32_16x16x32_bf16 v[42:45], v[190:193], v[198:201], v[42:45]
	v_mfma_f32_16x16x32_bf16 v[34:37], v[182:185], v[206:209], v[34:37]
	v_mfma_f32_16x16x32_bf16 v[26:29], v[190:193], v[206:209], v[26:29]
	v_mfma_f32_16x16x32_bf16 v[18:21], v[182:185], v[214:217], v[18:21]
	v_mfma_f32_16x16x32_bf16 v[10:13], v[190:193], v[214:217], v[10:13]
	v_mfma_f32_16x16x32_bf16 v[6:9], v[182:185], v[222:225], v[6:9]
	v_mfma_f32_16x16x32_bf16 v[2:5], v[190:193], v[222:225], v[2:5]
	s_setprio 0
	s_barrier
	s_add_i32 s71, s71, 2
	s_add_u32 s22, s22, 0x100
	s_addc_u32 s23, s23, 0
	s_add_u32 s69, s69, 0x100
	s_addc_u32 s70, s70, 0
	s_cmp_gt_u32 s71, 29
	s_cbranch_scc0 .LBB0_388
	s_and_b64 vcc, exec, s[10:11]
	s_cbranch_vccz .LBB0_391
	s_barrier

.LBB0_575:
	ds_read_b128 v[154:157], v149
	ds_read_b128 v[158:161], v149 offset:1024
	ds_read_b128 v[162:165], v149 offset:2048
	ds_read_b128 v[170:173], v149 offset:3072
	ds_read_b128 v[174:177], v150
	ds_read_b128 v[178:181], v150 offset:1024
	ds_read_b128 v[182:185], v150 offset:2048
	ds_read_b128 v[186:189], v150 offset:3072
	s_add_u32 s26, s24, 0xfff80080
	s_addc_u32 s27, s25, -1
	s_cmp_eq_u32 s50, 28
	s_cselect_b32 s29, s17, s27
	s_cselect_b32 s28, s46, s26
	s_cselect_b32 s27, s15, s49
	s_cselect_b32 s26, s47, s48
	v_lshl_add_u64 v[146:147], s[24:25], 0, v[138:139]
	s_add_i32 m0, s23, 0xc000
	ds_read_b128 v[190:193], v151
	ds_read_b128 v[194:197], v151 offset:1024
	ds_read_b128 v[198:201], v151 offset:2048
	ds_read_b128 v[202:205], v151 offset:3072
	ds_read_b128 v[206:209], v151 offset:4096
	ds_read_b128 v[210:213], v151 offset:5120
	ds_read_b128 v[214:217], v151 offset:6144
	ds_read_b128 v[218:221], v151 offset:7168
	global_load_lds_dwordx4 v[146:147], off
	v_lshl_add_u64 v[146:147], s[24:25], 0, v[140:141]
	s_add_i32 m0, s23, 0xe000
	s_nop 0
	global_load_lds_dwordx4 v[146:147], off
	s_waitcnt vmcnt(8)
	s_waitcnt lgkmcnt(0)
	s_barrier
	s_setprio 1
	v_mfma_f32_16x16x32_bf16 v[126:129], v[154:157], v[190:193], v[126:129]
	v_mfma_f32_16x16x32_bf16 v[122:125], v[162:165], v[190:193], v[122:125]
	v_mfma_f32_16x16x32_bf16 v[118:121], v[154:157], v[198:201], v[118:121]
	v_mfma_f32_16x16x32_bf16 v[110:113], v[162:165], v[198:201], v[110:113]
	v_mfma_f32_16x16x32_bf16 v[102:105], v[154:157], v[206:209], v[102:105]
	v_mfma_f32_16x16x32_bf16 v[94:97], v[162:165], v[206:209], v[94:97]
	v_mfma_f32_16x16x32_bf16 v[86:89], v[154:157], v[214:217], v[86:89]
	v_mfma_f32_16x16x32_bf16 v[78:81], v[162:165], v[214:217], v[78:81]
	v_mfma_f32_16x16x32_bf16 v[126:129], v[158:161], v[194:197], v[126:129]
	v_mfma_f32_16x16x32_bf16 v[122:125], v[170:173], v[194:197], v[122:125]
	v_mfma_f32_16x16x32_bf16 v[118:121], v[158:161], v[202:205], v[118:121]
	v_mfma_f32_16x16x32_bf16 v[110:113], v[170:173], v[202:205], v[110:113]
	v_mfma_f32_16x16x32_bf16 v[102:105], v[158:161], v[210:213], v[102:105]
	v_mfma_f32_16x16x32_bf16 v[94:97], v[170:173], v[210:213], v[94:97]
	v_mfma_f32_16x16x32_bf16 v[86:89], v[158:161], v[218:221], v[86:89]
	v_mfma_f32_16x16x32_bf16 v[78:81], v[170:173], v[218:221], v[78:81]
	v_mfma_f32_16x16x32_bf16 v[114:117], v[174:177], v[190:193], v[114:117]
	v_mfma_f32_16x16x32_bf16 v[106:109], v[182:185], v[190:193], v[106:109]
	v_mfma_f32_16x16x32_bf16 v[98:101], v[174:177], v[198:201], v[98:101]
	v_mfma_f32_16x16x32_bf16 v[90:93], v[182:185], v[198:201], v[90:93]
	v_mfma_f32_16x16x32_bf16 v[82:85], v[174:177], v[206:209], v[82:85]
	v_mfma_f32_16x16x32_bf16 v[74:77], v[182:185], v[206:209], v[74:77]
	v_mfma_f32_16x16x32_bf16 v[70:73], v[174:177], v[214:217], v[70:73]
	v_mfma_f32_16x16x32_bf16 v[66:69], v[182:185], v[214:217], v[66:69]
	v_mfma_f32_16x16x32_bf16 v[114:117], v[178:181], v[194:197], v[114:117]
	v_mfma_f32_16x16x32_bf16 v[106:109], v[186:189], v[194:197], v[106:109]
	v_mfma_f32_16x16x32_bf16 v[98:101], v[178:181], v[202:205], v[98:101]
	v_mfma_f32_16x16x32_bf16 v[90:93], v[186:189], v[202:205], v[90:93]
	v_mfma_f32_16x16x32_bf16 v[82:85], v[178:181], v[210:213], v[82:85]
	v_mfma_f32_16x16x32_bf16 v[74:77], v[186:189], v[210:213], v[74:77]
	v_mfma_f32_16x16x32_bf16 v[70:73], v[178:181], v[218:221], v[70:73]
	v_mfma_f32_16x16x32_bf16 v[66:69], v[186:189], v[218:221], v[66:69]
	s_setprio 0
	s_barrier
	s_add_i32 s51, s41, s31
	v_lshl_add_u64 v[146:147], s[26:27], 0, v[132:133]
	s_mov_b32 m0, s51
	ds_read_b128 v[190:193], v151 offset:16384
	ds_read_b128 v[194:197], v151 offset:17408
	ds_read_b128 v[198:201], v151 offset:18432
	ds_read_b128 v[202:205], v151 offset:19456
	ds_read_b128 v[206:209], v151 offset:20480
	ds_read_b128 v[210:213], v151 offset:21504
	ds_read_b128 v[214:217], v151 offset:22528
	ds_read_b128 v[218:221], v151 offset:23552
	global_load_lds_dwordx4 v[146:147], off
	s_add_i32 m0, s51, 0x2000
	s_add_u32 s68, s26, 0x80000
	v_lshl_add_u64 v[222:223], s[26:27], 0, v[136:137]
	s_addc_u32 s69, s27, 0
	s_add_i32 s51, s42, s31
	global_load_lds_dwordx4 v[222:223], off
	v_lshl_add_u64 v[224:225], s[68:69], 0, v[132:133]
	s_mov_b32 m0, s51
	v_lshl_add_u64 v[226:227], s[28:29], 0, v[134:135]
	global_load_lds_dwordx4 v[224:225], off
	v_lshl_add_u64 v[224:225], s[68:69], 0, v[136:137]
	s_add_i32 m0, s51, 0x2000
	s_nop 0
	global_load_lds_dwordx4 v[224:225], off
	v_lshl_add_u64 v[224:225], s[28:29], 0, v[130:131]
	s_mov_b32 m0, s23
	s_nop 0
	global_load_lds_dwordx4 v[224:225], off
	s_mov_b32 m0, s34
	s_nop 0
	global_load_lds_dwordx4 v[226:227], off
	s_waitcnt vmcnt(8)
	s_waitcnt lgkmcnt(0)
	s_barrier
	s_setprio 1
	v_mfma_f32_16x16x32_bf16 v[62:65], v[154:157], v[190:193], v[62:65]
	v_mfma_f32_16x16x32_bf16 v[58:61], v[162:165], v[190:193], v[58:61]
	v_mfma_f32_16x16x32_bf16 v[54:57], v[154:157], v[198:201], v[54:57]
	v_mfma_f32_16x16x32_bf16 v[46:49], v[162:165], v[198:201], v[46:49]
	v_mfma_f32_16x16x32_bf16 v[38:41], v[154:157], v[206:209], v[38:41]
	v_mfma_f32_16x16x32_bf16 v[30:33], v[162:165], v[206:209], v[30:33]
	v_mfma_f32_16x16x32_bf16 v[22:25], v[154:157], v[214:217], v[22:25]
	v_mfma_f32_16x16x32_bf16 v[14:17], v[162:165], v[214:217], v[14:17]
	v_mfma_f32_16x16x32_bf16 v[62:65], v[158:161], v[194:197], v[62:65]
	v_mfma_f32_16x16x32_bf16 v[58:61], v[170:173], v[194:197], v[58:61]
	v_mfma_f32_16x16x32_bf16 v[54:57], v[158:161], v[202:205], v[54:57]
	v_mfma_f32_16x16x32_bf16 v[46:49], v[170:173], v[202:205], v[46:49]
	v_mfma_f32_16x16x32_bf16 v[38:41], v[158:161], v[210:213], v[38:41]
	v_mfma_f32_16x16x32_bf16 v[30:33], v[170:173], v[210:213], v[30:33]
	v_mfma_f32_16x16x32_bf16 v[22:25], v[158:161], v[218:221], v[22:25]
	v_mfma_f32_16x16x32_bf16 v[14:17], v[170:173], v[218:221], v[14:17]
	v_mfma_f32_16x16x32_bf16 v[50:53], v[174:177], v[190:193], v[50:53]
	v_mfma_f32_16x16x32_bf16 v[42:45], v[182:185], v[190:193], v[42:45]
	v_mfma_f32_16x16x32_bf16 v[34:37], v[174:177], v[198:201], v[34:37]
	v_mfma_f32_16x16x32_bf16 v[26:29], v[182:185], v[198:201], v[26:29]
	v_mfma_f32_16x16x32_bf16 v[18:21], v[174:177], v[206:209], v[18:21]
	v_mfma_f32_16x16x32_bf16 v[10:13], v[182:185], v[206:209], v[10:13]
	v_mfma_f32_16x16x32_bf16 v[6:9], v[174:177], v[214:217], v[6:9]
	v_mfma_f32_16x16x32_bf16 v[2:5], v[182:185], v[214:217], v[2:5]
	v_mfma_f32_16x16x32_bf16 v[50:53], v[178:181], v[194:197], v[50:53]
	v_mfma_f32_16x16x32_bf16 v[42:45], v[186:189], v[194:197], v[42:45]
	v_mfma_f32_16x16x32_bf16 v[34:37], v[178:181], v[202:205], v[34:37]
	v_mfma_f32_16x16x32_bf16 v[26:29], v[186:189], v[202:205], v[26:29]
	v_mfma_f32_16x16x32_bf16 v[18:21], v[178:181], v[210:213], v[18:21]
	v_mfma_f32_16x16x32_bf16 v[10:13], v[186:189], v[210:213], v[10:13]
	v_mfma_f32_16x16x32_bf16 v[6:9], v[178:181], v[218:221], v[6:9]
	v_mfma_f32_16x16x32_bf16 v[2:5], v[186:189], v[218:221], v[2:5]
	s_setprio 0
	s_barrier
	ds_read_b128 v[154:157], v152
	ds_read_b128 v[158:161], v152 offset:1024
	ds_read_b128 v[162:165], v152 offset:2048
	ds_read_b128 v[170:173], v152 offset:3072
	ds_read_b128 v[174:177], v153
	ds_read_b128 v[178:181], v153 offset:1024
	ds_read_b128 v[182:185], v153 offset:2048
	ds_read_b128 v[186:189], v153 offset:3072
	s_add_u32 s28, s28, 0x80000
	s_addc_u32 s29, s29, 0
	s_mov_b32 m0, s35
	v_lshl_add_u64 v[228:229], s[28:29], 0, v[130:131]
	ds_read_b128 v[190:193], v151 offset:32768
	ds_read_b128 v[194:197], v151 offset:33792
	ds_read_b128 v[198:201], v151 offset:34816
	ds_read_b128 v[202:205], v151 offset:35840
	ds_read_b128 v[206:209], v151 offset:36864
	ds_read_b128 v[210:213], v151 offset:37888
	ds_read_b128 v[214:217], v151 offset:38912
	ds_read_b128 v[218:221], v151 offset:39936
	global_load_lds_dwordx4 v[228:229], off
	v_lshl_add_u64 v[228:229], s[28:29], 0, v[134:135]
	s_mov_b32 m0, s36
	s_nop 0
	global_load_lds_dwordx4 v[228:229], off
	s_waitcnt vmcnt(8)
	s_waitcnt lgkmcnt(0)
	s_barrier
	s_setprio 1
	v_mfma_f32_16x16x32_bf16 v[126:129], v[154:157], v[190:193], v[126:129]
	v_mfma_f32_16x16x32_bf16 v[122:125], v[162:165], v[190:193], v[122:125]
	v_mfma_f32_16x16x32_bf16 v[118:121], v[154:157], v[198:201], v[118:121]
	v_mfma_f32_16x16x32_bf16 v[110:113], v[162:165], v[198:201], v[110:113]
	v_mfma_f32_16x16x32_bf16 v[102:105], v[154:157], v[206:209], v[102:105]
	v_mfma_f32_16x16x32_bf16 v[94:97], v[162:165], v[206:209], v[94:97]
	v_mfma_f32_16x16x32_bf16 v[86:89], v[154:157], v[214:217], v[86:89]
	v_mfma_f32_16x16x32_bf16 v[78:81], v[162:165], v[214:217], v[78:81]
	v_mfma_f32_16x16x32_bf16 v[126:129], v[158:161], v[194:197], v[126:129]
	v_mfma_f32_16x16x32_bf16 v[122:125], v[170:173], v[194:197], v[122:125]
	v_mfma_f32_16x16x32_bf16 v[118:121], v[158:161], v[202:205], v[118:121]
	v_mfma_f32_16x16x32_bf16 v[110:113], v[170:173], v[202:205], v[110:113]
	v_mfma_f32_16x16x32_bf16 v[102:105], v[158:161], v[210:213], v[102:105]
	v_mfma_f32_16x16x32_bf16 v[94:97], v[170:173], v[210:213], v[94:97]
	v_mfma_f32_16x16x32_bf16 v[86:89], v[158:161], v[218:221], v[86:89]
	v_mfma_f32_16x16x32_bf16 v[78:81], v[170:173], v[218:221], v[78:81]
	v_mfma_f32_16x16x32_bf16 v[114:117], v[174:177], v[190:193], v[114:117]
	v_mfma_f32_16x16x32_bf16 v[106:109], v[182:185], v[190:193], v[106:109]
	v_mfma_f32_16x16x32_bf16 v[98:101], v[174:177], v[198:201], v[98:101]
	v_mfma_f32_16x16x32_bf16 v[90:93], v[182:185], v[198:201], v[90:93]
	v_mfma_f32_16x16x32_bf16 v[82:85], v[174:177], v[206:209], v[82:85]
	v_mfma_f32_16x16x32_bf16 v[74:77], v[182:185], v[206:209], v[74:77]
	v_mfma_f32_16x16x32_bf16 v[70:73], v[174:177], v[214:217], v[70:73]
	v_mfma_f32_16x16x32_bf16 v[66:69], v[182:185], v[214:217], v[66:69]
	v_mfma_f32_16x16x32_bf16 v[114:117], v[178:181], v[194:197], v[114:117]
	v_mfma_f32_16x16x32_bf16 v[106:109], v[186:189], v[194:197], v[106:109]
	v_mfma_f32_16x16x32_bf16 v[98:101], v[178:181], v[202:205], v[98:101]
	v_mfma_f32_16x16x32_bf16 v[90:93], v[186:189], v[202:205], v[90:93]
	v_mfma_f32_16x16x32_bf16 v[82:85], v[178:181], v[210:213], v[82:85]
	v_mfma_f32_16x16x32_bf16 v[74:77], v[186:189], v[210:213], v[74:77]
	v_mfma_f32_16x16x32_bf16 v[70:73], v[178:181], v[218:221], v[70:73]
	v_mfma_f32_16x16x32_bf16 v[66:69], v[186:189], v[218:221], v[66:69]
	s_setprio 0
	s_barrier
	s_add_i32 s28, s43, s31
	v_lshl_add_u64 v[146:147], v[146:147], 0, s[8:9]
	s_mov_b32 m0, s28
	ds_read_b128 v[190:193], v151 offset:49152
	ds_read_b128 v[194:197], v151 offset:50176
	ds_read_b128 v[198:201], v151 offset:51200
	ds_read_b128 v[202:205], v151 offset:52224
	ds_read_b128 v[206:209], v151 offset:53248
	ds_read_b128 v[210:213], v151 offset:54272
	ds_read_b128 v[214:217], v151 offset:55296
	ds_read_b128 v[218:221], v151 offset:56320
	global_load_lds_dwordx4 v[146:147], off
	s_add_i32 m0, s28, 0x2000
	s_add_u32 s26, s26, 0x80080
	v_lshl_add_u64 v[146:147], v[222:223], 0, s[8:9]
	s_addc_u32 s27, s27, 0
	s_add_i32 s28, s44, s31
	global_load_lds_dwordx4 v[146:147], off
	v_lshl_add_u64 v[146:147], s[26:27], 0, v[132:133]
	s_mov_b32 m0, s28
	s_nop 0
	global_load_lds_dwordx4 v[146:147], off
	v_lshl_add_u64 v[146:147], s[26:27], 0, v[136:137]
	s_add_i32 m0, s28, 0x2000
	s_nop 0
	global_load_lds_dwordx4 v[146:147], off
	v_lshl_add_u64 v[146:147], v[224:225], 0, s[8:9]
	s_mov_b32 m0, s37
	s_nop 0
	global_load_lds_dwordx4 v[146:147], off
	v_lshl_add_u64 v[146:147], v[226:227], 0, s[8:9]
	s_mov_b32 m0, s38
	s_nop 0
	global_load_lds_dwordx4 v[146:147], off
	s_waitcnt vmcnt(8)
	s_waitcnt lgkmcnt(0)
	s_barrier
	s_setprio 1
	v_mfma_f32_16x16x32_bf16 v[62:65], v[154:157], v[190:193], v[62:65]
	v_mfma_f32_16x16x32_bf16 v[58:61], v[162:165], v[190:193], v[58:61]
	v_mfma_f32_16x16x32_bf16 v[54:57], v[154:157], v[198:201], v[54:57]
	v_mfma_f32_16x16x32_bf16 v[46:49], v[162:165], v[198:201], v[46:49]
	v_mfma_f32_16x16x32_bf16 v[38:41], v[154:157], v[206:209], v[38:41]
	v_mfma_f32_16x16x32_bf16 v[30:33], v[162:165], v[206:209], v[30:33]
	v_mfma_f32_16x16x32_bf16 v[22:25], v[154:157], v[214:217], v[22:25]
	v_mfma_f32_16x16x32_bf16 v[14:17], v[162:165], v[214:217], v[14:17]
	v_mfma_f32_16x16x32_bf16 v[62:65], v[158:161], v[194:197], v[62:65]
	v_mfma_f32_16x16x32_bf16 v[58:61], v[170:173], v[194:197], v[58:61]
	v_mfma_f32_16x16x32_bf16 v[54:57], v[158:161], v[202:205], v[54:57]
	v_mfma_f32_16x16x32_bf16 v[46:49], v[170:173], v[202:205], v[46:49]
	v_mfma_f32_16x16x32_bf16 v[38:41], v[158:161], v[210:213], v[38:41]
	v_mfma_f32_16x16x32_bf16 v[30:33], v[170:173], v[210:213], v[30:33]
	v_mfma_f32_16x16x32_bf16 v[22:25], v[158:161], v[218:221], v[22:25]
	v_mfma_f32_16x16x32_bf16 v[14:17], v[170:173], v[218:221], v[14:17]
	v_mfma_f32_16x16x32_bf16 v[50:53], v[174:177], v[190:193], v[50:53]
	v_mfma_f32_16x16x32_bf16 v[42:45], v[182:185], v[190:193], v[42:45]
	v_mfma_f32_16x16x32_bf16 v[34:37], v[174:177], v[198:201], v[34:37]
	v_mfma_f32_16x16x32_bf16 v[26:29], v[182:185], v[198:201], v[26:29]
	v_mfma_f32_16x16x32_bf16 v[18:21], v[174:177], v[206:209], v[18:21]
	v_mfma_f32_16x16x32_bf16 v[10:13], v[182:185], v[206:209], v[10:13]
	v_mfma_f32_16x16x32_bf16 v[6:9], v[174:177], v[214:217], v[6:9]
	v_mfma_f32_16x16x32_bf16 v[2:5], v[182:185], v[214:217], v[2:5]
	v_mfma_f32_16x16x32_bf16 v[50:53], v[178:181], v[194:197], v[50:53]
	v_mfma_f32_16x16x32_bf16 v[42:45], v[186:189], v[194:197], v[42:45]
	v_mfma_f32_16x16x32_bf16 v[34:37], v[178:181], v[202:205], v[34:37]
	v_mfma_f32_16x16x32_bf16 v[26:29], v[186:189], v[202:205], v[26:29]
	v_mfma_f32_16x16x32_bf16 v[18:21], v[178:181], v[210:213], v[18:21]
	v_mfma_f32_16x16x32_bf16 v[10:13], v[186:189], v[210:213], v[10:13]
	v_mfma_f32_16x16x32_bf16 v[6:9], v[178:181], v[218:221], v[6:9]
	v_mfma_f32_16x16x32_bf16 v[2:5], v[186:189], v[218:221], v[2:5]
	s_setprio 0
	s_barrier
	s_add_i32 s50, s50, 2
	s_add_u32 s24, s24, 0x100
	s_addc_u32 s25, s25, 0
	s_add_u32 s48, s48, 0x100
	s_addc_u32 s49, s49, 0
	s_cmp_gt_u32 s50, 29
	s_cbranch_scc0 .LBB0_575
	s_and_b64 vcc, exec, s[12:13]
	s_cbranch_vccz .LBB0_578
	s_barrier

.LBB0_737:
	ds_read_b128 v[146:149], v178
	ds_read_b128 v[150:153], v178 offset:1024
	ds_read_b128 v[154:157], v178 offset:2048
	ds_read_b128 v[158:161], v178 offset:3072
	ds_read_b128 v[182:185], v179
	ds_read_b128 v[186:189], v179 offset:1024
	ds_read_b128 v[190:193], v179 offset:2048
	ds_read_b128 v[194:197], v179 offset:3072
	s_add_u32 s30, s28, 0xfffc0080
	s_addc_u32 s31, s29, -1
	s_cmp_eq_u32 s72, 12
	s_cselect_b32 s35, s21, s31
	s_cselect_b32 s34, s68, s30
	s_cselect_b32 s31, s19, s71
	s_cselect_b32 s30, s69, s70
	v_lshl_add_u64 v[162:163], s[28:29], 0, v[138:139]
	s_add_i32 m0, s27, 0xc000
	ds_read_b128 v[198:201], v180
	ds_read_b128 v[202:205], v180 offset:1024
	ds_read_b128 v[206:209], v180 offset:2048
	ds_read_b128 v[210:213], v180 offset:3072
	ds_read_b128 v[214:217], v180 offset:4096
	ds_read_b128 v[218:221], v180 offset:5120
	ds_read_b128 v[222:225], v180 offset:6144
	ds_read_b128 v[226:229], v180 offset:7168
	global_load_lds_dwordx4 v[162:163], off
	v_lshl_add_u64 v[162:163], s[28:29], 0, v[140:141]
	s_add_i32 m0, s27, 0xe000
	s_nop 0
	global_load_lds_dwordx4 v[162:163], off
	s_waitcnt vmcnt(8)
	s_waitcnt lgkmcnt(0)
	s_barrier
	s_setprio 1
	v_mfma_i32_16x16x64_i8 v[126:129], v[146:149], v[198:201], v[126:129]
	v_mfma_i32_16x16x64_i8 v[118:121], v[154:157], v[198:201], v[118:121]
	v_mfma_i32_16x16x64_i8 v[110:113], v[146:149], v[206:209], v[110:113]
	v_mfma_i32_16x16x64_i8 v[102:105], v[154:157], v[206:209], v[102:105]
	v_mfma_i32_16x16x64_i8 v[94:97], v[146:149], v[214:217], v[94:97]
	v_mfma_i32_16x16x64_i8 v[86:89], v[154:157], v[214:217], v[86:89]
	v_mfma_i32_16x16x64_i8 v[78:81], v[146:149], v[222:225], v[78:81]
	v_mfma_i32_16x16x64_i8 v[70:73], v[154:157], v[222:225], v[70:73]
	v_mfma_i32_16x16x64_i8 v[126:129], v[150:153], v[202:205], v[126:129]
	v_mfma_i32_16x16x64_i8 v[118:121], v[158:161], v[202:205], v[118:121]
	v_mfma_i32_16x16x64_i8 v[110:113], v[150:153], v[210:213], v[110:113]
	v_mfma_i32_16x16x64_i8 v[102:105], v[158:161], v[210:213], v[102:105]
	v_mfma_i32_16x16x64_i8 v[94:97], v[150:153], v[218:221], v[94:97]
	v_mfma_i32_16x16x64_i8 v[86:89], v[158:161], v[218:221], v[86:89]
	v_mfma_i32_16x16x64_i8 v[78:81], v[150:153], v[226:229], v[78:81]
	v_mfma_i32_16x16x64_i8 v[70:73], v[158:161], v[226:229], v[70:73]
	v_mfma_i32_16x16x64_i8 v[122:125], v[182:185], v[198:201], v[122:125]
	v_mfma_i32_16x16x64_i8 v[114:117], v[190:193], v[198:201], v[114:117]
	v_mfma_i32_16x16x64_i8 v[106:109], v[182:185], v[206:209], v[106:109]
	v_mfma_i32_16x16x64_i8 v[98:101], v[190:193], v[206:209], v[98:101]
	v_mfma_i32_16x16x64_i8 v[90:93], v[182:185], v[214:217], v[90:93]
	v_mfma_i32_16x16x64_i8 v[82:85], v[190:193], v[214:217], v[82:85]
	v_mfma_i32_16x16x64_i8 v[74:77], v[182:185], v[222:225], v[74:77]
	v_mfma_i32_16x16x64_i8 v[66:69], v[190:193], v[222:225], v[66:69]
	v_mfma_i32_16x16x64_i8 v[122:125], v[186:189], v[202:205], v[122:125]
	v_mfma_i32_16x16x64_i8 v[114:117], v[194:197], v[202:205], v[114:117]
	v_mfma_i32_16x16x64_i8 v[106:109], v[186:189], v[210:213], v[106:109]
	v_mfma_i32_16x16x64_i8 v[98:101], v[194:197], v[210:213], v[98:101]
	v_mfma_i32_16x16x64_i8 v[90:93], v[186:189], v[218:221], v[90:93]
	v_mfma_i32_16x16x64_i8 v[82:85], v[194:197], v[218:221], v[82:85]
	v_mfma_i32_16x16x64_i8 v[74:77], v[186:189], v[226:229], v[74:77]
	v_mfma_i32_16x16x64_i8 v[66:69], v[194:197], v[226:229], v[66:69]
	s_setprio 0
	s_barrier
	s_add_i32 s73, s46, s38
	v_lshl_add_u64 v[162:163], s[30:31], 0, v[134:135]
	s_mov_b32 m0, s73
	ds_read_b128 v[198:201], v180 offset:16384
	ds_read_b128 v[202:205], v180 offset:17408
	ds_read_b128 v[206:209], v180 offset:18432
	ds_read_b128 v[210:213], v180 offset:19456
	ds_read_b128 v[214:217], v180 offset:20480
	ds_read_b128 v[218:221], v180 offset:21504
	ds_read_b128 v[222:225], v180 offset:22528
	ds_read_b128 v[226:229], v180 offset:23552
	global_load_lds_dwordx4 v[162:163], off
	s_add_i32 m0, s73, 0x2000
	s_add_u32 s74, s30, 0x40000
	v_lshl_add_u64 v[230:231], s[30:31], 0, v[130:131]
	s_addc_u32 s75, s31, 0
	s_add_i32 s73, s47, s38
	global_load_lds_dwordx4 v[230:231], off
	v_lshl_add_u64 v[232:233], s[74:75], 0, v[134:135]
	s_mov_b32 m0, s73
	v_lshl_add_u64 v[234:235], s[34:35], 0, v[132:133]
	global_load_lds_dwordx4 v[232:233], off
	v_lshl_add_u64 v[232:233], s[74:75], 0, v[130:131]
	s_add_i32 m0, s73, 0x2000
	s_nop 0
	global_load_lds_dwordx4 v[232:233], off
	v_lshl_add_u64 v[232:233], s[34:35], 0, v[136:137]
	s_mov_b32 m0, s27
	s_nop 0
	global_load_lds_dwordx4 v[232:233], off
	s_mov_b32 m0, s40
	s_nop 0
	global_load_lds_dwordx4 v[234:235], off
	s_waitcnt vmcnt(8)
	s_waitcnt lgkmcnt(0)
	s_barrier
	s_setprio 1
	v_mfma_i32_16x16x64_i8 v[62:65], v[146:149], v[198:201], v[62:65]
	v_mfma_i32_16x16x64_i8 v[54:57], v[154:157], v[198:201], v[54:57]
	v_mfma_i32_16x16x64_i8 v[46:49], v[146:149], v[206:209], v[46:49]
	v_mfma_i32_16x16x64_i8 v[38:41], v[154:157], v[206:209], v[38:41]
	v_mfma_i32_16x16x64_i8 v[30:33], v[146:149], v[214:217], v[30:33]
	v_mfma_i32_16x16x64_i8 v[22:25], v[154:157], v[214:217], v[22:25]
	v_mfma_i32_16x16x64_i8 v[14:17], v[146:149], v[222:225], v[14:17]
	v_mfma_i32_16x16x64_i8 v[6:9], v[154:157], v[222:225], v[6:9]
	v_mfma_i32_16x16x64_i8 v[62:65], v[150:153], v[202:205], v[62:65]
	v_mfma_i32_16x16x64_i8 v[54:57], v[158:161], v[202:205], v[54:57]
	v_mfma_i32_16x16x64_i8 v[46:49], v[150:153], v[210:213], v[46:49]
	v_mfma_i32_16x16x64_i8 v[38:41], v[158:161], v[210:213], v[38:41]
	v_mfma_i32_16x16x64_i8 v[30:33], v[150:153], v[218:221], v[30:33]
	v_mfma_i32_16x16x64_i8 v[22:25], v[158:161], v[218:221], v[22:25]
	v_mfma_i32_16x16x64_i8 v[14:17], v[150:153], v[226:229], v[14:17]
	v_mfma_i32_16x16x64_i8 v[6:9], v[158:161], v[226:229], v[6:9]
	v_mfma_i32_16x16x64_i8 v[58:61], v[182:185], v[198:201], v[58:61]
	v_mfma_i32_16x16x64_i8 v[50:53], v[190:193], v[198:201], v[50:53]
	v_mfma_i32_16x16x64_i8 v[42:45], v[182:185], v[206:209], v[42:45]
	v_mfma_i32_16x16x64_i8 v[34:37], v[190:193], v[206:209], v[34:37]
	v_mfma_i32_16x16x64_i8 v[26:29], v[182:185], v[214:217], v[26:29]
	v_mfma_i32_16x16x64_i8 v[18:21], v[190:193], v[214:217], v[18:21]
	v_mfma_i32_16x16x64_i8 v[10:13], v[182:185], v[222:225], v[10:13]
	v_mfma_i32_16x16x64_i8 v[2:5], v[190:193], v[222:225], v[2:5]
	v_mfma_i32_16x16x64_i8 v[58:61], v[186:189], v[202:205], v[58:61]
	v_mfma_i32_16x16x64_i8 v[50:53], v[194:197], v[202:205], v[50:53]
	v_mfma_i32_16x16x64_i8 v[42:45], v[186:189], v[210:213], v[42:45]
	v_mfma_i32_16x16x64_i8 v[34:37], v[194:197], v[210:213], v[34:37]
	v_mfma_i32_16x16x64_i8 v[26:29], v[186:189], v[218:221], v[26:29]
	v_mfma_i32_16x16x64_i8 v[18:21], v[194:197], v[218:221], v[18:21]
	v_mfma_i32_16x16x64_i8 v[10:13], v[186:189], v[226:229], v[10:13]
	v_mfma_i32_16x16x64_i8 v[2:5], v[194:197], v[226:229], v[2:5]
	s_setprio 0
	s_barrier
	s_add_i32 s73, 0, 0x18000
	v_add_u32_e32 v158, s73, v169
	ds_read_b128 v[146:149], v158
	ds_read_b128 v[150:153], v158 offset:1024
	ds_read_b128 v[154:157], v158 offset:2048
	ds_read_b128 v[158:161], v158 offset:3072
	ds_read_b128 v[182:185], v181
	ds_read_b128 v[186:189], v181 offset:1024
	ds_read_b128 v[190:193], v181 offset:2048
	ds_read_b128 v[194:197], v181 offset:3072
	s_add_u32 s34, s34, 0x40000
	s_addc_u32 s35, s35, 0
	s_mov_b32 m0, s41
	v_lshl_add_u64 v[236:237], s[34:35], 0, v[136:137]
	ds_read_b128 v[198:201], v180 offset:32768
	ds_read_b128 v[202:205], v180 offset:33792
	ds_read_b128 v[206:209], v180 offset:34816
	ds_read_b128 v[210:213], v180 offset:35840
	ds_read_b128 v[214:217], v180 offset:36864
	ds_read_b128 v[218:221], v180 offset:37888
	ds_read_b128 v[222:225], v180 offset:38912
	ds_read_b128 v[226:229], v180 offset:39936
	global_load_lds_dwordx4 v[236:237], off
	v_lshl_add_u64 v[236:237], s[34:35], 0, v[132:133]
	s_mov_b32 m0, s42
	s_nop 0
	global_load_lds_dwordx4 v[236:237], off
	s_waitcnt vmcnt(8)
	s_waitcnt lgkmcnt(0)
	s_barrier
	s_setprio 1
	v_mfma_i32_16x16x64_i8 v[126:129], v[146:149], v[198:201], v[126:129]
	v_mfma_i32_16x16x64_i8 v[118:121], v[154:157], v[198:201], v[118:121]
	v_mfma_i32_16x16x64_i8 v[110:113], v[146:149], v[206:209], v[110:113]
	v_mfma_i32_16x16x64_i8 v[102:105], v[154:157], v[206:209], v[102:105]
	v_mfma_i32_16x16x64_i8 v[94:97], v[146:149], v[214:217], v[94:97]
	v_mfma_i32_16x16x64_i8 v[86:89], v[154:157], v[214:217], v[86:89]
	v_mfma_i32_16x16x64_i8 v[78:81], v[146:149], v[222:225], v[78:81]
	v_mfma_i32_16x16x64_i8 v[70:73], v[154:157], v[222:225], v[70:73]
	v_mfma_i32_16x16x64_i8 v[126:129], v[150:153], v[202:205], v[126:129]
	v_mfma_i32_16x16x64_i8 v[118:121], v[158:161], v[202:205], v[118:121]
	v_mfma_i32_16x16x64_i8 v[110:113], v[150:153], v[210:213], v[110:113]
	v_mfma_i32_16x16x64_i8 v[102:105], v[158:161], v[210:213], v[102:105]
	v_mfma_i32_16x16x64_i8 v[94:97], v[150:153], v[218:221], v[94:97]
	v_mfma_i32_16x16x64_i8 v[86:89], v[158:161], v[218:221], v[86:89]
	v_mfma_i32_16x16x64_i8 v[78:81], v[150:153], v[226:229], v[78:81]
	v_mfma_i32_16x16x64_i8 v[70:73], v[158:161], v[226:229], v[70:73]
	v_mfma_i32_16x16x64_i8 v[122:125], v[182:185], v[198:201], v[122:125]
	v_mfma_i32_16x16x64_i8 v[114:117], v[190:193], v[198:201], v[114:117]
	v_mfma_i32_16x16x64_i8 v[106:109], v[182:185], v[206:209], v[106:109]
	v_mfma_i32_16x16x64_i8 v[98:101], v[190:193], v[206:209], v[98:101]
	v_mfma_i32_16x16x64_i8 v[90:93], v[182:185], v[214:217], v[90:93]
	v_mfma_i32_16x16x64_i8 v[82:85], v[190:193], v[214:217], v[82:85]
	v_mfma_i32_16x16x64_i8 v[74:77], v[182:185], v[222:225], v[74:77]
	v_mfma_i32_16x16x64_i8 v[66:69], v[190:193], v[222:225], v[66:69]
	v_mfma_i32_16x16x64_i8 v[122:125], v[186:189], v[202:205], v[122:125]
	v_mfma_i32_16x16x64_i8 v[114:117], v[194:197], v[202:205], v[114:117]
	v_mfma_i32_16x16x64_i8 v[106:109], v[186:189], v[210:213], v[106:109]
	v_mfma_i32_16x16x64_i8 v[98:101], v[194:197], v[210:213], v[98:101]
	v_mfma_i32_16x16x64_i8 v[90:93], v[186:189], v[218:221], v[90:93]
	v_mfma_i32_16x16x64_i8 v[82:85], v[194:197], v[218:221], v[82:85]
	v_mfma_i32_16x16x64_i8 v[74:77], v[186:189], v[226:229], v[74:77]
	v_mfma_i32_16x16x64_i8 v[66:69], v[194:197], v[226:229], v[66:69]
	s_setprio 0
	s_barrier
	s_add_i32 s34, s73, s38
	v_lshl_add_u64 v[162:163], v[162:163], 0, s[10:11]
	s_mov_b32 m0, s34
	ds_read_b128 v[198:201], v180 offset:49152
	ds_read_b128 v[202:205], v180 offset:50176
	ds_read_b128 v[206:209], v180 offset:51200
	ds_read_b128 v[210:213], v180 offset:52224
	ds_read_b128 v[214:217], v180 offset:53248
	ds_read_b128 v[218:221], v180 offset:54272
	ds_read_b128 v[222:225], v180 offset:55296
	ds_read_b128 v[226:229], v180 offset:56320
	global_load_lds_dwordx4 v[162:163], off
	s_add_i32 m0, s34, 0x2000
	s_add_u32 s30, s30, 0x40080
	v_lshl_add_u64 v[162:163], v[230:231], 0, s[10:11]
	s_addc_u32 s31, s31, 0
	s_add_i32 s34, s48, s38
	global_load_lds_dwordx4 v[162:163], off
	v_lshl_add_u64 v[162:163], s[30:31], 0, v[134:135]
	s_mov_b32 m0, s34
	s_nop 0
	global_load_lds_dwordx4 v[162:163], off
	v_lshl_add_u64 v[162:163], s[30:31], 0, v[130:131]
	s_add_i32 m0, s34, 0x2000
	s_nop 0
	global_load_lds_dwordx4 v[162:163], off
	v_lshl_add_u64 v[162:163], v[232:233], 0, s[10:11]
	s_mov_b32 m0, s43
	s_nop 0
	global_load_lds_dwordx4 v[162:163], off
	v_lshl_add_u64 v[162:163], v[234:235], 0, s[10:11]
	s_mov_b32 m0, s44
	s_nop 0
	global_load_lds_dwordx4 v[162:163], off
	s_waitcnt vmcnt(8)
	s_waitcnt lgkmcnt(0)
	s_barrier
	s_setprio 1
	v_mfma_i32_16x16x64_i8 v[62:65], v[146:149], v[198:201], v[62:65]
	v_mfma_i32_16x16x64_i8 v[54:57], v[154:157], v[198:201], v[54:57]
	v_mfma_i32_16x16x64_i8 v[46:49], v[146:149], v[206:209], v[46:49]
	v_mfma_i32_16x16x64_i8 v[38:41], v[154:157], v[206:209], v[38:41]
	v_mfma_i32_16x16x64_i8 v[30:33], v[146:149], v[214:217], v[30:33]
	v_mfma_i32_16x16x64_i8 v[22:25], v[154:157], v[214:217], v[22:25]
	v_mfma_i32_16x16x64_i8 v[14:17], v[146:149], v[222:225], v[14:17]
	v_mfma_i32_16x16x64_i8 v[6:9], v[154:157], v[222:225], v[6:9]
	v_mfma_i32_16x16x64_i8 v[62:65], v[150:153], v[202:205], v[62:65]
	v_mfma_i32_16x16x64_i8 v[54:57], v[158:161], v[202:205], v[54:57]
	v_mfma_i32_16x16x64_i8 v[46:49], v[150:153], v[210:213], v[46:49]
	v_mfma_i32_16x16x64_i8 v[38:41], v[158:161], v[210:213], v[38:41]
	v_mfma_i32_16x16x64_i8 v[30:33], v[150:153], v[218:221], v[30:33]
	v_mfma_i32_16x16x64_i8 v[22:25], v[158:161], v[218:221], v[22:25]
	v_mfma_i32_16x16x64_i8 v[14:17], v[150:153], v[226:229], v[14:17]
	v_mfma_i32_16x16x64_i8 v[6:9], v[158:161], v[226:229], v[6:9]
	v_mfma_i32_16x16x64_i8 v[58:61], v[182:185], v[198:201], v[58:61]
	v_mfma_i32_16x16x64_i8 v[50:53], v[190:193], v[198:201], v[50:53]
	v_mfma_i32_16x16x64_i8 v[42:45], v[182:185], v[206:209], v[42:45]
	v_mfma_i32_16x16x64_i8 v[34:37], v[190:193], v[206:209], v[34:37]
	v_mfma_i32_16x16x64_i8 v[26:29], v[182:185], v[214:217], v[26:29]
	v_mfma_i32_16x16x64_i8 v[18:21], v[190:193], v[214:217], v[18:21]
	v_mfma_i32_16x16x64_i8 v[10:13], v[182:185], v[222:225], v[10:13]
	v_mfma_i32_16x16x64_i8 v[2:5], v[190:193], v[222:225], v[2:5]
	v_mfma_i32_16x16x64_i8 v[58:61], v[186:189], v[202:205], v[58:61]
	v_mfma_i32_16x16x64_i8 v[50:53], v[194:197], v[202:205], v[50:53]
	v_mfma_i32_16x16x64_i8 v[42:45], v[186:189], v[210:213], v[42:45]
	v_mfma_i32_16x16x64_i8 v[34:37], v[194:197], v[210:213], v[34:37]
	v_mfma_i32_16x16x64_i8 v[26:29], v[186:189], v[218:221], v[26:29]
	v_mfma_i32_16x16x64_i8 v[18:21], v[194:197], v[218:221], v[18:21]
	v_mfma_i32_16x16x64_i8 v[10:13], v[186:189], v[226:229], v[10:13]
	v_mfma_i32_16x16x64_i8 v[2:5], v[194:197], v[226:229], v[2:5]
	s_setprio 0
	s_barrier
	s_add_i32 s72, s72, 2
	s_add_u32 s28, s28, 0x100
	s_addc_u32 s29, s29, 0
	s_add_u32 s70, s70, 0x100
	s_addc_u32 s71, s71, 0
	s_cmp_gt_u32 s72, 13
	s_cbranch_scc0 .LBB0_737
	s_and_b64 vcc, exec, s[14:15]
	s_cbranch_vccz .LBB0_740
	s_barrier

.LBB0_846:
	ds_read_b128 v[154:157], v149
	ds_read_b128 v[158:161], v149 offset:1024
	ds_read_b128 v[162:165], v149 offset:2048
	ds_read_b128 v[170:173], v149 offset:3072
	ds_read_b128 v[174:177], v150
	ds_read_b128 v[178:181], v150 offset:1024
	ds_read_b128 v[182:185], v150 offset:2048
	ds_read_b128 v[186:189], v150 offset:3072
	s_add_u32 s20, s18, 0xffea0080
	s_addc_u32 s21, s19, -1
	s_cmpk_eq_i32 s46, 0x54
	s_cselect_b32 s23, s7, s21
	s_cselect_b32 s22, s6, s20
	s_cselect_b32 s21, s17, s45
	s_cselect_b32 s20, s16, s44
	v_lshl_add_u64 v[146:147], s[18:19], 0, v[138:139]
	s_add_i32 m0, s26, 0xc000
	ds_read_b128 v[190:193], v151
	ds_read_b128 v[194:197], v151 offset:1024
	ds_read_b128 v[198:201], v151 offset:2048
	ds_read_b128 v[202:205], v151 offset:3072
	ds_read_b128 v[206:209], v151 offset:4096
	ds_read_b128 v[210:213], v151 offset:5120
	ds_read_b128 v[214:217], v151 offset:6144
	ds_read_b128 v[218:221], v151 offset:7168
	global_load_lds_dwordx4 v[146:147], off
	v_lshl_add_u64 v[146:147], s[18:19], 0, v[140:141]
	s_add_i32 m0, s26, 0xe000
	s_nop 0
	global_load_lds_dwordx4 v[146:147], off
	s_waitcnt vmcnt(8)
	s_waitcnt lgkmcnt(0)
	s_barrier
	s_setprio 1
	v_mfma_f32_16x16x32_bf16 v[126:129], v[154:157], v[190:193], v[126:129]
	v_mfma_f32_16x16x32_bf16 v[122:125], v[162:165], v[190:193], v[122:125]
	v_mfma_f32_16x16x32_bf16 v[118:121], v[154:157], v[198:201], v[118:121]
	v_mfma_f32_16x16x32_bf16 v[110:113], v[162:165], v[198:201], v[110:113]
	v_mfma_f32_16x16x32_bf16 v[102:105], v[154:157], v[206:209], v[102:105]
	v_mfma_f32_16x16x32_bf16 v[94:97], v[162:165], v[206:209], v[94:97]
	v_mfma_f32_16x16x32_bf16 v[86:89], v[154:157], v[214:217], v[86:89]
	v_mfma_f32_16x16x32_bf16 v[78:81], v[162:165], v[214:217], v[78:81]
	v_mfma_f32_16x16x32_bf16 v[126:129], v[158:161], v[194:197], v[126:129]
	v_mfma_f32_16x16x32_bf16 v[122:125], v[170:173], v[194:197], v[122:125]
	v_mfma_f32_16x16x32_bf16 v[118:121], v[158:161], v[202:205], v[118:121]
	v_mfma_f32_16x16x32_bf16 v[110:113], v[170:173], v[202:205], v[110:113]
	v_mfma_f32_16x16x32_bf16 v[102:105], v[158:161], v[210:213], v[102:105]
	v_mfma_f32_16x16x32_bf16 v[94:97], v[170:173], v[210:213], v[94:97]
	v_mfma_f32_16x16x32_bf16 v[86:89], v[158:161], v[218:221], v[86:89]
	v_mfma_f32_16x16x32_bf16 v[78:81], v[170:173], v[218:221], v[78:81]
	v_mfma_f32_16x16x32_bf16 v[114:117], v[174:177], v[190:193], v[114:117]
	v_mfma_f32_16x16x32_bf16 v[106:109], v[182:185], v[190:193], v[106:109]
	v_mfma_f32_16x16x32_bf16 v[98:101], v[174:177], v[198:201], v[98:101]
	v_mfma_f32_16x16x32_bf16 v[90:93], v[182:185], v[198:201], v[90:93]
	v_mfma_f32_16x16x32_bf16 v[82:85], v[174:177], v[206:209], v[82:85]
	v_mfma_f32_16x16x32_bf16 v[74:77], v[182:185], v[206:209], v[74:77]
	v_mfma_f32_16x16x32_bf16 v[70:73], v[174:177], v[214:217], v[70:73]
	v_mfma_f32_16x16x32_bf16 v[66:69], v[182:185], v[214:217], v[66:69]
	v_mfma_f32_16x16x32_bf16 v[114:117], v[178:181], v[194:197], v[114:117]
	v_mfma_f32_16x16x32_bf16 v[106:109], v[186:189], v[194:197], v[106:109]
	v_mfma_f32_16x16x32_bf16 v[98:101], v[178:181], v[202:205], v[98:101]
	v_mfma_f32_16x16x32_bf16 v[90:93], v[186:189], v[202:205], v[90:93]
	v_mfma_f32_16x16x32_bf16 v[82:85], v[178:181], v[210:213], v[82:85]
	v_mfma_f32_16x16x32_bf16 v[74:77], v[186:189], v[210:213], v[74:77]
	v_mfma_f32_16x16x32_bf16 v[70:73], v[178:181], v[218:221], v[70:73]
	v_mfma_f32_16x16x32_bf16 v[66:69], v[186:189], v[218:221], v[66:69]
	s_setprio 0
	s_barrier
	s_add_i32 s47, s36, s25
	v_lshl_add_u64 v[146:147], s[20:21], 0, v[132:133]
	s_mov_b32 m0, s47
	ds_read_b128 v[190:193], v151 offset:16384
	ds_read_b128 v[194:197], v151 offset:17408
	ds_read_b128 v[198:201], v151 offset:18432
	ds_read_b128 v[202:205], v151 offset:19456
	ds_read_b128 v[206:209], v151 offset:20480
	ds_read_b128 v[210:213], v151 offset:21504
	ds_read_b128 v[214:217], v151 offset:22528
	ds_read_b128 v[218:221], v151 offset:23552
	global_load_lds_dwordx4 v[146:147], off
	s_add_i32 m0, s47, 0x2000
	s_add_u32 s48, s20, 0x160000
	v_lshl_add_u64 v[222:223], s[20:21], 0, v[136:137]
	s_addc_u32 s49, s21, 0
	s_add_i32 s47, s37, s25
	global_load_lds_dwordx4 v[222:223], off
	v_lshl_add_u64 v[224:225], s[48:49], 0, v[132:133]
	s_mov_b32 m0, s47
	v_lshl_add_u64 v[226:227], s[22:23], 0, v[134:135]
	global_load_lds_dwordx4 v[224:225], off
	v_lshl_add_u64 v[224:225], s[48:49], 0, v[136:137]
	s_add_i32 m0, s47, 0x2000
	s_nop 0
	global_load_lds_dwordx4 v[224:225], off
	v_lshl_add_u64 v[224:225], s[22:23], 0, v[130:131]
	s_mov_b32 m0, s26
	s_nop 0
	global_load_lds_dwordx4 v[224:225], off
	s_mov_b32 m0, s27
	s_nop 0
	global_load_lds_dwordx4 v[226:227], off
	s_waitcnt vmcnt(8)
	s_waitcnt lgkmcnt(0)
	s_barrier
	s_setprio 1
	v_mfma_f32_16x16x32_bf16 v[62:65], v[154:157], v[190:193], v[62:65]
	v_mfma_f32_16x16x32_bf16 v[58:61], v[162:165], v[190:193], v[58:61]
	v_mfma_f32_16x16x32_bf16 v[54:57], v[154:157], v[198:201], v[54:57]
	v_mfma_f32_16x16x32_bf16 v[46:49], v[162:165], v[198:201], v[46:49]
	v_mfma_f32_16x16x32_bf16 v[38:41], v[154:157], v[206:209], v[38:41]
	v_mfma_f32_16x16x32_bf16 v[30:33], v[162:165], v[206:209], v[30:33]
	v_mfma_f32_16x16x32_bf16 v[22:25], v[154:157], v[214:217], v[22:25]
	v_mfma_f32_16x16x32_bf16 v[14:17], v[162:165], v[214:217], v[14:17]
	v_mfma_f32_16x16x32_bf16 v[62:65], v[158:161], v[194:197], v[62:65]
	v_mfma_f32_16x16x32_bf16 v[58:61], v[170:173], v[194:197], v[58:61]
	v_mfma_f32_16x16x32_bf16 v[54:57], v[158:161], v[202:205], v[54:57]
	v_mfma_f32_16x16x32_bf16 v[46:49], v[170:173], v[202:205], v[46:49]
	v_mfma_f32_16x16x32_bf16 v[38:41], v[158:161], v[210:213], v[38:41]
	v_mfma_f32_16x16x32_bf16 v[30:33], v[170:173], v[210:213], v[30:33]
	v_mfma_f32_16x16x32_bf16 v[22:25], v[158:161], v[218:221], v[22:25]
	v_mfma_f32_16x16x32_bf16 v[14:17], v[170:173], v[218:221], v[14:17]
	v_mfma_f32_16x16x32_bf16 v[50:53], v[174:177], v[190:193], v[50:53]
	v_mfma_f32_16x16x32_bf16 v[42:45], v[182:185], v[190:193], v[42:45]
	v_mfma_f32_16x16x32_bf16 v[34:37], v[174:177], v[198:201], v[34:37]
	v_mfma_f32_16x16x32_bf16 v[26:29], v[182:185], v[198:201], v[26:29]
	v_mfma_f32_16x16x32_bf16 v[18:21], v[174:177], v[206:209], v[18:21]
	v_mfma_f32_16x16x32_bf16 v[10:13], v[182:185], v[206:209], v[10:13]
	v_mfma_f32_16x16x32_bf16 v[6:9], v[174:177], v[214:217], v[6:9]
	v_mfma_f32_16x16x32_bf16 v[2:5], v[182:185], v[214:217], v[2:5]
	v_mfma_f32_16x16x32_bf16 v[50:53], v[178:181], v[194:197], v[50:53]
	v_mfma_f32_16x16x32_bf16 v[42:45], v[186:189], v[194:197], v[42:45]
	v_mfma_f32_16x16x32_bf16 v[34:37], v[178:181], v[202:205], v[34:37]
	v_mfma_f32_16x16x32_bf16 v[26:29], v[186:189], v[202:205], v[26:29]
	v_mfma_f32_16x16x32_bf16 v[18:21], v[178:181], v[210:213], v[18:21]
	v_mfma_f32_16x16x32_bf16 v[10:13], v[186:189], v[210:213], v[10:13]
	v_mfma_f32_16x16x32_bf16 v[6:9], v[178:181], v[218:221], v[6:9]
	v_mfma_f32_16x16x32_bf16 v[2:5], v[186:189], v[218:221], v[2:5]
	s_setprio 0
	s_barrier
	ds_read_b128 v[154:157], v152
	ds_read_b128 v[158:161], v152 offset:1024
	ds_read_b128 v[162:165], v152 offset:2048
	ds_read_b128 v[170:173], v152 offset:3072
	ds_read_b128 v[174:177], v153
	ds_read_b128 v[178:181], v153 offset:1024
	ds_read_b128 v[182:185], v153 offset:2048
	ds_read_b128 v[186:189], v153 offset:3072
	s_add_u32 s22, s22, 0x160000
	s_addc_u32 s23, s23, 0
	s_mov_b32 m0, s28
	v_lshl_add_u64 v[228:229], s[22:23], 0, v[130:131]
	ds_read_b128 v[190:193], v151 offset:32768
	ds_read_b128 v[194:197], v151 offset:33792
	ds_read_b128 v[198:201], v151 offset:34816
	ds_read_b128 v[202:205], v151 offset:35840
	ds_read_b128 v[206:209], v151 offset:36864
	ds_read_b128 v[210:213], v151 offset:37888
	ds_read_b128 v[214:217], v151 offset:38912
	ds_read_b128 v[218:221], v151 offset:39936
	global_load_lds_dwordx4 v[228:229], off
	v_lshl_add_u64 v[228:229], s[22:23], 0, v[134:135]
	s_mov_b32 m0, s29
	s_nop 0
	global_load_lds_dwordx4 v[228:229], off
	s_waitcnt vmcnt(8)
	s_waitcnt lgkmcnt(0)
	s_barrier
	s_setprio 1
	v_mfma_f32_16x16x32_bf16 v[126:129], v[154:157], v[190:193], v[126:129]
	v_mfma_f32_16x16x32_bf16 v[122:125], v[162:165], v[190:193], v[122:125]
	v_mfma_f32_16x16x32_bf16 v[118:121], v[154:157], v[198:201], v[118:121]
	v_mfma_f32_16x16x32_bf16 v[110:113], v[162:165], v[198:201], v[110:113]
	v_mfma_f32_16x16x32_bf16 v[102:105], v[154:157], v[206:209], v[102:105]
	v_mfma_f32_16x16x32_bf16 v[94:97], v[162:165], v[206:209], v[94:97]
	v_mfma_f32_16x16x32_bf16 v[86:89], v[154:157], v[214:217], v[86:89]
	v_mfma_f32_16x16x32_bf16 v[78:81], v[162:165], v[214:217], v[78:81]
	v_mfma_f32_16x16x32_bf16 v[126:129], v[158:161], v[194:197], v[126:129]
	v_mfma_f32_16x16x32_bf16 v[122:125], v[170:173], v[194:197], v[122:125]
	v_mfma_f32_16x16x32_bf16 v[118:121], v[158:161], v[202:205], v[118:121]
	v_mfma_f32_16x16x32_bf16 v[110:113], v[170:173], v[202:205], v[110:113]
	v_mfma_f32_16x16x32_bf16 v[102:105], v[158:161], v[210:213], v[102:105]
	v_mfma_f32_16x16x32_bf16 v[94:97], v[170:173], v[210:213], v[94:97]
	v_mfma_f32_16x16x32_bf16 v[86:89], v[158:161], v[218:221], v[86:89]
	v_mfma_f32_16x16x32_bf16 v[78:81], v[170:173], v[218:221], v[78:81]
	v_mfma_f32_16x16x32_bf16 v[114:117], v[174:177], v[190:193], v[114:117]
	v_mfma_f32_16x16x32_bf16 v[106:109], v[182:185], v[190:193], v[106:109]
	v_mfma_f32_16x16x32_bf16 v[98:101], v[174:177], v[198:201], v[98:101]
	v_mfma_f32_16x16x32_bf16 v[90:93], v[182:185], v[198:201], v[90:93]
	v_mfma_f32_16x16x32_bf16 v[82:85], v[174:177], v[206:209], v[82:85]
	v_mfma_f32_16x16x32_bf16 v[74:77], v[182:185], v[206:209], v[74:77]
	v_mfma_f32_16x16x32_bf16 v[70:73], v[174:177], v[214:217], v[70:73]
	v_mfma_f32_16x16x32_bf16 v[66:69], v[182:185], v[214:217], v[66:69]
	v_mfma_f32_16x16x32_bf16 v[114:117], v[178:181], v[194:197], v[114:117]
	v_mfma_f32_16x16x32_bf16 v[106:109], v[186:189], v[194:197], v[106:109]
	v_mfma_f32_16x16x32_bf16 v[98:101], v[178:181], v[202:205], v[98:101]
	v_mfma_f32_16x16x32_bf16 v[90:93], v[186:189], v[202:205], v[90:93]
	v_mfma_f32_16x16x32_bf16 v[82:85], v[178:181], v[210:213], v[82:85]
	v_mfma_f32_16x16x32_bf16 v[74:77], v[186:189], v[210:213], v[74:77]
	v_mfma_f32_16x16x32_bf16 v[70:73], v[178:181], v[218:221], v[70:73]
	v_mfma_f32_16x16x32_bf16 v[66:69], v[186:189], v[218:221], v[66:69]
	s_setprio 0
	s_barrier
	s_add_i32 s22, s38, s25
	v_lshl_add_u64 v[146:147], v[146:147], 0, s[8:9]
	s_mov_b32 m0, s22
	ds_read_b128 v[190:193], v151 offset:49152
	ds_read_b128 v[194:197], v151 offset:50176
	ds_read_b128 v[198:201], v151 offset:51200
	ds_read_b128 v[202:205], v151 offset:52224
	ds_read_b128 v[206:209], v151 offset:53248
	ds_read_b128 v[210:213], v151 offset:54272
	ds_read_b128 v[214:217], v151 offset:55296
	ds_read_b128 v[218:221], v151 offset:56320
	global_load_lds_dwordx4 v[146:147], off
	s_add_i32 m0, s22, 0x2000
	s_add_u32 s20, s20, 0x160080
	v_lshl_add_u64 v[146:147], v[222:223], 0, s[8:9]
	s_addc_u32 s21, s21, 0
	s_add_i32 s22, s39, s25
	global_load_lds_dwordx4 v[146:147], off
	v_lshl_add_u64 v[146:147], s[20:21], 0, v[132:133]
	s_mov_b32 m0, s22
	s_nop 0
	global_load_lds_dwordx4 v[146:147], off
	v_lshl_add_u64 v[146:147], s[20:21], 0, v[136:137]
	s_add_i32 m0, s22, 0x2000
	s_nop 0
	global_load_lds_dwordx4 v[146:147], off
	v_lshl_add_u64 v[146:147], v[224:225], 0, s[8:9]
	s_mov_b32 m0, s30
	s_nop 0
	global_load_lds_dwordx4 v[146:147], off
	v_lshl_add_u64 v[146:147], v[226:227], 0, s[8:9]
	s_mov_b32 m0, s31
	s_nop 0
	global_load_lds_dwordx4 v[146:147], off
	s_waitcnt vmcnt(8)
	s_waitcnt lgkmcnt(0)
	s_barrier
	s_setprio 1
	v_mfma_f32_16x16x32_bf16 v[62:65], v[154:157], v[190:193], v[62:65]
	v_mfma_f32_16x16x32_bf16 v[58:61], v[162:165], v[190:193], v[58:61]
	v_mfma_f32_16x16x32_bf16 v[54:57], v[154:157], v[198:201], v[54:57]
	v_mfma_f32_16x16x32_bf16 v[46:49], v[162:165], v[198:201], v[46:49]
	v_mfma_f32_16x16x32_bf16 v[38:41], v[154:157], v[206:209], v[38:41]
	v_mfma_f32_16x16x32_bf16 v[30:33], v[162:165], v[206:209], v[30:33]
	v_mfma_f32_16x16x32_bf16 v[22:25], v[154:157], v[214:217], v[22:25]
	v_mfma_f32_16x16x32_bf16 v[14:17], v[162:165], v[214:217], v[14:17]
	v_mfma_f32_16x16x32_bf16 v[62:65], v[158:161], v[194:197], v[62:65]
	v_mfma_f32_16x16x32_bf16 v[58:61], v[170:173], v[194:197], v[58:61]
	v_mfma_f32_16x16x32_bf16 v[54:57], v[158:161], v[202:205], v[54:57]
	v_mfma_f32_16x16x32_bf16 v[46:49], v[170:173], v[202:205], v[46:49]
	v_mfma_f32_16x16x32_bf16 v[38:41], v[158:161], v[210:213], v[38:41]
	v_mfma_f32_16x16x32_bf16 v[30:33], v[170:173], v[210:213], v[30:33]
	v_mfma_f32_16x16x32_bf16 v[22:25], v[158:161], v[218:221], v[22:25]
	v_mfma_f32_16x16x32_bf16 v[14:17], v[170:173], v[218:221], v[14:17]
	v_mfma_f32_16x16x32_bf16 v[50:53], v[174:177], v[190:193], v[50:53]
	v_mfma_f32_16x16x32_bf16 v[42:45], v[182:185], v[190:193], v[42:45]
	v_mfma_f32_16x16x32_bf16 v[34:37], v[174:177], v[198:201], v[34:37]
	v_mfma_f32_16x16x32_bf16 v[26:29], v[182:185], v[198:201], v[26:29]
	v_mfma_f32_16x16x32_bf16 v[18:21], v[174:177], v[206:209], v[18:21]
	v_mfma_f32_16x16x32_bf16 v[10:13], v[182:185], v[206:209], v[10:13]
	v_mfma_f32_16x16x32_bf16 v[6:9], v[174:177], v[214:217], v[6:9]
	v_mfma_f32_16x16x32_bf16 v[2:5], v[182:185], v[214:217], v[2:5]
	v_mfma_f32_16x16x32_bf16 v[50:53], v[178:181], v[194:197], v[50:53]
	v_mfma_f32_16x16x32_bf16 v[42:45], v[186:189], v[194:197], v[42:45]
	v_mfma_f32_16x16x32_bf16 v[34:37], v[178:181], v[202:205], v[34:37]
	v_mfma_f32_16x16x32_bf16 v[26:29], v[186:189], v[202:205], v[26:29]
	v_mfma_f32_16x16x32_bf16 v[18:21], v[178:181], v[210:213], v[18:21]
	v_mfma_f32_16x16x32_bf16 v[10:13], v[186:189], v[210:213], v[10:13]
	v_mfma_f32_16x16x32_bf16 v[6:9], v[178:181], v[218:221], v[6:9]
	v_mfma_f32_16x16x32_bf16 v[2:5], v[186:189], v[218:221], v[2:5]
	s_setprio 0
	s_barrier
	s_add_i32 s46, s46, 2
	s_add_u32 s18, s18, 0x100
	s_addc_u32 s19, s19, 0
	s_add_u32 s44, s44, 0x100
	s_addc_u32 s45, s45, 0
	s_cmpk_gt_u32 s46, 0x55
	s_cbranch_scc0 .LBB0_846
	s_and_b64 vcc, exec, s[14:15]
	s_cbranch_vccz .LBB0_849
	s_barrier

.LBB0_1262:
	ds_read_b128 v[148:151], v162
	ds_read_b128 v[152:155], v162 offset:1024
	ds_read_b128 v[156:159], v162 offset:2048
	ds_read_b128 v[170:173], v162 offset:3072
	ds_read_b128 v[174:177], v163
	ds_read_b128 v[178:181], v163 offset:1024
	ds_read_b128 v[182:185], v163 offset:2048
	ds_read_b128 v[186:189], v163 offset:3072
	s_add_u32 s26, s24, 0xfff80080
	s_addc_u32 s27, s25, -1
	s_cmp_eq_u32 s69, 28
	s_cselect_b32 s29, s17, s27
	s_cselect_b32 s28, s23, s26
	s_cselect_b32 s27, s15, s68
	s_cselect_b32 s26, s51, s63
	v_lshl_add_u64 v[222:223], s[24:25], 0, v[140:141]
	s_add_i32 m0, s35, 0xc000
	ds_read_b128 v[190:193], v164
	ds_read_b128 v[194:197], v164 offset:1024
	ds_read_b128 v[198:201], v164 offset:2048
	ds_read_b128 v[202:205], v164 offset:3072
	ds_read_b128 v[206:209], v164 offset:4096
	ds_read_b128 v[210:213], v164 offset:5120
	ds_read_b128 v[214:217], v164 offset:6144
	ds_read_b128 v[218:221], v164 offset:7168
	global_load_lds_dwordx4 v[222:223], off
	v_lshl_add_u64 v[222:223], s[24:25], 0, v[142:143]
	s_add_i32 m0, s35, 0xe000
	s_nop 0
	global_load_lds_dwordx4 v[222:223], off
	s_waitcnt vmcnt(8)
	s_waitcnt lgkmcnt(0)
	s_barrier
	s_setprio 1
	v_mfma_f32_16x16x32_bf16 v[126:129], v[148:151], v[190:193], v[126:129]
	v_mfma_f32_16x16x32_bf16 v[122:125], v[156:159], v[190:193], v[122:125]
	v_mfma_f32_16x16x32_bf16 v[118:121], v[148:151], v[198:201], v[118:121]
	v_mfma_f32_16x16x32_bf16 v[110:113], v[156:159], v[198:201], v[110:113]
	v_mfma_f32_16x16x32_bf16 v[102:105], v[148:151], v[206:209], v[102:105]
	v_mfma_f32_16x16x32_bf16 v[94:97], v[156:159], v[206:209], v[94:97]
	v_mfma_f32_16x16x32_bf16 v[86:89], v[148:151], v[214:217], v[86:89]
	v_mfma_f32_16x16x32_bf16 v[78:81], v[156:159], v[214:217], v[78:81]
	v_mfma_f32_16x16x32_bf16 v[126:129], v[152:155], v[194:197], v[126:129]
	v_mfma_f32_16x16x32_bf16 v[122:125], v[170:173], v[194:197], v[122:125]
	v_mfma_f32_16x16x32_bf16 v[118:121], v[152:155], v[202:205], v[118:121]
	v_mfma_f32_16x16x32_bf16 v[110:113], v[170:173], v[202:205], v[110:113]
	v_mfma_f32_16x16x32_bf16 v[102:105], v[152:155], v[210:213], v[102:105]
	v_mfma_f32_16x16x32_bf16 v[94:97], v[170:173], v[210:213], v[94:97]
	v_mfma_f32_16x16x32_bf16 v[86:89], v[152:155], v[218:221], v[86:89]
	v_mfma_f32_16x16x32_bf16 v[78:81], v[170:173], v[218:221], v[78:81]
	v_mfma_f32_16x16x32_bf16 v[114:117], v[174:177], v[190:193], v[114:117]
	v_mfma_f32_16x16x32_bf16 v[106:109], v[182:185], v[190:193], v[106:109]
	v_mfma_f32_16x16x32_bf16 v[98:101], v[174:177], v[198:201], v[98:101]
	v_mfma_f32_16x16x32_bf16 v[90:93], v[182:185], v[198:201], v[90:93]
	v_mfma_f32_16x16x32_bf16 v[82:85], v[174:177], v[206:209], v[82:85]
	v_mfma_f32_16x16x32_bf16 v[74:77], v[182:185], v[206:209], v[74:77]
	v_mfma_f32_16x16x32_bf16 v[70:73], v[174:177], v[214:217], v[70:73]
	v_mfma_f32_16x16x32_bf16 v[66:69], v[182:185], v[214:217], v[66:69]
	v_mfma_f32_16x16x32_bf16 v[114:117], v[178:181], v[194:197], v[114:117]
	v_mfma_f32_16x16x32_bf16 v[106:109], v[186:189], v[194:197], v[106:109]
	v_mfma_f32_16x16x32_bf16 v[98:101], v[178:181], v[202:205], v[98:101]
	v_mfma_f32_16x16x32_bf16 v[90:93], v[186:189], v[202:205], v[90:93]
	v_mfma_f32_16x16x32_bf16 v[82:85], v[178:181], v[210:213], v[82:85]
	v_mfma_f32_16x16x32_bf16 v[74:77], v[186:189], v[210:213], v[74:77]
	v_mfma_f32_16x16x32_bf16 v[70:73], v[178:181], v[218:221], v[70:73]
	v_mfma_f32_16x16x32_bf16 v[66:69], v[186:189], v[218:221], v[66:69]
	s_setprio 0
	s_barrier
	s_add_i32 s70, s43, s30
	v_lshl_add_u64 v[222:223], s[26:27], 0, v[134:135]
	s_mov_b32 m0, s70
	ds_read_b128 v[190:193], v164 offset:16384
	ds_read_b128 v[194:197], v164 offset:17408
	ds_read_b128 v[198:201], v164 offset:18432
	ds_read_b128 v[202:205], v164 offset:19456
	ds_read_b128 v[206:209], v164 offset:20480
	ds_read_b128 v[210:213], v164 offset:21504
	ds_read_b128 v[214:217], v164 offset:22528
	ds_read_b128 v[218:221], v164 offset:23552
	global_load_lds_dwordx4 v[222:223], off
	s_add_i32 m0, s70, 0x2000
	s_add_u32 s70, s26, 0x80000
	v_lshl_add_u64 v[224:225], s[26:27], 0, v[130:131]
	s_addc_u32 s71, s27, 0
	s_add_i32 s72, s44, s30
	global_load_lds_dwordx4 v[224:225], off
	v_lshl_add_u64 v[226:227], s[70:71], 0, v[134:135]
	s_mov_b32 m0, s72
	v_lshl_add_u64 v[228:229], s[28:29], 0, v[132:133]
	global_load_lds_dwordx4 v[226:227], off
	v_lshl_add_u64 v[226:227], s[70:71], 0, v[130:131]
	s_add_i32 m0, s72, 0x2000
	s_nop 0
	global_load_lds_dwordx4 v[226:227], off
	v_lshl_add_u64 v[226:227], s[28:29], 0, v[136:137]
	s_mov_b32 m0, s35
	s_nop 0
	global_load_lds_dwordx4 v[226:227], off
	s_mov_b32 m0, s36
	s_nop 0
	global_load_lds_dwordx4 v[228:229], off
	s_waitcnt vmcnt(8)
	s_waitcnt lgkmcnt(0)
	s_barrier
	s_setprio 1
	v_mfma_f32_16x16x32_bf16 v[62:65], v[148:151], v[190:193], v[62:65]
	v_mfma_f32_16x16x32_bf16 v[58:61], v[156:159], v[190:193], v[58:61]
	v_mfma_f32_16x16x32_bf16 v[50:53], v[148:151], v[198:201], v[50:53]
	v_mfma_f32_16x16x32_bf16 v[42:45], v[156:159], v[198:201], v[42:45]
	v_mfma_f32_16x16x32_bf16 v[38:41], v[148:151], v[206:209], v[38:41]
	v_mfma_f32_16x16x32_bf16 v[30:33], v[156:159], v[206:209], v[30:33]
	v_mfma_f32_16x16x32_bf16 v[22:25], v[148:151], v[214:217], v[22:25]
	v_mfma_f32_16x16x32_bf16 v[14:17], v[156:159], v[214:217], v[14:17]
	v_mfma_f32_16x16x32_bf16 v[62:65], v[152:155], v[194:197], v[62:65]
	v_mfma_f32_16x16x32_bf16 v[58:61], v[170:173], v[194:197], v[58:61]
	v_mfma_f32_16x16x32_bf16 v[50:53], v[152:155], v[202:205], v[50:53]
	v_mfma_f32_16x16x32_bf16 v[42:45], v[170:173], v[202:205], v[42:45]
	v_mfma_f32_16x16x32_bf16 v[38:41], v[152:155], v[210:213], v[38:41]
	v_mfma_f32_16x16x32_bf16 v[30:33], v[170:173], v[210:213], v[30:33]
	v_mfma_f32_16x16x32_bf16 v[22:25], v[152:155], v[218:221], v[22:25]
	v_mfma_f32_16x16x32_bf16 v[14:17], v[170:173], v[218:221], v[14:17]
	v_mfma_f32_16x16x32_bf16 v[54:57], v[174:177], v[190:193], v[54:57]
	v_mfma_f32_16x16x32_bf16 v[46:49], v[182:185], v[190:193], v[46:49]
	v_mfma_f32_16x16x32_bf16 v[34:37], v[174:177], v[198:201], v[34:37]
	v_mfma_f32_16x16x32_bf16 v[26:29], v[182:185], v[198:201], v[26:29]
	v_mfma_f32_16x16x32_bf16 v[18:21], v[174:177], v[206:209], v[18:21]
	v_mfma_f32_16x16x32_bf16 v[10:13], v[182:185], v[206:209], v[10:13]
	v_mfma_f32_16x16x32_bf16 v[6:9], v[174:177], v[214:217], v[6:9]
	v_mfma_f32_16x16x32_bf16 v[2:5], v[182:185], v[214:217], v[2:5]
	v_mfma_f32_16x16x32_bf16 v[54:57], v[178:181], v[194:197], v[54:57]
	v_mfma_f32_16x16x32_bf16 v[46:49], v[186:189], v[194:197], v[46:49]
	v_mfma_f32_16x16x32_bf16 v[34:37], v[178:181], v[202:205], v[34:37]
	v_mfma_f32_16x16x32_bf16 v[26:29], v[186:189], v[202:205], v[26:29]
	v_mfma_f32_16x16x32_bf16 v[18:21], v[178:181], v[210:213], v[18:21]
	v_mfma_f32_16x16x32_bf16 v[10:13], v[186:189], v[210:213], v[10:13]
	v_mfma_f32_16x16x32_bf16 v[6:9], v[178:181], v[218:221], v[6:9]
	v_mfma_f32_16x16x32_bf16 v[2:5], v[186:189], v[218:221], v[2:5]
	s_setprio 0
	s_barrier
	ds_read_b128 v[148:151], v165
	ds_read_b128 v[152:155], v165 offset:1024
	ds_read_b128 v[156:159], v165 offset:2048
	ds_read_b128 v[170:173], v165 offset:3072
	ds_read_b128 v[174:177], v169
	ds_read_b128 v[178:181], v169 offset:1024
	ds_read_b128 v[182:185], v169 offset:2048
	ds_read_b128 v[186:189], v169 offset:3072
	s_add_u32 s28, s28, 0x80000
	s_addc_u32 s29, s29, 0
	s_mov_b32 m0, s37
	v_lshl_add_u64 v[230:231], s[28:29], 0, v[136:137]
	ds_read_b128 v[190:193], v164 offset:32768
	ds_read_b128 v[194:197], v164 offset:33792
	ds_read_b128 v[198:201], v164 offset:34816
	ds_read_b128 v[202:205], v164 offset:35840
	ds_read_b128 v[206:209], v164 offset:36864
	ds_read_b128 v[210:213], v164 offset:37888
	ds_read_b128 v[214:217], v164 offset:38912
	ds_read_b128 v[218:221], v164 offset:39936
	global_load_lds_dwordx4 v[230:231], off
	v_lshl_add_u64 v[230:231], s[28:29], 0, v[132:133]
	s_mov_b32 m0, s38
	s_nop 0
	global_load_lds_dwordx4 v[230:231], off
	s_waitcnt vmcnt(8)
	s_waitcnt lgkmcnt(0)
	s_barrier
	s_setprio 1
	v_mfma_f32_16x16x32_bf16 v[126:129], v[148:151], v[190:193], v[126:129]
	v_mfma_f32_16x16x32_bf16 v[122:125], v[156:159], v[190:193], v[122:125]
	v_mfma_f32_16x16x32_bf16 v[118:121], v[148:151], v[198:201], v[118:121]
	v_mfma_f32_16x16x32_bf16 v[110:113], v[156:159], v[198:201], v[110:113]
	v_mfma_f32_16x16x32_bf16 v[102:105], v[148:151], v[206:209], v[102:105]
	v_mfma_f32_16x16x32_bf16 v[94:97], v[156:159], v[206:209], v[94:97]
	v_mfma_f32_16x16x32_bf16 v[86:89], v[148:151], v[214:217], v[86:89]
	v_mfma_f32_16x16x32_bf16 v[78:81], v[156:159], v[214:217], v[78:81]
	v_mfma_f32_16x16x32_bf16 v[126:129], v[152:155], v[194:197], v[126:129]
	v_mfma_f32_16x16x32_bf16 v[122:125], v[170:173], v[194:197], v[122:125]
	v_mfma_f32_16x16x32_bf16 v[118:121], v[152:155], v[202:205], v[118:121]
	v_mfma_f32_16x16x32_bf16 v[110:113], v[170:173], v[202:205], v[110:113]
	v_mfma_f32_16x16x32_bf16 v[102:105], v[152:155], v[210:213], v[102:105]
	v_mfma_f32_16x16x32_bf16 v[94:97], v[170:173], v[210:213], v[94:97]
	v_mfma_f32_16x16x32_bf16 v[86:89], v[152:155], v[218:221], v[86:89]
	v_mfma_f32_16x16x32_bf16 v[78:81], v[170:173], v[218:221], v[78:81]
	v_mfma_f32_16x16x32_bf16 v[114:117], v[174:177], v[190:193], v[114:117]
	v_mfma_f32_16x16x32_bf16 v[106:109], v[182:185], v[190:193], v[106:109]
	v_mfma_f32_16x16x32_bf16 v[98:101], v[174:177], v[198:201], v[98:101]
	v_mfma_f32_16x16x32_bf16 v[90:93], v[182:185], v[198:201], v[90:93]
	v_mfma_f32_16x16x32_bf16 v[82:85], v[174:177], v[206:209], v[82:85]
	v_mfma_f32_16x16x32_bf16 v[74:77], v[182:185], v[206:209], v[74:77]
	v_mfma_f32_16x16x32_bf16 v[70:73], v[174:177], v[214:217], v[70:73]
	v_mfma_f32_16x16x32_bf16 v[66:69], v[182:185], v[214:217], v[66:69]
	v_mfma_f32_16x16x32_bf16 v[114:117], v[178:181], v[194:197], v[114:117]
	v_mfma_f32_16x16x32_bf16 v[106:109], v[186:189], v[194:197], v[106:109]
	v_mfma_f32_16x16x32_bf16 v[98:101], v[178:181], v[202:205], v[98:101]
	v_mfma_f32_16x16x32_bf16 v[90:93], v[186:189], v[202:205], v[90:93]
	v_mfma_f32_16x16x32_bf16 v[82:85], v[178:181], v[210:213], v[82:85]
	v_mfma_f32_16x16x32_bf16 v[74:77], v[186:189], v[210:213], v[74:77]
	v_mfma_f32_16x16x32_bf16 v[70:73], v[178:181], v[218:221], v[70:73]
	v_mfma_f32_16x16x32_bf16 v[66:69], v[186:189], v[218:221], v[66:69]
	s_setprio 0
	s_barrier
	s_add_i32 s28, s45, s30
	v_lshl_add_u64 v[222:223], v[222:223], 0, s[8:9]
	s_mov_b32 m0, s28
	ds_read_b128 v[190:193], v164 offset:49152
	ds_read_b128 v[194:197], v164 offset:50176
	ds_read_b128 v[198:201], v164 offset:51200
	ds_read_b128 v[202:205], v164 offset:52224
	ds_read_b128 v[206:209], v164 offset:53248
	ds_read_b128 v[210:213], v164 offset:54272
	ds_read_b128 v[214:217], v164 offset:55296
	ds_read_b128 v[218:221], v164 offset:56320
	global_load_lds_dwordx4 v[222:223], off
	s_add_i32 m0, s28, 0x2000
	s_add_u32 s26, s26, 0x80080
	v_lshl_add_u64 v[222:223], v[224:225], 0, s[8:9]
	s_addc_u32 s27, s27, 0
	s_add_i32 s28, s46, s30
	global_load_lds_dwordx4 v[222:223], off
	v_lshl_add_u64 v[222:223], s[26:27], 0, v[134:135]
	s_mov_b32 m0, s28
	s_nop 0
	global_load_lds_dwordx4 v[222:223], off
	v_lshl_add_u64 v[222:223], s[26:27], 0, v[130:131]
	s_add_i32 m0, s28, 0x2000
	s_nop 0
	global_load_lds_dwordx4 v[222:223], off
	v_lshl_add_u64 v[222:223], v[226:227], 0, s[8:9]
	s_mov_b32 m0, s39
	s_nop 0
	global_load_lds_dwordx4 v[222:223], off
	v_lshl_add_u64 v[222:223], v[228:229], 0, s[8:9]
	s_mov_b32 m0, s40
	s_nop 0
	global_load_lds_dwordx4 v[222:223], off
	s_waitcnt vmcnt(8)
	s_waitcnt lgkmcnt(0)
	s_barrier
	s_setprio 1
	v_mfma_f32_16x16x32_bf16 v[62:65], v[148:151], v[190:193], v[62:65]
	v_mfma_f32_16x16x32_bf16 v[58:61], v[156:159], v[190:193], v[58:61]
	v_mfma_f32_16x16x32_bf16 v[50:53], v[148:151], v[198:201], v[50:53]
	v_mfma_f32_16x16x32_bf16 v[42:45], v[156:159], v[198:201], v[42:45]
	v_mfma_f32_16x16x32_bf16 v[38:41], v[148:151], v[206:209], v[38:41]
	v_mfma_f32_16x16x32_bf16 v[30:33], v[156:159], v[206:209], v[30:33]
	v_mfma_f32_16x16x32_bf16 v[22:25], v[148:151], v[214:217], v[22:25]
	v_mfma_f32_16x16x32_bf16 v[14:17], v[156:159], v[214:217], v[14:17]
	v_mfma_f32_16x16x32_bf16 v[62:65], v[152:155], v[194:197], v[62:65]
	v_mfma_f32_16x16x32_bf16 v[58:61], v[170:173], v[194:197], v[58:61]
	v_mfma_f32_16x16x32_bf16 v[50:53], v[152:155], v[202:205], v[50:53]
	v_mfma_f32_16x16x32_bf16 v[42:45], v[170:173], v[202:205], v[42:45]
	v_mfma_f32_16x16x32_bf16 v[38:41], v[152:155], v[210:213], v[38:41]
	v_mfma_f32_16x16x32_bf16 v[30:33], v[170:173], v[210:213], v[30:33]
	v_mfma_f32_16x16x32_bf16 v[22:25], v[152:155], v[218:221], v[22:25]
	v_mfma_f32_16x16x32_bf16 v[14:17], v[170:173], v[218:221], v[14:17]
	v_mfma_f32_16x16x32_bf16 v[54:57], v[174:177], v[190:193], v[54:57]
	v_mfma_f32_16x16x32_bf16 v[46:49], v[182:185], v[190:193], v[46:49]
	v_mfma_f32_16x16x32_bf16 v[34:37], v[174:177], v[198:201], v[34:37]
	v_mfma_f32_16x16x32_bf16 v[26:29], v[182:185], v[198:201], v[26:29]
	v_mfma_f32_16x16x32_bf16 v[18:21], v[174:177], v[206:209], v[18:21]
	v_mfma_f32_16x16x32_bf16 v[10:13], v[182:185], v[206:209], v[10:13]
	v_mfma_f32_16x16x32_bf16 v[6:9], v[174:177], v[214:217], v[6:9]
	v_mfma_f32_16x16x32_bf16 v[2:5], v[182:185], v[214:217], v[2:5]
	v_mfma_f32_16x16x32_bf16 v[54:57], v[178:181], v[194:197], v[54:57]
	v_mfma_f32_16x16x32_bf16 v[46:49], v[186:189], v[194:197], v[46:49]
	v_mfma_f32_16x16x32_bf16 v[34:37], v[178:181], v[202:205], v[34:37]
	v_mfma_f32_16x16x32_bf16 v[26:29], v[186:189], v[202:205], v[26:29]
	v_mfma_f32_16x16x32_bf16 v[18:21], v[178:181], v[210:213], v[18:21]
	v_mfma_f32_16x16x32_bf16 v[10:13], v[186:189], v[210:213], v[10:13]
	v_mfma_f32_16x16x32_bf16 v[6:9], v[178:181], v[218:221], v[6:9]
	v_mfma_f32_16x16x32_bf16 v[2:5], v[186:189], v[218:221], v[2:5]
	s_setprio 0
	s_barrier
	s_add_i32 s69, s69, 2
	s_add_u32 s24, s24, 0x100
	s_addc_u32 s25, s25, 0
	s_add_u32 s63, s63, 0x100
	s_addc_u32 s68, s68, 0
	s_cmp_gt_u32 s69, 29
	s_cbranch_scc0 .LBB0_1262
	s_and_b64 vcc, exec, s[12:13]
	s_cbranch_vccz .LBB0_1265
	s_barrier

.LBB0_1433:
	ds_read_b128 v[154:157], v149
	ds_read_b128 v[158:161], v149 offset:1024
	ds_read_b128 v[162:165], v149 offset:2048
	ds_read_b128 v[170:173], v149 offset:3072
	ds_read_b128 v[174:177], v150
	ds_read_b128 v[178:181], v150 offset:1024
	ds_read_b128 v[182:185], v150 offset:2048
	ds_read_b128 v[186:189], v150 offset:3072
	s_add_u32 s28, s26, 0xfff80080
	s_addc_u32 s29, s27, -1
	s_cmp_eq_u32 s52, 28
	s_cselect_b32 s31, s17, s29
	s_cselect_b32 s30, s48, s28
	s_cselect_b32 s29, s15, s51
	s_cselect_b32 s28, s49, s50
	v_lshl_add_u64 v[146:147], s[26:27], 0, v[138:139]
	s_add_i32 m0, s25, 0xc000
	ds_read_b128 v[190:193], v151
	ds_read_b128 v[194:197], v151 offset:1024
	ds_read_b128 v[198:201], v151 offset:2048
	ds_read_b128 v[202:205], v151 offset:3072
	ds_read_b128 v[206:209], v151 offset:4096
	ds_read_b128 v[210:213], v151 offset:5120
	ds_read_b128 v[214:217], v151 offset:6144
	ds_read_b128 v[218:221], v151 offset:7168
	global_load_lds_dwordx4 v[146:147], off
	v_lshl_add_u64 v[146:147], s[26:27], 0, v[140:141]
	s_add_i32 m0, s25, 0xe000
	s_nop 0
	global_load_lds_dwordx4 v[146:147], off
	s_waitcnt vmcnt(8)
	s_waitcnt lgkmcnt(0)
	s_barrier
	s_setprio 1
	v_mfma_f32_16x16x32_bf16 v[126:129], v[154:157], v[190:193], v[126:129]
	v_mfma_f32_16x16x32_bf16 v[122:125], v[162:165], v[190:193], v[122:125]
	v_mfma_f32_16x16x32_bf16 v[118:121], v[154:157], v[198:201], v[118:121]
	v_mfma_f32_16x16x32_bf16 v[110:113], v[162:165], v[198:201], v[110:113]
	v_mfma_f32_16x16x32_bf16 v[102:105], v[154:157], v[206:209], v[102:105]
	v_mfma_f32_16x16x32_bf16 v[94:97], v[162:165], v[206:209], v[94:97]
	v_mfma_f32_16x16x32_bf16 v[86:89], v[154:157], v[214:217], v[86:89]
	v_mfma_f32_16x16x32_bf16 v[78:81], v[162:165], v[214:217], v[78:81]
	v_mfma_f32_16x16x32_bf16 v[126:129], v[158:161], v[194:197], v[126:129]
	v_mfma_f32_16x16x32_bf16 v[122:125], v[170:173], v[194:197], v[122:125]
	v_mfma_f32_16x16x32_bf16 v[118:121], v[158:161], v[202:205], v[118:121]
	v_mfma_f32_16x16x32_bf16 v[110:113], v[170:173], v[202:205], v[110:113]
	v_mfma_f32_16x16x32_bf16 v[102:105], v[158:161], v[210:213], v[102:105]
	v_mfma_f32_16x16x32_bf16 v[94:97], v[170:173], v[210:213], v[94:97]
	v_mfma_f32_16x16x32_bf16 v[86:89], v[158:161], v[218:221], v[86:89]
	v_mfma_f32_16x16x32_bf16 v[78:81], v[170:173], v[218:221], v[78:81]
	v_mfma_f32_16x16x32_bf16 v[114:117], v[174:177], v[190:193], v[114:117]
	v_mfma_f32_16x16x32_bf16 v[106:109], v[182:185], v[190:193], v[106:109]
	v_mfma_f32_16x16x32_bf16 v[98:101], v[174:177], v[198:201], v[98:101]
	v_mfma_f32_16x16x32_bf16 v[90:93], v[182:185], v[198:201], v[90:93]
	v_mfma_f32_16x16x32_bf16 v[82:85], v[174:177], v[206:209], v[82:85]
	v_mfma_f32_16x16x32_bf16 v[74:77], v[182:185], v[206:209], v[74:77]
	v_mfma_f32_16x16x32_bf16 v[70:73], v[174:177], v[214:217], v[70:73]
	v_mfma_f32_16x16x32_bf16 v[66:69], v[182:185], v[214:217], v[66:69]
	v_mfma_f32_16x16x32_bf16 v[114:117], v[178:181], v[194:197], v[114:117]
	v_mfma_f32_16x16x32_bf16 v[106:109], v[186:189], v[194:197], v[106:109]
	v_mfma_f32_16x16x32_bf16 v[98:101], v[178:181], v[202:205], v[98:101]
	v_mfma_f32_16x16x32_bf16 v[90:93], v[186:189], v[202:205], v[90:93]
	v_mfma_f32_16x16x32_bf16 v[82:85], v[178:181], v[210:213], v[82:85]
	v_mfma_f32_16x16x32_bf16 v[74:77], v[186:189], v[210:213], v[74:77]
	v_mfma_f32_16x16x32_bf16 v[70:73], v[178:181], v[218:221], v[70:73]
	v_mfma_f32_16x16x32_bf16 v[66:69], v[186:189], v[218:221], v[66:69]
	s_setprio 0
	s_barrier
	s_add_i32 s53, s43, s35
	v_lshl_add_u64 v[146:147], s[28:29], 0, v[132:133]
	s_mov_b32 m0, s53
	ds_read_b128 v[190:193], v151 offset:16384
	ds_read_b128 v[194:197], v151 offset:17408
	ds_read_b128 v[198:201], v151 offset:18432
	ds_read_b128 v[202:205], v151 offset:19456
	ds_read_b128 v[206:209], v151 offset:20480
	ds_read_b128 v[210:213], v151 offset:21504
	ds_read_b128 v[214:217], v151 offset:22528
	ds_read_b128 v[218:221], v151 offset:23552
	global_load_lds_dwordx4 v[146:147], off
	s_add_i32 m0, s53, 0x2000
	s_add_u32 s68, s28, 0x80000
	v_lshl_add_u64 v[222:223], s[28:29], 0, v[136:137]
	s_addc_u32 s69, s29, 0
	s_add_i32 s53, s44, s35
	global_load_lds_dwordx4 v[222:223], off
	v_lshl_add_u64 v[224:225], s[68:69], 0, v[132:133]
	s_mov_b32 m0, s53
	v_lshl_add_u64 v[226:227], s[30:31], 0, v[134:135]
	global_load_lds_dwordx4 v[224:225], off
	v_lshl_add_u64 v[224:225], s[68:69], 0, v[136:137]
	s_add_i32 m0, s53, 0x2000
	s_nop 0
	global_load_lds_dwordx4 v[224:225], off
	v_lshl_add_u64 v[224:225], s[30:31], 0, v[130:131]
	s_mov_b32 m0, s25
	s_nop 0
	global_load_lds_dwordx4 v[224:225], off
	s_mov_b32 m0, s36
	s_nop 0
	global_load_lds_dwordx4 v[226:227], off
	s_waitcnt vmcnt(8)
	s_waitcnt lgkmcnt(0)
	s_barrier
	s_setprio 1
	v_mfma_f32_16x16x32_bf16 v[62:65], v[154:157], v[190:193], v[62:65]
	v_mfma_f32_16x16x32_bf16 v[58:61], v[162:165], v[190:193], v[58:61]
	v_mfma_f32_16x16x32_bf16 v[54:57], v[154:157], v[198:201], v[54:57]
	v_mfma_f32_16x16x32_bf16 v[46:49], v[162:165], v[198:201], v[46:49]
	v_mfma_f32_16x16x32_bf16 v[38:41], v[154:157], v[206:209], v[38:41]
	v_mfma_f32_16x16x32_bf16 v[30:33], v[162:165], v[206:209], v[30:33]
	v_mfma_f32_16x16x32_bf16 v[22:25], v[154:157], v[214:217], v[22:25]
	v_mfma_f32_16x16x32_bf16 v[14:17], v[162:165], v[214:217], v[14:17]
	v_mfma_f32_16x16x32_bf16 v[62:65], v[158:161], v[194:197], v[62:65]
	v_mfma_f32_16x16x32_bf16 v[58:61], v[170:173], v[194:197], v[58:61]
	v_mfma_f32_16x16x32_bf16 v[54:57], v[158:161], v[202:205], v[54:57]
	v_mfma_f32_16x16x32_bf16 v[46:49], v[170:173], v[202:205], v[46:49]
	v_mfma_f32_16x16x32_bf16 v[38:41], v[158:161], v[210:213], v[38:41]
	v_mfma_f32_16x16x32_bf16 v[30:33], v[170:173], v[210:213], v[30:33]
	v_mfma_f32_16x16x32_bf16 v[22:25], v[158:161], v[218:221], v[22:25]
	v_mfma_f32_16x16x32_bf16 v[14:17], v[170:173], v[218:221], v[14:17]
	v_mfma_f32_16x16x32_bf16 v[50:53], v[174:177], v[190:193], v[50:53]
	v_mfma_f32_16x16x32_bf16 v[42:45], v[182:185], v[190:193], v[42:45]
	v_mfma_f32_16x16x32_bf16 v[34:37], v[174:177], v[198:201], v[34:37]
	v_mfma_f32_16x16x32_bf16 v[26:29], v[182:185], v[198:201], v[26:29]
	v_mfma_f32_16x16x32_bf16 v[18:21], v[174:177], v[206:209], v[18:21]
	v_mfma_f32_16x16x32_bf16 v[10:13], v[182:185], v[206:209], v[10:13]
	v_mfma_f32_16x16x32_bf16 v[6:9], v[174:177], v[214:217], v[6:9]
	v_mfma_f32_16x16x32_bf16 v[2:5], v[182:185], v[214:217], v[2:5]
	v_mfma_f32_16x16x32_bf16 v[50:53], v[178:181], v[194:197], v[50:53]
	v_mfma_f32_16x16x32_bf16 v[42:45], v[186:189], v[194:197], v[42:45]
	v_mfma_f32_16x16x32_bf16 v[34:37], v[178:181], v[202:205], v[34:37]
	v_mfma_f32_16x16x32_bf16 v[26:29], v[186:189], v[202:205], v[26:29]
	v_mfma_f32_16x16x32_bf16 v[18:21], v[178:181], v[210:213], v[18:21]
	v_mfma_f32_16x16x32_bf16 v[10:13], v[186:189], v[210:213], v[10:13]
	v_mfma_f32_16x16x32_bf16 v[6:9], v[178:181], v[218:221], v[6:9]
	v_mfma_f32_16x16x32_bf16 v[2:5], v[186:189], v[218:221], v[2:5]
	s_setprio 0
	s_barrier
	ds_read_b128 v[154:157], v152
	ds_read_b128 v[158:161], v152 offset:1024
	ds_read_b128 v[162:165], v152 offset:2048
	ds_read_b128 v[170:173], v152 offset:3072
	ds_read_b128 v[174:177], v153
	ds_read_b128 v[178:181], v153 offset:1024
	ds_read_b128 v[182:185], v153 offset:2048
	ds_read_b128 v[186:189], v153 offset:3072
	s_add_u32 s30, s30, 0x80000
	s_addc_u32 s31, s31, 0
	s_mov_b32 m0, s37
	v_lshl_add_u64 v[228:229], s[30:31], 0, v[130:131]
	ds_read_b128 v[190:193], v151 offset:32768
	ds_read_b128 v[194:197], v151 offset:33792
	ds_read_b128 v[198:201], v151 offset:34816
	ds_read_b128 v[202:205], v151 offset:35840
	ds_read_b128 v[206:209], v151 offset:36864
	ds_read_b128 v[210:213], v151 offset:37888
	ds_read_b128 v[214:217], v151 offset:38912
	ds_read_b128 v[218:221], v151 offset:39936
	global_load_lds_dwordx4 v[228:229], off
	v_lshl_add_u64 v[228:229], s[30:31], 0, v[134:135]
	s_mov_b32 m0, s38
	s_nop 0
	global_load_lds_dwordx4 v[228:229], off
	s_waitcnt vmcnt(8)
	s_waitcnt lgkmcnt(0)
	s_barrier
	s_setprio 1
	v_mfma_f32_16x16x32_bf16 v[126:129], v[154:157], v[190:193], v[126:129]
	v_mfma_f32_16x16x32_bf16 v[122:125], v[162:165], v[190:193], v[122:125]
	v_mfma_f32_16x16x32_bf16 v[118:121], v[154:157], v[198:201], v[118:121]
	v_mfma_f32_16x16x32_bf16 v[110:113], v[162:165], v[198:201], v[110:113]
	v_mfma_f32_16x16x32_bf16 v[102:105], v[154:157], v[206:209], v[102:105]
	v_mfma_f32_16x16x32_bf16 v[94:97], v[162:165], v[206:209], v[94:97]
	v_mfma_f32_16x16x32_bf16 v[86:89], v[154:157], v[214:217], v[86:89]
	v_mfma_f32_16x16x32_bf16 v[78:81], v[162:165], v[214:217], v[78:81]
	v_mfma_f32_16x16x32_bf16 v[126:129], v[158:161], v[194:197], v[126:129]
	v_mfma_f32_16x16x32_bf16 v[122:125], v[170:173], v[194:197], v[122:125]
	v_mfma_f32_16x16x32_bf16 v[118:121], v[158:161], v[202:205], v[118:121]
	v_mfma_f32_16x16x32_bf16 v[110:113], v[170:173], v[202:205], v[110:113]
	v_mfma_f32_16x16x32_bf16 v[102:105], v[158:161], v[210:213], v[102:105]
	v_mfma_f32_16x16x32_bf16 v[94:97], v[170:173], v[210:213], v[94:97]
	v_mfma_f32_16x16x32_bf16 v[86:89], v[158:161], v[218:221], v[86:89]
	v_mfma_f32_16x16x32_bf16 v[78:81], v[170:173], v[218:221], v[78:81]
	v_mfma_f32_16x16x32_bf16 v[114:117], v[174:177], v[190:193], v[114:117]
	v_mfma_f32_16x16x32_bf16 v[106:109], v[182:185], v[190:193], v[106:109]
	v_mfma_f32_16x16x32_bf16 v[98:101], v[174:177], v[198:201], v[98:101]
	v_mfma_f32_16x16x32_bf16 v[90:93], v[182:185], v[198:201], v[90:93]
	v_mfma_f32_16x16x32_bf16 v[82:85], v[174:177], v[206:209], v[82:85]
	v_mfma_f32_16x16x32_bf16 v[74:77], v[182:185], v[206:209], v[74:77]
	v_mfma_f32_16x16x32_bf16 v[70:73], v[174:177], v[214:217], v[70:73]
	v_mfma_f32_16x16x32_bf16 v[66:69], v[182:185], v[214:217], v[66:69]
	v_mfma_f32_16x16x32_bf16 v[114:117], v[178:181], v[194:197], v[114:117]
	v_mfma_f32_16x16x32_bf16 v[106:109], v[186:189], v[194:197], v[106:109]
	v_mfma_f32_16x16x32_bf16 v[98:101], v[178:181], v[202:205], v[98:101]
	v_mfma_f32_16x16x32_bf16 v[90:93], v[186:189], v[202:205], v[90:93]
	v_mfma_f32_16x16x32_bf16 v[82:85], v[178:181], v[210:213], v[82:85]
	v_mfma_f32_16x16x32_bf16 v[74:77], v[186:189], v[210:213], v[74:77]
	v_mfma_f32_16x16x32_bf16 v[70:73], v[178:181], v[218:221], v[70:73]
	v_mfma_f32_16x16x32_bf16 v[66:69], v[186:189], v[218:221], v[66:69]
	s_setprio 0
	s_barrier
	s_add_i32 s30, s45, s35
	v_lshl_add_u64 v[146:147], v[146:147], 0, s[8:9]
	s_mov_b32 m0, s30
	ds_read_b128 v[190:193], v151 offset:49152
	ds_read_b128 v[194:197], v151 offset:50176
	ds_read_b128 v[198:201], v151 offset:51200
	ds_read_b128 v[202:205], v151 offset:52224
	ds_read_b128 v[206:209], v151 offset:53248
	ds_read_b128 v[210:213], v151 offset:54272
	ds_read_b128 v[214:217], v151 offset:55296
	ds_read_b128 v[218:221], v151 offset:56320
	global_load_lds_dwordx4 v[146:147], off
	s_add_i32 m0, s30, 0x2000
	s_add_u32 s28, s28, 0x80080
	v_lshl_add_u64 v[146:147], v[222:223], 0, s[8:9]
	s_addc_u32 s29, s29, 0
	s_add_i32 s30, s46, s35
	global_load_lds_dwordx4 v[146:147], off
	v_lshl_add_u64 v[146:147], s[28:29], 0, v[132:133]
	s_mov_b32 m0, s30
	s_nop 0
	global_load_lds_dwordx4 v[146:147], off
	v_lshl_add_u64 v[146:147], s[28:29], 0, v[136:137]
	s_add_i32 m0, s30, 0x2000
	s_nop 0
	global_load_lds_dwordx4 v[146:147], off
	v_lshl_add_u64 v[146:147], v[224:225], 0, s[8:9]
	s_mov_b32 m0, s39
	s_nop 0
	global_load_lds_dwordx4 v[146:147], off
	v_lshl_add_u64 v[146:147], v[226:227], 0, s[8:9]
	s_mov_b32 m0, s40
	s_nop 0
	global_load_lds_dwordx4 v[146:147], off
	s_waitcnt vmcnt(8)
	s_waitcnt lgkmcnt(0)
	s_barrier
	s_setprio 1
	v_mfma_f32_16x16x32_bf16 v[62:65], v[154:157], v[190:193], v[62:65]
	v_mfma_f32_16x16x32_bf16 v[58:61], v[162:165], v[190:193], v[58:61]
	v_mfma_f32_16x16x32_bf16 v[54:57], v[154:157], v[198:201], v[54:57]
	v_mfma_f32_16x16x32_bf16 v[46:49], v[162:165], v[198:201], v[46:49]
	v_mfma_f32_16x16x32_bf16 v[38:41], v[154:157], v[206:209], v[38:41]
	v_mfma_f32_16x16x32_bf16 v[30:33], v[162:165], v[206:209], v[30:33]
	v_mfma_f32_16x16x32_bf16 v[22:25], v[154:157], v[214:217], v[22:25]
	v_mfma_f32_16x16x32_bf16 v[14:17], v[162:165], v[214:217], v[14:17]
	v_mfma_f32_16x16x32_bf16 v[62:65], v[158:161], v[194:197], v[62:65]
	v_mfma_f32_16x16x32_bf16 v[58:61], v[170:173], v[194:197], v[58:61]
	v_mfma_f32_16x16x32_bf16 v[54:57], v[158:161], v[202:205], v[54:57]
	v_mfma_f32_16x16x32_bf16 v[46:49], v[170:173], v[202:205], v[46:49]
	v_mfma_f32_16x16x32_bf16 v[38:41], v[158:161], v[210:213], v[38:41]
	v_mfma_f32_16x16x32_bf16 v[30:33], v[170:173], v[210:213], v[30:33]
	v_mfma_f32_16x16x32_bf16 v[22:25], v[158:161], v[218:221], v[22:25]
	v_mfma_f32_16x16x32_bf16 v[14:17], v[170:173], v[218:221], v[14:17]
	v_mfma_f32_16x16x32_bf16 v[50:53], v[174:177], v[190:193], v[50:53]
	v_mfma_f32_16x16x32_bf16 v[42:45], v[182:185], v[190:193], v[42:45]
	v_mfma_f32_16x16x32_bf16 v[34:37], v[174:177], v[198:201], v[34:37]
	v_mfma_f32_16x16x32_bf16 v[26:29], v[182:185], v[198:201], v[26:29]
	v_mfma_f32_16x16x32_bf16 v[18:21], v[174:177], v[206:209], v[18:21]
	v_mfma_f32_16x16x32_bf16 v[10:13], v[182:185], v[206:209], v[10:13]
	v_mfma_f32_16x16x32_bf16 v[6:9], v[174:177], v[214:217], v[6:9]
	v_mfma_f32_16x16x32_bf16 v[2:5], v[182:185], v[214:217], v[2:5]
	v_mfma_f32_16x16x32_bf16 v[50:53], v[178:181], v[194:197], v[50:53]
	v_mfma_f32_16x16x32_bf16 v[42:45], v[186:189], v[194:197], v[42:45]
	v_mfma_f32_16x16x32_bf16 v[34:37], v[178:181], v[202:205], v[34:37]
	v_mfma_f32_16x16x32_bf16 v[26:29], v[186:189], v[202:205], v[26:29]
	v_mfma_f32_16x16x32_bf16 v[18:21], v[178:181], v[210:213], v[18:21]
	v_mfma_f32_16x16x32_bf16 v[10:13], v[186:189], v[210:213], v[10:13]
	v_mfma_f32_16x16x32_bf16 v[6:9], v[178:181], v[218:221], v[6:9]
	v_mfma_f32_16x16x32_bf16 v[2:5], v[186:189], v[218:221], v[2:5]
	s_setprio 0
	s_barrier
	s_add_i32 s52, s52, 2
	s_add_u32 s26, s26, 0x100
	s_addc_u32 s27, s27, 0
	s_add_u32 s50, s50, 0x100
	s_addc_u32 s51, s51, 0
	s_cmp_gt_u32 s52, 29
	s_cbranch_scc0 .LBB0_1433
	s_and_b64 vcc, exec, s[12:13]
	s_cbranch_vccz .LBB0_1436
	s_barrier

.LBB0_1595:
	ds_read_b128 v[146:149], v178
	ds_read_b128 v[150:153], v178 offset:1024
	ds_read_b128 v[154:157], v178 offset:2048
	ds_read_b128 v[158:161], v178 offset:3072
	ds_read_b128 v[182:185], v179
	ds_read_b128 v[186:189], v179 offset:1024
	ds_read_b128 v[190:193], v179 offset:2048
	ds_read_b128 v[194:197], v179 offset:3072
	s_add_u32 s34, s30, 0xfffc0080
	s_addc_u32 s35, s31, -1
	s_cmp_eq_u32 s72, 12
	s_cselect_b32 s37, s23, s35
	s_cselect_b32 s36, s68, s34
	s_cselect_b32 s35, s21, s71
	s_cselect_b32 s34, s69, s70
	v_lshl_add_u64 v[162:163], s[30:31], 0, v[138:139]
	s_add_i32 m0, s29, 0xc000
	ds_read_b128 v[198:201], v180
	ds_read_b128 v[202:205], v180 offset:1024
	ds_read_b128 v[206:209], v180 offset:2048
	ds_read_b128 v[210:213], v180 offset:3072
	ds_read_b128 v[214:217], v180 offset:4096
	ds_read_b128 v[218:221], v180 offset:5120
	ds_read_b128 v[222:225], v180 offset:6144
	ds_read_b128 v[226:229], v180 offset:7168
	global_load_lds_dwordx4 v[162:163], off
	v_lshl_add_u64 v[162:163], s[30:31], 0, v[140:141]
	s_add_i32 m0, s29, 0xe000
	s_nop 0
	global_load_lds_dwordx4 v[162:163], off
	s_waitcnt vmcnt(8)
	s_waitcnt lgkmcnt(0)
	s_barrier
	s_setprio 1
	v_mfma_i32_16x16x64_i8 v[126:129], v[146:149], v[198:201], v[126:129]
	v_mfma_i32_16x16x64_i8 v[118:121], v[154:157], v[198:201], v[118:121]
	v_mfma_i32_16x16x64_i8 v[110:113], v[146:149], v[206:209], v[110:113]
	v_mfma_i32_16x16x64_i8 v[102:105], v[154:157], v[206:209], v[102:105]
	v_mfma_i32_16x16x64_i8 v[94:97], v[146:149], v[214:217], v[94:97]
	v_mfma_i32_16x16x64_i8 v[86:89], v[154:157], v[214:217], v[86:89]
	v_mfma_i32_16x16x64_i8 v[78:81], v[146:149], v[222:225], v[78:81]
	v_mfma_i32_16x16x64_i8 v[70:73], v[154:157], v[222:225], v[70:73]
	v_mfma_i32_16x16x64_i8 v[126:129], v[150:153], v[202:205], v[126:129]
	v_mfma_i32_16x16x64_i8 v[118:121], v[158:161], v[202:205], v[118:121]
	v_mfma_i32_16x16x64_i8 v[110:113], v[150:153], v[210:213], v[110:113]
	v_mfma_i32_16x16x64_i8 v[102:105], v[158:161], v[210:213], v[102:105]
	v_mfma_i32_16x16x64_i8 v[94:97], v[150:153], v[218:221], v[94:97]
	v_mfma_i32_16x16x64_i8 v[86:89], v[158:161], v[218:221], v[86:89]
	v_mfma_i32_16x16x64_i8 v[78:81], v[150:153], v[226:229], v[78:81]
	v_mfma_i32_16x16x64_i8 v[70:73], v[158:161], v[226:229], v[70:73]
	v_mfma_i32_16x16x64_i8 v[122:125], v[182:185], v[198:201], v[122:125]
	v_mfma_i32_16x16x64_i8 v[114:117], v[190:193], v[198:201], v[114:117]
	v_mfma_i32_16x16x64_i8 v[106:109], v[182:185], v[206:209], v[106:109]
	v_mfma_i32_16x16x64_i8 v[98:101], v[190:193], v[206:209], v[98:101]
	v_mfma_i32_16x16x64_i8 v[90:93], v[182:185], v[214:217], v[90:93]
	v_mfma_i32_16x16x64_i8 v[82:85], v[190:193], v[214:217], v[82:85]
	v_mfma_i32_16x16x64_i8 v[74:77], v[182:185], v[222:225], v[74:77]
	v_mfma_i32_16x16x64_i8 v[66:69], v[190:193], v[222:225], v[66:69]
	v_mfma_i32_16x16x64_i8 v[122:125], v[186:189], v[202:205], v[122:125]
	v_mfma_i32_16x16x64_i8 v[114:117], v[194:197], v[202:205], v[114:117]
	v_mfma_i32_16x16x64_i8 v[106:109], v[186:189], v[210:213], v[106:109]
	v_mfma_i32_16x16x64_i8 v[98:101], v[194:197], v[210:213], v[98:101]
	v_mfma_i32_16x16x64_i8 v[90:93], v[186:189], v[218:221], v[90:93]
	v_mfma_i32_16x16x64_i8 v[82:85], v[194:197], v[218:221], v[82:85]
	v_mfma_i32_16x16x64_i8 v[74:77], v[186:189], v[226:229], v[74:77]
	v_mfma_i32_16x16x64_i8 v[66:69], v[194:197], v[226:229], v[66:69]
	s_setprio 0
	s_barrier
	s_add_i32 s73, s48, s40
	v_lshl_add_u64 v[162:163], s[34:35], 0, v[134:135]
	s_mov_b32 m0, s73
	ds_read_b128 v[198:201], v180 offset:16384
	ds_read_b128 v[202:205], v180 offset:17408
	ds_read_b128 v[206:209], v180 offset:18432
	ds_read_b128 v[210:213], v180 offset:19456
	ds_read_b128 v[214:217], v180 offset:20480
	ds_read_b128 v[218:221], v180 offset:21504
	ds_read_b128 v[222:225], v180 offset:22528
	ds_read_b128 v[226:229], v180 offset:23552
	global_load_lds_dwordx4 v[162:163], off
	s_add_i32 m0, s73, 0x2000
	s_add_u32 s74, s34, 0x40000
	v_lshl_add_u64 v[230:231], s[34:35], 0, v[130:131]
	s_addc_u32 s75, s35, 0
	s_add_i32 s73, s49, s40
	global_load_lds_dwordx4 v[230:231], off
	v_lshl_add_u64 v[232:233], s[74:75], 0, v[134:135]
	s_mov_b32 m0, s73
	v_lshl_add_u64 v[234:235], s[36:37], 0, v[132:133]
	global_load_lds_dwordx4 v[232:233], off
	v_lshl_add_u64 v[232:233], s[74:75], 0, v[130:131]
	s_add_i32 m0, s73, 0x2000
	s_nop 0
	global_load_lds_dwordx4 v[232:233], off
	v_lshl_add_u64 v[232:233], s[36:37], 0, v[136:137]
	s_mov_b32 m0, s29
	s_nop 0
	global_load_lds_dwordx4 v[232:233], off
	s_mov_b32 m0, s42
	s_nop 0
	global_load_lds_dwordx4 v[234:235], off
	s_waitcnt vmcnt(8)
	s_waitcnt lgkmcnt(0)
	s_barrier
	s_setprio 1
	v_mfma_i32_16x16x64_i8 v[62:65], v[146:149], v[198:201], v[62:65]
	v_mfma_i32_16x16x64_i8 v[54:57], v[154:157], v[198:201], v[54:57]
	v_mfma_i32_16x16x64_i8 v[46:49], v[146:149], v[206:209], v[46:49]
	v_mfma_i32_16x16x64_i8 v[38:41], v[154:157], v[206:209], v[38:41]
	v_mfma_i32_16x16x64_i8 v[30:33], v[146:149], v[214:217], v[30:33]
	v_mfma_i32_16x16x64_i8 v[22:25], v[154:157], v[214:217], v[22:25]
	v_mfma_i32_16x16x64_i8 v[14:17], v[146:149], v[222:225], v[14:17]
	v_mfma_i32_16x16x64_i8 v[6:9], v[154:157], v[222:225], v[6:9]
	v_mfma_i32_16x16x64_i8 v[62:65], v[150:153], v[202:205], v[62:65]
	v_mfma_i32_16x16x64_i8 v[54:57], v[158:161], v[202:205], v[54:57]
	v_mfma_i32_16x16x64_i8 v[46:49], v[150:153], v[210:213], v[46:49]
	v_mfma_i32_16x16x64_i8 v[38:41], v[158:161], v[210:213], v[38:41]
	v_mfma_i32_16x16x64_i8 v[30:33], v[150:153], v[218:221], v[30:33]
	v_mfma_i32_16x16x64_i8 v[22:25], v[158:161], v[218:221], v[22:25]
	v_mfma_i32_16x16x64_i8 v[14:17], v[150:153], v[226:229], v[14:17]
	v_mfma_i32_16x16x64_i8 v[6:9], v[158:161], v[226:229], v[6:9]
	v_mfma_i32_16x16x64_i8 v[58:61], v[182:185], v[198:201], v[58:61]
	v_mfma_i32_16x16x64_i8 v[50:53], v[190:193], v[198:201], v[50:53]
	v_mfma_i32_16x16x64_i8 v[42:45], v[182:185], v[206:209], v[42:45]
	v_mfma_i32_16x16x64_i8 v[34:37], v[190:193], v[206:209], v[34:37]
	v_mfma_i32_16x16x64_i8 v[26:29], v[182:185], v[214:217], v[26:29]
	v_mfma_i32_16x16x64_i8 v[18:21], v[190:193], v[214:217], v[18:21]
	v_mfma_i32_16x16x64_i8 v[10:13], v[182:185], v[222:225], v[10:13]
	v_mfma_i32_16x16x64_i8 v[2:5], v[190:193], v[222:225], v[2:5]
	v_mfma_i32_16x16x64_i8 v[58:61], v[186:189], v[202:205], v[58:61]
	v_mfma_i32_16x16x64_i8 v[50:53], v[194:197], v[202:205], v[50:53]
	v_mfma_i32_16x16x64_i8 v[42:45], v[186:189], v[210:213], v[42:45]
	v_mfma_i32_16x16x64_i8 v[34:37], v[194:197], v[210:213], v[34:37]
	v_mfma_i32_16x16x64_i8 v[26:29], v[186:189], v[218:221], v[26:29]
	v_mfma_i32_16x16x64_i8 v[18:21], v[194:197], v[218:221], v[18:21]
	v_mfma_i32_16x16x64_i8 v[10:13], v[186:189], v[226:229], v[10:13]
	v_mfma_i32_16x16x64_i8 v[2:5], v[194:197], v[226:229], v[2:5]
	s_setprio 0
	s_barrier
	s_add_i32 s73, 0, 0x18000
	v_add_u32_e32 v158, s73, v169
	ds_read_b128 v[146:149], v158
	ds_read_b128 v[150:153], v158 offset:1024
	ds_read_b128 v[154:157], v158 offset:2048
	ds_read_b128 v[158:161], v158 offset:3072
	ds_read_b128 v[182:185], v181
	ds_read_b128 v[186:189], v181 offset:1024
	ds_read_b128 v[190:193], v181 offset:2048
	ds_read_b128 v[194:197], v181 offset:3072
	s_add_u32 s36, s36, 0x40000
	s_addc_u32 s37, s37, 0
	s_mov_b32 m0, s43
	v_lshl_add_u64 v[236:237], s[36:37], 0, v[136:137]
	ds_read_b128 v[198:201], v180 offset:32768
	ds_read_b128 v[202:205], v180 offset:33792
	ds_read_b128 v[206:209], v180 offset:34816
	ds_read_b128 v[210:213], v180 offset:35840
	ds_read_b128 v[214:217], v180 offset:36864
	ds_read_b128 v[218:221], v180 offset:37888
	ds_read_b128 v[222:225], v180 offset:38912
	ds_read_b128 v[226:229], v180 offset:39936
	global_load_lds_dwordx4 v[236:237], off
	v_lshl_add_u64 v[236:237], s[36:37], 0, v[132:133]
	s_mov_b32 m0, s44
	s_nop 0
	global_load_lds_dwordx4 v[236:237], off
	s_waitcnt vmcnt(8)
	s_waitcnt lgkmcnt(0)
	s_barrier
	s_setprio 1
	v_mfma_i32_16x16x64_i8 v[126:129], v[146:149], v[198:201], v[126:129]
	v_mfma_i32_16x16x64_i8 v[118:121], v[154:157], v[198:201], v[118:121]
	v_mfma_i32_16x16x64_i8 v[110:113], v[146:149], v[206:209], v[110:113]
	v_mfma_i32_16x16x64_i8 v[102:105], v[154:157], v[206:209], v[102:105]
	v_mfma_i32_16x16x64_i8 v[94:97], v[146:149], v[214:217], v[94:97]
	v_mfma_i32_16x16x64_i8 v[86:89], v[154:157], v[214:217], v[86:89]
	v_mfma_i32_16x16x64_i8 v[78:81], v[146:149], v[222:225], v[78:81]
	v_mfma_i32_16x16x64_i8 v[70:73], v[154:157], v[222:225], v[70:73]
	v_mfma_i32_16x16x64_i8 v[126:129], v[150:153], v[202:205], v[126:129]
	v_mfma_i32_16x16x64_i8 v[118:121], v[158:161], v[202:205], v[118:121]
	v_mfma_i32_16x16x64_i8 v[110:113], v[150:153], v[210:213], v[110:113]
	v_mfma_i32_16x16x64_i8 v[102:105], v[158:161], v[210:213], v[102:105]
	v_mfma_i32_16x16x64_i8 v[94:97], v[150:153], v[218:221], v[94:97]
	v_mfma_i32_16x16x64_i8 v[86:89], v[158:161], v[218:221], v[86:89]
	v_mfma_i32_16x16x64_i8 v[78:81], v[150:153], v[226:229], v[78:81]
	v_mfma_i32_16x16x64_i8 v[70:73], v[158:161], v[226:229], v[70:73]
	v_mfma_i32_16x16x64_i8 v[122:125], v[182:185], v[198:201], v[122:125]
	v_mfma_i32_16x16x64_i8 v[114:117], v[190:193], v[198:201], v[114:117]
	v_mfma_i32_16x16x64_i8 v[106:109], v[182:185], v[206:209], v[106:109]
	v_mfma_i32_16x16x64_i8 v[98:101], v[190:193], v[206:209], v[98:101]
	v_mfma_i32_16x16x64_i8 v[90:93], v[182:185], v[214:217], v[90:93]
	v_mfma_i32_16x16x64_i8 v[82:85], v[190:193], v[214:217], v[82:85]
	v_mfma_i32_16x16x64_i8 v[74:77], v[182:185], v[222:225], v[74:77]
	v_mfma_i32_16x16x64_i8 v[66:69], v[190:193], v[222:225], v[66:69]
	v_mfma_i32_16x16x64_i8 v[122:125], v[186:189], v[202:205], v[122:125]
	v_mfma_i32_16x16x64_i8 v[114:117], v[194:197], v[202:205], v[114:117]
	v_mfma_i32_16x16x64_i8 v[106:109], v[186:189], v[210:213], v[106:109]
	v_mfma_i32_16x16x64_i8 v[98:101], v[194:197], v[210:213], v[98:101]
	v_mfma_i32_16x16x64_i8 v[90:93], v[186:189], v[218:221], v[90:93]
	v_mfma_i32_16x16x64_i8 v[82:85], v[194:197], v[218:221], v[82:85]
	v_mfma_i32_16x16x64_i8 v[74:77], v[186:189], v[226:229], v[74:77]
	v_mfma_i32_16x16x64_i8 v[66:69], v[194:197], v[226:229], v[66:69]
	s_setprio 0
	s_barrier
	s_add_i32 s36, s73, s40
	v_lshl_add_u64 v[162:163], v[162:163], 0, s[10:11]
	s_mov_b32 m0, s36
	ds_read_b128 v[198:201], v180 offset:49152
	ds_read_b128 v[202:205], v180 offset:50176
	ds_read_b128 v[206:209], v180 offset:51200
	ds_read_b128 v[210:213], v180 offset:52224
	ds_read_b128 v[214:217], v180 offset:53248
	ds_read_b128 v[218:221], v180 offset:54272
	ds_read_b128 v[222:225], v180 offset:55296
	ds_read_b128 v[226:229], v180 offset:56320
	global_load_lds_dwordx4 v[162:163], off
	s_add_i32 m0, s36, 0x2000
	s_add_u32 s34, s34, 0x40080
	v_lshl_add_u64 v[162:163], v[230:231], 0, s[10:11]
	s_addc_u32 s35, s35, 0
	s_add_i32 s36, s50, s40
	global_load_lds_dwordx4 v[162:163], off
	v_lshl_add_u64 v[162:163], s[34:35], 0, v[134:135]
	s_mov_b32 m0, s36
	s_nop 0
	global_load_lds_dwordx4 v[162:163], off
	v_lshl_add_u64 v[162:163], s[34:35], 0, v[130:131]
	s_add_i32 m0, s36, 0x2000
	s_nop 0
	global_load_lds_dwordx4 v[162:163], off
	v_lshl_add_u64 v[162:163], v[232:233], 0, s[10:11]
	s_mov_b32 m0, s45
	s_nop 0
	global_load_lds_dwordx4 v[162:163], off
	v_lshl_add_u64 v[162:163], v[234:235], 0, s[10:11]
	s_mov_b32 m0, s46
	s_nop 0
	global_load_lds_dwordx4 v[162:163], off
	s_waitcnt vmcnt(8)
	s_waitcnt lgkmcnt(0)
	s_barrier
	s_setprio 1
	v_mfma_i32_16x16x64_i8 v[62:65], v[146:149], v[198:201], v[62:65]
	v_mfma_i32_16x16x64_i8 v[54:57], v[154:157], v[198:201], v[54:57]
	v_mfma_i32_16x16x64_i8 v[46:49], v[146:149], v[206:209], v[46:49]
	v_mfma_i32_16x16x64_i8 v[38:41], v[154:157], v[206:209], v[38:41]
	v_mfma_i32_16x16x64_i8 v[30:33], v[146:149], v[214:217], v[30:33]
	v_mfma_i32_16x16x64_i8 v[22:25], v[154:157], v[214:217], v[22:25]
	v_mfma_i32_16x16x64_i8 v[14:17], v[146:149], v[222:225], v[14:17]
	v_mfma_i32_16x16x64_i8 v[6:9], v[154:157], v[222:225], v[6:9]
	v_mfma_i32_16x16x64_i8 v[62:65], v[150:153], v[202:205], v[62:65]
	v_mfma_i32_16x16x64_i8 v[54:57], v[158:161], v[202:205], v[54:57]
	v_mfma_i32_16x16x64_i8 v[46:49], v[150:153], v[210:213], v[46:49]
	v_mfma_i32_16x16x64_i8 v[38:41], v[158:161], v[210:213], v[38:41]
	v_mfma_i32_16x16x64_i8 v[30:33], v[150:153], v[218:221], v[30:33]
	v_mfma_i32_16x16x64_i8 v[22:25], v[158:161], v[218:221], v[22:25]
	v_mfma_i32_16x16x64_i8 v[14:17], v[150:153], v[226:229], v[14:17]
	v_mfma_i32_16x16x64_i8 v[6:9], v[158:161], v[226:229], v[6:9]
	v_mfma_i32_16x16x64_i8 v[58:61], v[182:185], v[198:201], v[58:61]
	v_mfma_i32_16x16x64_i8 v[50:53], v[190:193], v[198:201], v[50:53]
	v_mfma_i32_16x16x64_i8 v[42:45], v[182:185], v[206:209], v[42:45]
	v_mfma_i32_16x16x64_i8 v[34:37], v[190:193], v[206:209], v[34:37]
	v_mfma_i32_16x16x64_i8 v[26:29], v[182:185], v[214:217], v[26:29]
	v_mfma_i32_16x16x64_i8 v[18:21], v[190:193], v[214:217], v[18:21]
	v_mfma_i32_16x16x64_i8 v[10:13], v[182:185], v[222:225], v[10:13]
	v_mfma_i32_16x16x64_i8 v[2:5], v[190:193], v[222:225], v[2:5]
	v_mfma_i32_16x16x64_i8 v[58:61], v[186:189], v[202:205], v[58:61]
	v_mfma_i32_16x16x64_i8 v[50:53], v[194:197], v[202:205], v[50:53]
	v_mfma_i32_16x16x64_i8 v[42:45], v[186:189], v[210:213], v[42:45]
	v_mfma_i32_16x16x64_i8 v[34:37], v[194:197], v[210:213], v[34:37]
	v_mfma_i32_16x16x64_i8 v[26:29], v[186:189], v[218:221], v[26:29]
	v_mfma_i32_16x16x64_i8 v[18:21], v[194:197], v[218:221], v[18:21]
	v_mfma_i32_16x16x64_i8 v[10:13], v[186:189], v[226:229], v[10:13]
	v_mfma_i32_16x16x64_i8 v[2:5], v[194:197], v[226:229], v[2:5]
	s_setprio 0
	s_barrier
	s_add_i32 s72, s72, 2
	s_add_u32 s30, s30, 0x100
	s_addc_u32 s31, s31, 0
	s_add_u32 s70, s70, 0x100
	s_addc_u32 s71, s71, 0
	s_cmp_gt_u32 s72, 13
	s_cbranch_scc0 .LBB0_1595
	s_and_b64 vcc, exec, s[14:15]
	s_cbranch_vccz .LBB0_1598
	s_barrier

.LBB0_1704:
	ds_read_b128 v[154:157], v149
	ds_read_b128 v[158:161], v149 offset:1024
	ds_read_b128 v[162:165], v149 offset:2048
	ds_read_b128 v[170:173], v149 offset:3072
	ds_read_b128 v[174:177], v150
	ds_read_b128 v[178:181], v150 offset:1024
	ds_read_b128 v[182:185], v150 offset:2048
	ds_read_b128 v[186:189], v150 offset:3072
	s_add_u32 s22, s20, 0xffea0080
	s_addc_u32 s23, s21, -1
	s_cmpk_eq_i32 s48, 0x54
	s_cselect_b32 s25, s7, s23
	s_cselect_b32 s24, s6, s22
	s_cselect_b32 s23, s17, s47
	s_cselect_b32 s22, s16, s46
	v_lshl_add_u64 v[146:147], s[20:21], 0, v[138:139]
	s_add_i32 m0, s28, 0xc000
	ds_read_b128 v[190:193], v151
	ds_read_b128 v[194:197], v151 offset:1024
	ds_read_b128 v[198:201], v151 offset:2048
	ds_read_b128 v[202:205], v151 offset:3072
	ds_read_b128 v[206:209], v151 offset:4096
	ds_read_b128 v[210:213], v151 offset:5120
	ds_read_b128 v[214:217], v151 offset:6144
	ds_read_b128 v[218:221], v151 offset:7168
	global_load_lds_dwordx4 v[146:147], off
	v_lshl_add_u64 v[146:147], s[20:21], 0, v[140:141]
	s_add_i32 m0, s28, 0xe000
	s_nop 0
	global_load_lds_dwordx4 v[146:147], off
	s_waitcnt vmcnt(8)
	s_waitcnt lgkmcnt(0)
	s_barrier
	s_setprio 1
	v_mfma_f32_16x16x32_bf16 v[126:129], v[154:157], v[190:193], v[126:129]
	v_mfma_f32_16x16x32_bf16 v[122:125], v[162:165], v[190:193], v[122:125]
	v_mfma_f32_16x16x32_bf16 v[118:121], v[154:157], v[198:201], v[118:121]
	v_mfma_f32_16x16x32_bf16 v[110:113], v[162:165], v[198:201], v[110:113]
	v_mfma_f32_16x16x32_bf16 v[102:105], v[154:157], v[206:209], v[102:105]
	v_mfma_f32_16x16x32_bf16 v[94:97], v[162:165], v[206:209], v[94:97]
	v_mfma_f32_16x16x32_bf16 v[86:89], v[154:157], v[214:217], v[86:89]
	v_mfma_f32_16x16x32_bf16 v[78:81], v[162:165], v[214:217], v[78:81]
	v_mfma_f32_16x16x32_bf16 v[126:129], v[158:161], v[194:197], v[126:129]
	v_mfma_f32_16x16x32_bf16 v[122:125], v[170:173], v[194:197], v[122:125]
	v_mfma_f32_16x16x32_bf16 v[118:121], v[158:161], v[202:205], v[118:121]
	v_mfma_f32_16x16x32_bf16 v[110:113], v[170:173], v[202:205], v[110:113]
	v_mfma_f32_16x16x32_bf16 v[102:105], v[158:161], v[210:213], v[102:105]
	v_mfma_f32_16x16x32_bf16 v[94:97], v[170:173], v[210:213], v[94:97]
	v_mfma_f32_16x16x32_bf16 v[86:89], v[158:161], v[218:221], v[86:89]
	v_mfma_f32_16x16x32_bf16 v[78:81], v[170:173], v[218:221], v[78:81]
	v_mfma_f32_16x16x32_bf16 v[114:117], v[174:177], v[190:193], v[114:117]
	v_mfma_f32_16x16x32_bf16 v[106:109], v[182:185], v[190:193], v[106:109]
	v_mfma_f32_16x16x32_bf16 v[98:101], v[174:177], v[198:201], v[98:101]
	v_mfma_f32_16x16x32_bf16 v[90:93], v[182:185], v[198:201], v[90:93]
	v_mfma_f32_16x16x32_bf16 v[82:85], v[174:177], v[206:209], v[82:85]
	v_mfma_f32_16x16x32_bf16 v[74:77], v[182:185], v[206:209], v[74:77]
	v_mfma_f32_16x16x32_bf16 v[70:73], v[174:177], v[214:217], v[70:73]
	v_mfma_f32_16x16x32_bf16 v[66:69], v[182:185], v[214:217], v[66:69]
	v_mfma_f32_16x16x32_bf16 v[114:117], v[178:181], v[194:197], v[114:117]
	v_mfma_f32_16x16x32_bf16 v[106:109], v[186:189], v[194:197], v[106:109]
	v_mfma_f32_16x16x32_bf16 v[98:101], v[178:181], v[202:205], v[98:101]
	v_mfma_f32_16x16x32_bf16 v[90:93], v[186:189], v[202:205], v[90:93]
	v_mfma_f32_16x16x32_bf16 v[82:85], v[178:181], v[210:213], v[82:85]
	v_mfma_f32_16x16x32_bf16 v[74:77], v[186:189], v[210:213], v[74:77]
	v_mfma_f32_16x16x32_bf16 v[70:73], v[178:181], v[218:221], v[70:73]
	v_mfma_f32_16x16x32_bf16 v[66:69], v[186:189], v[218:221], v[66:69]
	s_setprio 0
	s_barrier
	s_add_i32 s49, s38, s27
	v_lshl_add_u64 v[146:147], s[22:23], 0, v[132:133]
	s_mov_b32 m0, s49
	ds_read_b128 v[190:193], v151 offset:16384
	ds_read_b128 v[194:197], v151 offset:17408
	ds_read_b128 v[198:201], v151 offset:18432
	ds_read_b128 v[202:205], v151 offset:19456
	ds_read_b128 v[206:209], v151 offset:20480
	ds_read_b128 v[210:213], v151 offset:21504
	ds_read_b128 v[214:217], v151 offset:22528
	ds_read_b128 v[218:221], v151 offset:23552
	global_load_lds_dwordx4 v[146:147], off
	s_add_i32 m0, s49, 0x2000
	s_add_u32 s50, s22, 0x160000
	v_lshl_add_u64 v[222:223], s[22:23], 0, v[136:137]
	s_addc_u32 s51, s23, 0
	s_add_i32 s49, s39, s27
	global_load_lds_dwordx4 v[222:223], off
	v_lshl_add_u64 v[224:225], s[50:51], 0, v[132:133]
	s_mov_b32 m0, s49
	v_lshl_add_u64 v[226:227], s[24:25], 0, v[134:135]
	global_load_lds_dwordx4 v[224:225], off
	v_lshl_add_u64 v[224:225], s[50:51], 0, v[136:137]
	s_add_i32 m0, s49, 0x2000
	s_nop 0
	global_load_lds_dwordx4 v[224:225], off
	v_lshl_add_u64 v[224:225], s[24:25], 0, v[130:131]
	s_mov_b32 m0, s28
	s_nop 0
	global_load_lds_dwordx4 v[224:225], off
	s_mov_b32 m0, s29
	s_nop 0
	global_load_lds_dwordx4 v[226:227], off
	s_waitcnt vmcnt(8)
	s_waitcnt lgkmcnt(0)
	s_barrier
	s_setprio 1
	v_mfma_f32_16x16x32_bf16 v[62:65], v[154:157], v[190:193], v[62:65]
	v_mfma_f32_16x16x32_bf16 v[58:61], v[162:165], v[190:193], v[58:61]
	v_mfma_f32_16x16x32_bf16 v[54:57], v[154:157], v[198:201], v[54:57]
	v_mfma_f32_16x16x32_bf16 v[46:49], v[162:165], v[198:201], v[46:49]
	v_mfma_f32_16x16x32_bf16 v[38:41], v[154:157], v[206:209], v[38:41]
	v_mfma_f32_16x16x32_bf16 v[30:33], v[162:165], v[206:209], v[30:33]
	v_mfma_f32_16x16x32_bf16 v[22:25], v[154:157], v[214:217], v[22:25]
	v_mfma_f32_16x16x32_bf16 v[14:17], v[162:165], v[214:217], v[14:17]
	v_mfma_f32_16x16x32_bf16 v[62:65], v[158:161], v[194:197], v[62:65]
	v_mfma_f32_16x16x32_bf16 v[58:61], v[170:173], v[194:197], v[58:61]
	v_mfma_f32_16x16x32_bf16 v[54:57], v[158:161], v[202:205], v[54:57]
	v_mfma_f32_16x16x32_bf16 v[46:49], v[170:173], v[202:205], v[46:49]
	v_mfma_f32_16x16x32_bf16 v[38:41], v[158:161], v[210:213], v[38:41]
	v_mfma_f32_16x16x32_bf16 v[30:33], v[170:173], v[210:213], v[30:33]
	v_mfma_f32_16x16x32_bf16 v[22:25], v[158:161], v[218:221], v[22:25]
	v_mfma_f32_16x16x32_bf16 v[14:17], v[170:173], v[218:221], v[14:17]
	v_mfma_f32_16x16x32_bf16 v[50:53], v[174:177], v[190:193], v[50:53]
	v_mfma_f32_16x16x32_bf16 v[42:45], v[182:185], v[190:193], v[42:45]
	v_mfma_f32_16x16x32_bf16 v[34:37], v[174:177], v[198:201], v[34:37]
	v_mfma_f32_16x16x32_bf16 v[26:29], v[182:185], v[198:201], v[26:29]
	v_mfma_f32_16x16x32_bf16 v[18:21], v[174:177], v[206:209], v[18:21]
	v_mfma_f32_16x16x32_bf16 v[10:13], v[182:185], v[206:209], v[10:13]
	v_mfma_f32_16x16x32_bf16 v[6:9], v[174:177], v[214:217], v[6:9]
	v_mfma_f32_16x16x32_bf16 v[2:5], v[182:185], v[214:217], v[2:5]
	v_mfma_f32_16x16x32_bf16 v[50:53], v[178:181], v[194:197], v[50:53]
	v_mfma_f32_16x16x32_bf16 v[42:45], v[186:189], v[194:197], v[42:45]
	v_mfma_f32_16x16x32_bf16 v[34:37], v[178:181], v[202:205], v[34:37]
	v_mfma_f32_16x16x32_bf16 v[26:29], v[186:189], v[202:205], v[26:29]
	v_mfma_f32_16x16x32_bf16 v[18:21], v[178:181], v[210:213], v[18:21]
	v_mfma_f32_16x16x32_bf16 v[10:13], v[186:189], v[210:213], v[10:13]
	v_mfma_f32_16x16x32_bf16 v[6:9], v[178:181], v[218:221], v[6:9]
	v_mfma_f32_16x16x32_bf16 v[2:5], v[186:189], v[218:221], v[2:5]
	s_setprio 0
	s_barrier
	ds_read_b128 v[154:157], v152
	ds_read_b128 v[158:161], v152 offset:1024
	ds_read_b128 v[162:165], v152 offset:2048
	ds_read_b128 v[170:173], v152 offset:3072
	ds_read_b128 v[174:177], v153
	ds_read_b128 v[178:181], v153 offset:1024
	ds_read_b128 v[182:185], v153 offset:2048
	ds_read_b128 v[186:189], v153 offset:3072
	s_add_u32 s24, s24, 0x160000
	s_addc_u32 s25, s25, 0
	s_mov_b32 m0, s30
	v_lshl_add_u64 v[228:229], s[24:25], 0, v[130:131]
	ds_read_b128 v[190:193], v151 offset:32768
	ds_read_b128 v[194:197], v151 offset:33792
	ds_read_b128 v[198:201], v151 offset:34816
	ds_read_b128 v[202:205], v151 offset:35840
	ds_read_b128 v[206:209], v151 offset:36864
	ds_read_b128 v[210:213], v151 offset:37888
	ds_read_b128 v[214:217], v151 offset:38912
	ds_read_b128 v[218:221], v151 offset:39936
	global_load_lds_dwordx4 v[228:229], off
	v_lshl_add_u64 v[228:229], s[24:25], 0, v[134:135]
	s_mov_b32 m0, s31
	s_nop 0
	global_load_lds_dwordx4 v[228:229], off
	s_waitcnt vmcnt(8)
	s_waitcnt lgkmcnt(0)
	s_barrier
	s_setprio 1
	v_mfma_f32_16x16x32_bf16 v[126:129], v[154:157], v[190:193], v[126:129]
	v_mfma_f32_16x16x32_bf16 v[122:125], v[162:165], v[190:193], v[122:125]
	v_mfma_f32_16x16x32_bf16 v[118:121], v[154:157], v[198:201], v[118:121]
	v_mfma_f32_16x16x32_bf16 v[110:113], v[162:165], v[198:201], v[110:113]
	v_mfma_f32_16x16x32_bf16 v[102:105], v[154:157], v[206:209], v[102:105]
	v_mfma_f32_16x16x32_bf16 v[94:97], v[162:165], v[206:209], v[94:97]
	v_mfma_f32_16x16x32_bf16 v[86:89], v[154:157], v[214:217], v[86:89]
	v_mfma_f32_16x16x32_bf16 v[78:81], v[162:165], v[214:217], v[78:81]
	v_mfma_f32_16x16x32_bf16 v[126:129], v[158:161], v[194:197], v[126:129]
	v_mfma_f32_16x16x32_bf16 v[122:125], v[170:173], v[194:197], v[122:125]
	v_mfma_f32_16x16x32_bf16 v[118:121], v[158:161], v[202:205], v[118:121]
	v_mfma_f32_16x16x32_bf16 v[110:113], v[170:173], v[202:205], v[110:113]
	v_mfma_f32_16x16x32_bf16 v[102:105], v[158:161], v[210:213], v[102:105]
	v_mfma_f32_16x16x32_bf16 v[94:97], v[170:173], v[210:213], v[94:97]
	v_mfma_f32_16x16x32_bf16 v[86:89], v[158:161], v[218:221], v[86:89]
	v_mfma_f32_16x16x32_bf16 v[78:81], v[170:173], v[218:221], v[78:81]
	v_mfma_f32_16x16x32_bf16 v[114:117], v[174:177], v[190:193], v[114:117]
	v_mfma_f32_16x16x32_bf16 v[106:109], v[182:185], v[190:193], v[106:109]
	v_mfma_f32_16x16x32_bf16 v[98:101], v[174:177], v[198:201], v[98:101]
	v_mfma_f32_16x16x32_bf16 v[90:93], v[182:185], v[198:201], v[90:93]
	v_mfma_f32_16x16x32_bf16 v[82:85], v[174:177], v[206:209], v[82:85]
	v_mfma_f32_16x16x32_bf16 v[74:77], v[182:185], v[206:209], v[74:77]
	v_mfma_f32_16x16x32_bf16 v[70:73], v[174:177], v[214:217], v[70:73]
	v_mfma_f32_16x16x32_bf16 v[66:69], v[182:185], v[214:217], v[66:69]
	v_mfma_f32_16x16x32_bf16 v[114:117], v[178:181], v[194:197], v[114:117]
	v_mfma_f32_16x16x32_bf16 v[106:109], v[186:189], v[194:197], v[106:109]
	v_mfma_f32_16x16x32_bf16 v[98:101], v[178:181], v[202:205], v[98:101]
	v_mfma_f32_16x16x32_bf16 v[90:93], v[186:189], v[202:205], v[90:93]
	v_mfma_f32_16x16x32_bf16 v[82:85], v[178:181], v[210:213], v[82:85]
	v_mfma_f32_16x16x32_bf16 v[74:77], v[186:189], v[210:213], v[74:77]
	v_mfma_f32_16x16x32_bf16 v[70:73], v[178:181], v[218:221], v[70:73]
	v_mfma_f32_16x16x32_bf16 v[66:69], v[186:189], v[218:221], v[66:69]
	s_setprio 0
	s_barrier
	s_add_i32 s24, s40, s27
	v_lshl_add_u64 v[146:147], v[146:147], 0, s[8:9]
	s_mov_b32 m0, s24
	ds_read_b128 v[190:193], v151 offset:49152
	ds_read_b128 v[194:197], v151 offset:50176
	ds_read_b128 v[198:201], v151 offset:51200
	ds_read_b128 v[202:205], v151 offset:52224
	ds_read_b128 v[206:209], v151 offset:53248
	ds_read_b128 v[210:213], v151 offset:54272
	ds_read_b128 v[214:217], v151 offset:55296
	ds_read_b128 v[218:221], v151 offset:56320
	global_load_lds_dwordx4 v[146:147], off
	s_add_i32 m0, s24, 0x2000
	s_add_u32 s22, s22, 0x160080
	v_lshl_add_u64 v[146:147], v[222:223], 0, s[8:9]
	s_addc_u32 s23, s23, 0
	s_add_i32 s24, s41, s27
	global_load_lds_dwordx4 v[146:147], off
	v_lshl_add_u64 v[146:147], s[22:23], 0, v[132:133]
	s_mov_b32 m0, s24
	s_nop 0
	global_load_lds_dwordx4 v[146:147], off
	v_lshl_add_u64 v[146:147], s[22:23], 0, v[136:137]
	s_add_i32 m0, s24, 0x2000
	s_nop 0
	global_load_lds_dwordx4 v[146:147], off
	v_lshl_add_u64 v[146:147], v[224:225], 0, s[8:9]
	s_mov_b32 m0, s34
	s_nop 0
	global_load_lds_dwordx4 v[146:147], off
	v_lshl_add_u64 v[146:147], v[226:227], 0, s[8:9]
	s_mov_b32 m0, s35
	s_nop 0
	global_load_lds_dwordx4 v[146:147], off
	s_waitcnt vmcnt(8)
	s_waitcnt lgkmcnt(0)
	s_barrier
	s_setprio 1
	v_mfma_f32_16x16x32_bf16 v[62:65], v[154:157], v[190:193], v[62:65]
	v_mfma_f32_16x16x32_bf16 v[58:61], v[162:165], v[190:193], v[58:61]
	v_mfma_f32_16x16x32_bf16 v[54:57], v[154:157], v[198:201], v[54:57]
	v_mfma_f32_16x16x32_bf16 v[46:49], v[162:165], v[198:201], v[46:49]
	v_mfma_f32_16x16x32_bf16 v[38:41], v[154:157], v[206:209], v[38:41]
	v_mfma_f32_16x16x32_bf16 v[30:33], v[162:165], v[206:209], v[30:33]
	v_mfma_f32_16x16x32_bf16 v[22:25], v[154:157], v[214:217], v[22:25]
	v_mfma_f32_16x16x32_bf16 v[14:17], v[162:165], v[214:217], v[14:17]
	v_mfma_f32_16x16x32_bf16 v[62:65], v[158:161], v[194:197], v[62:65]
	v_mfma_f32_16x16x32_bf16 v[58:61], v[170:173], v[194:197], v[58:61]
	v_mfma_f32_16x16x32_bf16 v[54:57], v[158:161], v[202:205], v[54:57]
	v_mfma_f32_16x16x32_bf16 v[46:49], v[170:173], v[202:205], v[46:49]
	v_mfma_f32_16x16x32_bf16 v[38:41], v[158:161], v[210:213], v[38:41]
	v_mfma_f32_16x16x32_bf16 v[30:33], v[170:173], v[210:213], v[30:33]
	v_mfma_f32_16x16x32_bf16 v[22:25], v[158:161], v[218:221], v[22:25]
	v_mfma_f32_16x16x32_bf16 v[14:17], v[170:173], v[218:221], v[14:17]
	v_mfma_f32_16x16x32_bf16 v[50:53], v[174:177], v[190:193], v[50:53]
	v_mfma_f32_16x16x32_bf16 v[42:45], v[182:185], v[190:193], v[42:45]
	v_mfma_f32_16x16x32_bf16 v[34:37], v[174:177], v[198:201], v[34:37]
	v_mfma_f32_16x16x32_bf16 v[26:29], v[182:185], v[198:201], v[26:29]
	v_mfma_f32_16x16x32_bf16 v[18:21], v[174:177], v[206:209], v[18:21]
	v_mfma_f32_16x16x32_bf16 v[10:13], v[182:185], v[206:209], v[10:13]
	v_mfma_f32_16x16x32_bf16 v[6:9], v[174:177], v[214:217], v[6:9]
	v_mfma_f32_16x16x32_bf16 v[2:5], v[182:185], v[214:217], v[2:5]
	v_mfma_f32_16x16x32_bf16 v[50:53], v[178:181], v[194:197], v[50:53]
	v_mfma_f32_16x16x32_bf16 v[42:45], v[186:189], v[194:197], v[42:45]
	v_mfma_f32_16x16x32_bf16 v[34:37], v[178:181], v[202:205], v[34:37]
	v_mfma_f32_16x16x32_bf16 v[26:29], v[186:189], v[202:205], v[26:29]
	v_mfma_f32_16x16x32_bf16 v[18:21], v[178:181], v[210:213], v[18:21]
	v_mfma_f32_16x16x32_bf16 v[10:13], v[186:189], v[210:213], v[10:13]
	v_mfma_f32_16x16x32_bf16 v[6:9], v[178:181], v[218:221], v[6:9]
	v_mfma_f32_16x16x32_bf16 v[2:5], v[186:189], v[218:221], v[2:5]
	s_setprio 0
	s_barrier
	s_add_i32 s48, s48, 2
	s_add_u32 s20, s20, 0x100
	s_addc_u32 s21, s21, 0
	s_add_u32 s46, s46, 0x100
	s_addc_u32 s47, s47, 0
	s_cmpk_gt_u32 s48, 0x55
	s_cbranch_scc0 .LBB0_1704
	s_and_b64 vcc, exec, s[14:15]
	s_cbranch_vccz .LBB0_1707
	s_barrier

.LBB0_2308:
	ds_read_b128 v[74:77], v198
	ds_read_b128 v[78:81], v198 offset:1024
	ds_read_b128 v[86:89], v198 offset:2048
	ds_read_b128 v[98:101], v198 offset:3072
	ds_read_b128 v[146:149], v199
	ds_read_b128 v[150:153], v199 offset:1024
	ds_read_b128 v[154:157], v199 offset:2048
	ds_read_b128 v[158:161], v199 offset:3072
	s_add_u32 s28, s26, 0xfff80080
	s_addc_u32 s29, s27, -1
	s_cmp_eq_u32 s52, 28
	s_cselect_b32 s31, s17, s29
	s_cselect_b32 s30, s48, s28
	s_cselect_b32 s29, s15, s51
	s_cselect_b32 s28, s49, s50
	v_lshl_add_u64 v[220:221], s[26:27], 0, v[178:179]
	s_add_i32 m0, s25, 0xc000
	ds_read_b128 v[162:165], v200
	ds_read_b128 v[186:189], v200 offset:1024
	ds_read_b128 v[190:193], v200 offset:2048
	ds_read_b128 v[194:197], v200 offset:3072
	ds_read_b128 v[204:207], v200 offset:4096
	ds_read_b128 v[208:211], v200 offset:5120
	ds_read_b128 v[212:215], v200 offset:6144
	ds_read_b128 v[216:219], v200 offset:7168
	global_load_lds_dwordx4 v[220:221], off
	v_lshl_add_u64 v[220:221], s[26:27], 0, v[180:181]
	s_add_i32 m0, s25, 0xe000
	s_nop 0
	global_load_lds_dwordx4 v[220:221], off
	s_waitcnt vmcnt(8)
	s_waitcnt lgkmcnt(0)
	s_barrier
	s_setprio 1
	v_mfma_f32_16x16x32_bf16 v[142:145], v[74:77], v[162:165], v[142:145]
	v_mfma_f32_16x16x32_bf16 v[138:141], v[86:89], v[162:165], v[138:141]
	v_mfma_f32_16x16x32_bf16 v[126:129], v[74:77], v[190:193], v[126:129]
	v_mfma_f32_16x16x32_bf16 v[122:125], v[86:89], v[190:193], v[122:125]
	v_mfma_f32_16x16x32_bf16 v[110:113], v[74:77], v[204:207], v[110:113]
	v_mfma_f32_16x16x32_bf16 v[106:109], v[86:89], v[204:207], v[106:109]
	v_mfma_f32_16x16x32_bf16 v[90:93], v[74:77], v[212:215], v[90:93]
	v_mfma_f32_16x16x32_bf16 v[82:85], v[86:89], v[212:215], v[82:85]
	v_mfma_f32_16x16x32_bf16 v[142:145], v[78:81], v[186:189], v[142:145]
	v_mfma_f32_16x16x32_bf16 v[138:141], v[98:101], v[186:189], v[138:141]
	v_mfma_f32_16x16x32_bf16 v[126:129], v[78:81], v[194:197], v[126:129]
	v_mfma_f32_16x16x32_bf16 v[122:125], v[98:101], v[194:197], v[122:125]
	v_mfma_f32_16x16x32_bf16 v[110:113], v[78:81], v[208:211], v[110:113]
	v_mfma_f32_16x16x32_bf16 v[106:109], v[98:101], v[208:211], v[106:109]
	v_mfma_f32_16x16x32_bf16 v[90:93], v[78:81], v[216:219], v[90:93]
	v_mfma_f32_16x16x32_bf16 v[82:85], v[98:101], v[216:219], v[82:85]
	v_mfma_f32_16x16x32_bf16 v[134:137], v[146:149], v[162:165], v[134:137]
	v_mfma_f32_16x16x32_bf16 v[130:133], v[154:157], v[162:165], v[130:133]
	v_mfma_f32_16x16x32_bf16 v[118:121], v[146:149], v[190:193], v[118:121]
	v_mfma_f32_16x16x32_bf16 v[114:117], v[154:157], v[190:193], v[114:117]
	v_mfma_f32_16x16x32_bf16 v[102:105], v[146:149], v[204:207], v[102:105]
	v_mfma_f32_16x16x32_bf16 v[94:97], v[154:157], v[204:207], v[94:97]
	v_mfma_f32_16x16x32_bf16 v[70:73], v[146:149], v[212:215], v[70:73]
	v_mfma_f32_16x16x32_bf16 v[66:69], v[154:157], v[212:215], v[66:69]
	v_mfma_f32_16x16x32_bf16 v[134:137], v[150:153], v[186:189], v[134:137]
	v_mfma_f32_16x16x32_bf16 v[130:133], v[158:161], v[186:189], v[130:133]
	v_mfma_f32_16x16x32_bf16 v[118:121], v[150:153], v[194:197], v[118:121]
	v_mfma_f32_16x16x32_bf16 v[114:117], v[158:161], v[194:197], v[114:117]
	v_mfma_f32_16x16x32_bf16 v[102:105], v[150:153], v[208:211], v[102:105]
	v_mfma_f32_16x16x32_bf16 v[94:97], v[158:161], v[208:211], v[94:97]
	v_mfma_f32_16x16x32_bf16 v[70:73], v[150:153], v[216:219], v[70:73]
	v_mfma_f32_16x16x32_bf16 v[66:69], v[158:161], v[216:219], v[66:69]
	s_setprio 0
	s_barrier
	s_add_i32 s53, s43, s35
	v_lshl_add_u64 v[220:221], s[28:29], 0, v[172:173]
	s_mov_b32 m0, s53
	ds_read_b128 v[162:165], v200 offset:16384
	ds_read_b128 v[186:189], v200 offset:17408
	ds_read_b128 v[190:193], v200 offset:18432
	ds_read_b128 v[194:197], v200 offset:19456
	ds_read_b128 v[204:207], v200 offset:20480
	ds_read_b128 v[208:211], v200 offset:21504
	ds_read_b128 v[212:215], v200 offset:22528
	ds_read_b128 v[216:219], v200 offset:23552
	global_load_lds_dwordx4 v[220:221], off
	s_add_i32 m0, s53, 0x2000
	s_add_u32 s54, s28, 0x80000
	v_lshl_add_u64 v[222:223], s[28:29], 0, v[176:177]
	s_addc_u32 s55, s29, 0
	s_add_i32 s53, s44, s35
	global_load_lds_dwordx4 v[222:223], off
	v_lshl_add_u64 v[224:225], s[54:55], 0, v[172:173]
	s_mov_b32 m0, s53
	v_lshl_add_u64 v[226:227], s[30:31], 0, v[174:175]
	global_load_lds_dwordx4 v[224:225], off
	v_lshl_add_u64 v[224:225], s[54:55], 0, v[176:177]
	s_add_i32 m0, s53, 0x2000
	s_nop 0
	global_load_lds_dwordx4 v[224:225], off
	v_lshl_add_u64 v[224:225], s[30:31], 0, v[170:171]
	s_mov_b32 m0, s25
	s_nop 0
	global_load_lds_dwordx4 v[224:225], off
	s_mov_b32 m0, s36
	s_nop 0
	global_load_lds_dwordx4 v[226:227], off
	s_waitcnt vmcnt(8)
	s_waitcnt lgkmcnt(0)
	s_barrier
	s_setprio 1
	v_mfma_f32_16x16x32_bf16 v[62:65], v[74:77], v[162:165], v[62:65]
	v_mfma_f32_16x16x32_bf16 v[58:61], v[86:89], v[162:165], v[58:61]
	v_mfma_f32_16x16x32_bf16 v[46:49], v[74:77], v[190:193], v[46:49]
	v_mfma_f32_16x16x32_bf16 v[42:45], v[86:89], v[190:193], v[42:45]
	v_mfma_f32_16x16x32_bf16 v[30:33], v[74:77], v[204:207], v[30:33]
	v_mfma_f32_16x16x32_bf16 v[26:29], v[86:89], v[204:207], v[26:29]
	v_mfma_f32_16x16x32_bf16 v[14:17], v[74:77], v[212:215], v[14:17]
	v_mfma_f32_16x16x32_bf16 v[10:13], v[86:89], v[212:215], v[10:13]
	v_mfma_f32_16x16x32_bf16 v[62:65], v[78:81], v[186:189], v[62:65]
	v_mfma_f32_16x16x32_bf16 v[58:61], v[98:101], v[186:189], v[58:61]
	v_mfma_f32_16x16x32_bf16 v[46:49], v[78:81], v[194:197], v[46:49]
	v_mfma_f32_16x16x32_bf16 v[42:45], v[98:101], v[194:197], v[42:45]
	v_mfma_f32_16x16x32_bf16 v[30:33], v[78:81], v[208:211], v[30:33]
	v_mfma_f32_16x16x32_bf16 v[26:29], v[98:101], v[208:211], v[26:29]
	v_mfma_f32_16x16x32_bf16 v[14:17], v[78:81], v[216:219], v[14:17]
	v_mfma_f32_16x16x32_bf16 v[10:13], v[98:101], v[216:219], v[10:13]
	v_mfma_f32_16x16x32_bf16 v[54:57], v[146:149], v[162:165], v[54:57]
	v_mfma_f32_16x16x32_bf16 v[50:53], v[154:157], v[162:165], v[50:53]
	v_mfma_f32_16x16x32_bf16 v[38:41], v[146:149], v[190:193], v[38:41]
	v_mfma_f32_16x16x32_bf16 v[34:37], v[154:157], v[190:193], v[34:37]
	v_mfma_f32_16x16x32_bf16 v[22:25], v[146:149], v[204:207], v[22:25]
	v_mfma_f32_16x16x32_bf16 v[18:21], v[154:157], v[204:207], v[18:21]
	v_mfma_f32_16x16x32_bf16 v[6:9], v[146:149], v[212:215], v[6:9]
	v_mfma_f32_16x16x32_bf16 v[2:5], v[154:157], v[212:215], v[2:5]
	v_mfma_f32_16x16x32_bf16 v[54:57], v[150:153], v[186:189], v[54:57]
	v_mfma_f32_16x16x32_bf16 v[50:53], v[158:161], v[186:189], v[50:53]
	v_mfma_f32_16x16x32_bf16 v[38:41], v[150:153], v[194:197], v[38:41]
	v_mfma_f32_16x16x32_bf16 v[34:37], v[158:161], v[194:197], v[34:37]
	v_mfma_f32_16x16x32_bf16 v[22:25], v[150:153], v[208:211], v[22:25]
	v_mfma_f32_16x16x32_bf16 v[18:21], v[158:161], v[208:211], v[18:21]
	v_mfma_f32_16x16x32_bf16 v[6:9], v[150:153], v[216:219], v[6:9]
	v_mfma_f32_16x16x32_bf16 v[2:5], v[158:161], v[216:219], v[2:5]
	s_setprio 0
	s_barrier
	ds_read_b128 v[74:77], v201
	ds_read_b128 v[78:81], v201 offset:1024
	ds_read_b128 v[86:89], v201 offset:2048
	ds_read_b128 v[98:101], v201 offset:3072
	ds_read_b128 v[146:149], v202
	ds_read_b128 v[150:153], v202 offset:1024
	ds_read_b128 v[154:157], v202 offset:2048
	ds_read_b128 v[158:161], v202 offset:3072
	s_add_u32 s30, s30, 0x80000
	s_addc_u32 s31, s31, 0
	s_mov_b32 m0, s37
	v_lshl_add_u64 v[228:229], s[30:31], 0, v[170:171]
	ds_read_b128 v[162:165], v200 offset:32768
	ds_read_b128 v[186:189], v200 offset:33792
	ds_read_b128 v[190:193], v200 offset:34816
	ds_read_b128 v[194:197], v200 offset:35840
	ds_read_b128 v[204:207], v200 offset:36864
	ds_read_b128 v[208:211], v200 offset:37888
	ds_read_b128 v[212:215], v200 offset:38912
	ds_read_b128 v[216:219], v200 offset:39936
	global_load_lds_dwordx4 v[228:229], off
	v_lshl_add_u64 v[228:229], s[30:31], 0, v[174:175]
	s_mov_b32 m0, s38
	s_nop 0
	global_load_lds_dwordx4 v[228:229], off
	s_waitcnt vmcnt(8)
	s_waitcnt lgkmcnt(0)
	s_barrier
	s_setprio 1
	v_mfma_f32_16x16x32_bf16 v[142:145], v[74:77], v[162:165], v[142:145]
	v_mfma_f32_16x16x32_bf16 v[138:141], v[86:89], v[162:165], v[138:141]
	v_mfma_f32_16x16x32_bf16 v[126:129], v[74:77], v[190:193], v[126:129]
	v_mfma_f32_16x16x32_bf16 v[122:125], v[86:89], v[190:193], v[122:125]
	v_mfma_f32_16x16x32_bf16 v[110:113], v[74:77], v[204:207], v[110:113]
	v_mfma_f32_16x16x32_bf16 v[106:109], v[86:89], v[204:207], v[106:109]
	v_mfma_f32_16x16x32_bf16 v[90:93], v[74:77], v[212:215], v[90:93]
	v_mfma_f32_16x16x32_bf16 v[82:85], v[86:89], v[212:215], v[82:85]
	v_mfma_f32_16x16x32_bf16 v[142:145], v[78:81], v[186:189], v[142:145]
	v_mfma_f32_16x16x32_bf16 v[138:141], v[98:101], v[186:189], v[138:141]
	v_mfma_f32_16x16x32_bf16 v[126:129], v[78:81], v[194:197], v[126:129]
	v_mfma_f32_16x16x32_bf16 v[122:125], v[98:101], v[194:197], v[122:125]
	v_mfma_f32_16x16x32_bf16 v[110:113], v[78:81], v[208:211], v[110:113]
	v_mfma_f32_16x16x32_bf16 v[106:109], v[98:101], v[208:211], v[106:109]
	v_mfma_f32_16x16x32_bf16 v[90:93], v[78:81], v[216:219], v[90:93]
	v_mfma_f32_16x16x32_bf16 v[82:85], v[98:101], v[216:219], v[82:85]
	v_mfma_f32_16x16x32_bf16 v[134:137], v[146:149], v[162:165], v[134:137]
	v_mfma_f32_16x16x32_bf16 v[130:133], v[154:157], v[162:165], v[130:133]
	v_mfma_f32_16x16x32_bf16 v[118:121], v[146:149], v[190:193], v[118:121]
	v_mfma_f32_16x16x32_bf16 v[114:117], v[154:157], v[190:193], v[114:117]
	v_mfma_f32_16x16x32_bf16 v[102:105], v[146:149], v[204:207], v[102:105]
	v_mfma_f32_16x16x32_bf16 v[94:97], v[154:157], v[204:207], v[94:97]
	v_mfma_f32_16x16x32_bf16 v[70:73], v[146:149], v[212:215], v[70:73]
	v_mfma_f32_16x16x32_bf16 v[66:69], v[154:157], v[212:215], v[66:69]
	v_mfma_f32_16x16x32_bf16 v[134:137], v[150:153], v[186:189], v[134:137]
	v_mfma_f32_16x16x32_bf16 v[130:133], v[158:161], v[186:189], v[130:133]
	v_mfma_f32_16x16x32_bf16 v[118:121], v[150:153], v[194:197], v[118:121]
	v_mfma_f32_16x16x32_bf16 v[114:117], v[158:161], v[194:197], v[114:117]
	v_mfma_f32_16x16x32_bf16 v[102:105], v[150:153], v[208:211], v[102:105]
	v_mfma_f32_16x16x32_bf16 v[94:97], v[158:161], v[208:211], v[94:97]
	v_mfma_f32_16x16x32_bf16 v[70:73], v[150:153], v[216:219], v[70:73]
	v_mfma_f32_16x16x32_bf16 v[66:69], v[158:161], v[216:219], v[66:69]
	s_setprio 0
	s_barrier
	s_add_i32 s30, s45, s35
	v_lshl_add_u64 v[220:221], v[220:221], 0, s[6:7]
	s_mov_b32 m0, s30
	ds_read_b128 v[162:165], v200 offset:49152
	ds_read_b128 v[186:189], v200 offset:50176
	ds_read_b128 v[190:193], v200 offset:51200
	ds_read_b128 v[194:197], v200 offset:52224
	ds_read_b128 v[204:207], v200 offset:53248
	ds_read_b128 v[208:211], v200 offset:54272
	ds_read_b128 v[212:215], v200 offset:55296
	ds_read_b128 v[216:219], v200 offset:56320
	global_load_lds_dwordx4 v[220:221], off
	s_add_i32 m0, s30, 0x2000
	s_add_u32 s28, s28, 0x80080
	v_lshl_add_u64 v[220:221], v[222:223], 0, s[6:7]
	s_addc_u32 s29, s29, 0
	s_add_i32 s30, s46, s35
	global_load_lds_dwordx4 v[220:221], off
	v_lshl_add_u64 v[220:221], s[28:29], 0, v[172:173]
	s_mov_b32 m0, s30
	s_nop 0
	global_load_lds_dwordx4 v[220:221], off
	v_lshl_add_u64 v[220:221], s[28:29], 0, v[176:177]
	s_add_i32 m0, s30, 0x2000
	s_nop 0
	global_load_lds_dwordx4 v[220:221], off
	v_lshl_add_u64 v[220:221], v[224:225], 0, s[6:7]
	s_mov_b32 m0, s39
	s_nop 0
	global_load_lds_dwordx4 v[220:221], off
	v_lshl_add_u64 v[220:221], v[226:227], 0, s[6:7]
	s_mov_b32 m0, s40
	s_nop 0
	global_load_lds_dwordx4 v[220:221], off
	s_waitcnt vmcnt(8)
	s_waitcnt lgkmcnt(0)
	s_barrier
	s_setprio 1
	v_mfma_f32_16x16x32_bf16 v[62:65], v[74:77], v[162:165], v[62:65]
	v_mfma_f32_16x16x32_bf16 v[58:61], v[86:89], v[162:165], v[58:61]
	v_mfma_f32_16x16x32_bf16 v[46:49], v[74:77], v[190:193], v[46:49]
	v_mfma_f32_16x16x32_bf16 v[42:45], v[86:89], v[190:193], v[42:45]
	v_mfma_f32_16x16x32_bf16 v[30:33], v[74:77], v[204:207], v[30:33]
	v_mfma_f32_16x16x32_bf16 v[26:29], v[86:89], v[204:207], v[26:29]
	v_mfma_f32_16x16x32_bf16 v[14:17], v[74:77], v[212:215], v[14:17]
	v_mfma_f32_16x16x32_bf16 v[10:13], v[86:89], v[212:215], v[10:13]
	v_mfma_f32_16x16x32_bf16 v[62:65], v[78:81], v[186:189], v[62:65]
	v_mfma_f32_16x16x32_bf16 v[58:61], v[98:101], v[186:189], v[58:61]
	v_mfma_f32_16x16x32_bf16 v[46:49], v[78:81], v[194:197], v[46:49]
	v_mfma_f32_16x16x32_bf16 v[42:45], v[98:101], v[194:197], v[42:45]
	v_mfma_f32_16x16x32_bf16 v[30:33], v[78:81], v[208:211], v[30:33]
	v_mfma_f32_16x16x32_bf16 v[26:29], v[98:101], v[208:211], v[26:29]
	v_mfma_f32_16x16x32_bf16 v[14:17], v[78:81], v[216:219], v[14:17]
	v_mfma_f32_16x16x32_bf16 v[10:13], v[98:101], v[216:219], v[10:13]
	v_mfma_f32_16x16x32_bf16 v[54:57], v[146:149], v[162:165], v[54:57]
	v_mfma_f32_16x16x32_bf16 v[50:53], v[154:157], v[162:165], v[50:53]
	v_mfma_f32_16x16x32_bf16 v[38:41], v[146:149], v[190:193], v[38:41]
	v_mfma_f32_16x16x32_bf16 v[34:37], v[154:157], v[190:193], v[34:37]
	v_mfma_f32_16x16x32_bf16 v[22:25], v[146:149], v[204:207], v[22:25]
	v_mfma_f32_16x16x32_bf16 v[18:21], v[154:157], v[204:207], v[18:21]
	v_mfma_f32_16x16x32_bf16 v[6:9], v[146:149], v[212:215], v[6:9]
	v_mfma_f32_16x16x32_bf16 v[2:5], v[154:157], v[212:215], v[2:5]
	v_mfma_f32_16x16x32_bf16 v[54:57], v[150:153], v[186:189], v[54:57]
	v_mfma_f32_16x16x32_bf16 v[50:53], v[158:161], v[186:189], v[50:53]
	v_mfma_f32_16x16x32_bf16 v[38:41], v[150:153], v[194:197], v[38:41]
	v_mfma_f32_16x16x32_bf16 v[34:37], v[158:161], v[194:197], v[34:37]
	v_mfma_f32_16x16x32_bf16 v[22:25], v[150:153], v[208:211], v[22:25]
	v_mfma_f32_16x16x32_bf16 v[18:21], v[158:161], v[208:211], v[18:21]
	v_mfma_f32_16x16x32_bf16 v[6:9], v[150:153], v[216:219], v[6:9]
	v_mfma_f32_16x16x32_bf16 v[2:5], v[158:161], v[216:219], v[2:5]
	s_setprio 0
	s_barrier
	s_add_i32 s52, s52, 2
	s_add_u32 s26, s26, 0x100
	s_addc_u32 s27, s27, 0
	s_add_u32 s50, s50, 0x100
	s_addc_u32 s51, s51, 0
	s_cmp_gt_u32 s52, 29
	s_cbranch_scc0 .LBB0_2308
	s_and_b64 vcc, exec, s[10:11]
	s_cbranch_vccz .LBB0_2311
	s_barrier

.LBB0_2470:
	ds_read_b128 v[146:149], v178
	ds_read_b128 v[150:153], v178 offset:1024
	ds_read_b128 v[154:157], v178 offset:2048
	ds_read_b128 v[158:161], v178 offset:3072
	ds_read_b128 v[182:185], v179
	ds_read_b128 v[186:189], v179 offset:1024
	ds_read_b128 v[190:193], v179 offset:2048
	ds_read_b128 v[194:197], v179 offset:3072
	s_add_u32 s30, s28, 0xfffc0080
	s_addc_u32 s31, s29, -1
	s_cmp_eq_u32 s57, 12
	s_cselect_b32 s35, s21, s31
	s_cselect_b32 s34, s53, s30
	s_cselect_b32 s31, s17, s56
	s_cselect_b32 s30, s54, s55
	v_lshl_add_u64 v[162:163], s[28:29], 0, v[138:139]
	s_add_i32 m0, s27, 0xc000
	ds_read_b128 v[198:201], v180
	ds_read_b128 v[202:205], v180 offset:1024
	ds_read_b128 v[206:209], v180 offset:2048
	ds_read_b128 v[210:213], v180 offset:3072
	ds_read_b128 v[214:217], v180 offset:4096
	ds_read_b128 v[218:221], v180 offset:5120
	ds_read_b128 v[222:225], v180 offset:6144
	ds_read_b128 v[226:229], v180 offset:7168
	global_load_lds_dwordx4 v[162:163], off
	v_lshl_add_u64 v[162:163], s[28:29], 0, v[140:141]
	s_add_i32 m0, s27, 0xe000
	s_nop 0
	global_load_lds_dwordx4 v[162:163], off
	s_waitcnt vmcnt(8)
	s_waitcnt lgkmcnt(0)
	s_barrier
	s_setprio 1
	v_mfma_i32_16x16x64_i8 v[126:129], v[146:149], v[198:201], v[126:129]
	v_mfma_i32_16x16x64_i8 v[118:121], v[154:157], v[198:201], v[118:121]
	v_mfma_i32_16x16x64_i8 v[110:113], v[146:149], v[206:209], v[110:113]
	v_mfma_i32_16x16x64_i8 v[102:105], v[154:157], v[206:209], v[102:105]
	v_mfma_i32_16x16x64_i8 v[94:97], v[146:149], v[214:217], v[94:97]
	v_mfma_i32_16x16x64_i8 v[86:89], v[154:157], v[214:217], v[86:89]
	v_mfma_i32_16x16x64_i8 v[78:81], v[146:149], v[222:225], v[78:81]
	v_mfma_i32_16x16x64_i8 v[70:73], v[154:157], v[222:225], v[70:73]
	v_mfma_i32_16x16x64_i8 v[126:129], v[150:153], v[202:205], v[126:129]
	v_mfma_i32_16x16x64_i8 v[118:121], v[158:161], v[202:205], v[118:121]
	v_mfma_i32_16x16x64_i8 v[110:113], v[150:153], v[210:213], v[110:113]
	v_mfma_i32_16x16x64_i8 v[102:105], v[158:161], v[210:213], v[102:105]
	v_mfma_i32_16x16x64_i8 v[94:97], v[150:153], v[218:221], v[94:97]
	v_mfma_i32_16x16x64_i8 v[86:89], v[158:161], v[218:221], v[86:89]
	v_mfma_i32_16x16x64_i8 v[78:81], v[150:153], v[226:229], v[78:81]
	v_mfma_i32_16x16x64_i8 v[70:73], v[158:161], v[226:229], v[70:73]
	v_mfma_i32_16x16x64_i8 v[122:125], v[182:185], v[198:201], v[122:125]
	v_mfma_i32_16x16x64_i8 v[114:117], v[190:193], v[198:201], v[114:117]
	v_mfma_i32_16x16x64_i8 v[106:109], v[182:185], v[206:209], v[106:109]
	v_mfma_i32_16x16x64_i8 v[98:101], v[190:193], v[206:209], v[98:101]
	v_mfma_i32_16x16x64_i8 v[90:93], v[182:185], v[214:217], v[90:93]
	v_mfma_i32_16x16x64_i8 v[82:85], v[190:193], v[214:217], v[82:85]
	v_mfma_i32_16x16x64_i8 v[74:77], v[182:185], v[222:225], v[74:77]
	v_mfma_i32_16x16x64_i8 v[66:69], v[190:193], v[222:225], v[66:69]
	v_mfma_i32_16x16x64_i8 v[122:125], v[186:189], v[202:205], v[122:125]
	v_mfma_i32_16x16x64_i8 v[114:117], v[194:197], v[202:205], v[114:117]
	v_mfma_i32_16x16x64_i8 v[106:109], v[186:189], v[210:213], v[106:109]
	v_mfma_i32_16x16x64_i8 v[98:101], v[194:197], v[210:213], v[98:101]
	v_mfma_i32_16x16x64_i8 v[90:93], v[186:189], v[218:221], v[90:93]
	v_mfma_i32_16x16x64_i8 v[82:85], v[194:197], v[218:221], v[82:85]
	v_mfma_i32_16x16x64_i8 v[74:77], v[186:189], v[226:229], v[74:77]
	v_mfma_i32_16x16x64_i8 v[66:69], v[194:197], v[226:229], v[66:69]
	s_setprio 0
	s_barrier
	s_add_i32 s63, s46, s38
	v_lshl_add_u64 v[162:163], s[30:31], 0, v[134:135]
	s_mov_b32 m0, s63
	ds_read_b128 v[198:201], v180 offset:16384
	ds_read_b128 v[202:205], v180 offset:17408
	ds_read_b128 v[206:209], v180 offset:18432
	ds_read_b128 v[210:213], v180 offset:19456
	ds_read_b128 v[214:217], v180 offset:20480
	ds_read_b128 v[218:221], v180 offset:21504
	ds_read_b128 v[222:225], v180 offset:22528
	ds_read_b128 v[226:229], v180 offset:23552
	global_load_lds_dwordx4 v[162:163], off
	s_add_i32 m0, s63, 0x2000
	s_add_u32 s68, s30, 0x40000
	v_lshl_add_u64 v[230:231], s[30:31], 0, v[130:131]
	s_addc_u32 s69, s31, 0
	s_add_i32 s63, s47, s38
	global_load_lds_dwordx4 v[230:231], off
	v_lshl_add_u64 v[232:233], s[68:69], 0, v[134:135]
	s_mov_b32 m0, s63
	v_lshl_add_u64 v[234:235], s[34:35], 0, v[132:133]
	global_load_lds_dwordx4 v[232:233], off
	v_lshl_add_u64 v[232:233], s[68:69], 0, v[130:131]
	s_add_i32 m0, s63, 0x2000
	s_nop 0
	global_load_lds_dwordx4 v[232:233], off
	v_lshl_add_u64 v[232:233], s[34:35], 0, v[136:137]
	s_mov_b32 m0, s27
	s_nop 0
	global_load_lds_dwordx4 v[232:233], off
	s_mov_b32 m0, s40
	s_nop 0
	global_load_lds_dwordx4 v[234:235], off
	s_waitcnt vmcnt(8)
	s_waitcnt lgkmcnt(0)
	s_barrier
	s_setprio 1
	v_mfma_i32_16x16x64_i8 v[62:65], v[146:149], v[198:201], v[62:65]
	v_mfma_i32_16x16x64_i8 v[54:57], v[154:157], v[198:201], v[54:57]
	v_mfma_i32_16x16x64_i8 v[46:49], v[146:149], v[206:209], v[46:49]
	v_mfma_i32_16x16x64_i8 v[38:41], v[154:157], v[206:209], v[38:41]
	v_mfma_i32_16x16x64_i8 v[30:33], v[146:149], v[214:217], v[30:33]
	v_mfma_i32_16x16x64_i8 v[22:25], v[154:157], v[214:217], v[22:25]
	v_mfma_i32_16x16x64_i8 v[14:17], v[146:149], v[222:225], v[14:17]
	v_mfma_i32_16x16x64_i8 v[6:9], v[154:157], v[222:225], v[6:9]
	v_mfma_i32_16x16x64_i8 v[62:65], v[150:153], v[202:205], v[62:65]
	v_mfma_i32_16x16x64_i8 v[54:57], v[158:161], v[202:205], v[54:57]
	v_mfma_i32_16x16x64_i8 v[46:49], v[150:153], v[210:213], v[46:49]
	v_mfma_i32_16x16x64_i8 v[38:41], v[158:161], v[210:213], v[38:41]
	v_mfma_i32_16x16x64_i8 v[30:33], v[150:153], v[218:221], v[30:33]
	v_mfma_i32_16x16x64_i8 v[22:25], v[158:161], v[218:221], v[22:25]
	v_mfma_i32_16x16x64_i8 v[14:17], v[150:153], v[226:229], v[14:17]
	v_mfma_i32_16x16x64_i8 v[6:9], v[158:161], v[226:229], v[6:9]
	v_mfma_i32_16x16x64_i8 v[58:61], v[182:185], v[198:201], v[58:61]
	v_mfma_i32_16x16x64_i8 v[50:53], v[190:193], v[198:201], v[50:53]
	v_mfma_i32_16x16x64_i8 v[42:45], v[182:185], v[206:209], v[42:45]
	v_mfma_i32_16x16x64_i8 v[34:37], v[190:193], v[206:209], v[34:37]
	v_mfma_i32_16x16x64_i8 v[26:29], v[182:185], v[214:217], v[26:29]
	v_mfma_i32_16x16x64_i8 v[18:21], v[190:193], v[214:217], v[18:21]
	v_mfma_i32_16x16x64_i8 v[10:13], v[182:185], v[222:225], v[10:13]
	v_mfma_i32_16x16x64_i8 v[2:5], v[190:193], v[222:225], v[2:5]
	v_mfma_i32_16x16x64_i8 v[58:61], v[186:189], v[202:205], v[58:61]
	v_mfma_i32_16x16x64_i8 v[50:53], v[194:197], v[202:205], v[50:53]
	v_mfma_i32_16x16x64_i8 v[42:45], v[186:189], v[210:213], v[42:45]
	v_mfma_i32_16x16x64_i8 v[34:37], v[194:197], v[210:213], v[34:37]
	v_mfma_i32_16x16x64_i8 v[26:29], v[186:189], v[218:221], v[26:29]
	v_mfma_i32_16x16x64_i8 v[18:21], v[194:197], v[218:221], v[18:21]
	v_mfma_i32_16x16x64_i8 v[10:13], v[186:189], v[226:229], v[10:13]
	v_mfma_i32_16x16x64_i8 v[2:5], v[194:197], v[226:229], v[2:5]
	s_setprio 0
	s_barrier
	s_add_i32 s63, 0, 0x18000
	v_add_u32_e32 v158, s63, v169
	ds_read_b128 v[146:149], v158
	ds_read_b128 v[150:153], v158 offset:1024
	ds_read_b128 v[154:157], v158 offset:2048
	ds_read_b128 v[158:161], v158 offset:3072
	ds_read_b128 v[182:185], v181
	ds_read_b128 v[186:189], v181 offset:1024
	ds_read_b128 v[190:193], v181 offset:2048
	ds_read_b128 v[194:197], v181 offset:3072
	s_add_u32 s34, s34, 0x40000
	s_addc_u32 s35, s35, 0
	s_mov_b32 m0, s41
	v_lshl_add_u64 v[236:237], s[34:35], 0, v[136:137]
	ds_read_b128 v[198:201], v180 offset:32768
	ds_read_b128 v[202:205], v180 offset:33792
	ds_read_b128 v[206:209], v180 offset:34816
	ds_read_b128 v[210:213], v180 offset:35840
	ds_read_b128 v[214:217], v180 offset:36864
	ds_read_b128 v[218:221], v180 offset:37888
	ds_read_b128 v[222:225], v180 offset:38912
	ds_read_b128 v[226:229], v180 offset:39936
	global_load_lds_dwordx4 v[236:237], off
	v_lshl_add_u64 v[236:237], s[34:35], 0, v[132:133]
	s_mov_b32 m0, s42
	s_nop 0
	global_load_lds_dwordx4 v[236:237], off
	s_waitcnt vmcnt(8)
	s_waitcnt lgkmcnt(0)
	s_barrier
	s_setprio 1
	v_mfma_i32_16x16x64_i8 v[126:129], v[146:149], v[198:201], v[126:129]
	v_mfma_i32_16x16x64_i8 v[118:121], v[154:157], v[198:201], v[118:121]
	v_mfma_i32_16x16x64_i8 v[110:113], v[146:149], v[206:209], v[110:113]
	v_mfma_i32_16x16x64_i8 v[102:105], v[154:157], v[206:209], v[102:105]
	v_mfma_i32_16x16x64_i8 v[94:97], v[146:149], v[214:217], v[94:97]
	v_mfma_i32_16x16x64_i8 v[86:89], v[154:157], v[214:217], v[86:89]
	v_mfma_i32_16x16x64_i8 v[78:81], v[146:149], v[222:225], v[78:81]
	v_mfma_i32_16x16x64_i8 v[70:73], v[154:157], v[222:225], v[70:73]
	v_mfma_i32_16x16x64_i8 v[126:129], v[150:153], v[202:205], v[126:129]
	v_mfma_i32_16x16x64_i8 v[118:121], v[158:161], v[202:205], v[118:121]
	v_mfma_i32_16x16x64_i8 v[110:113], v[150:153], v[210:213], v[110:113]
	v_mfma_i32_16x16x64_i8 v[102:105], v[158:161], v[210:213], v[102:105]
	v_mfma_i32_16x16x64_i8 v[94:97], v[150:153], v[218:221], v[94:97]
	v_mfma_i32_16x16x64_i8 v[86:89], v[158:161], v[218:221], v[86:89]
	v_mfma_i32_16x16x64_i8 v[78:81], v[150:153], v[226:229], v[78:81]
	v_mfma_i32_16x16x64_i8 v[70:73], v[158:161], v[226:229], v[70:73]
	v_mfma_i32_16x16x64_i8 v[122:125], v[182:185], v[198:201], v[122:125]
	v_mfma_i32_16x16x64_i8 v[114:117], v[190:193], v[198:201], v[114:117]
	v_mfma_i32_16x16x64_i8 v[106:109], v[182:185], v[206:209], v[106:109]
	v_mfma_i32_16x16x64_i8 v[98:101], v[190:193], v[206:209], v[98:101]
	v_mfma_i32_16x16x64_i8 v[90:93], v[182:185], v[214:217], v[90:93]
	v_mfma_i32_16x16x64_i8 v[82:85], v[190:193], v[214:217], v[82:85]
	v_mfma_i32_16x16x64_i8 v[74:77], v[182:185], v[222:225], v[74:77]
	v_mfma_i32_16x16x64_i8 v[66:69], v[190:193], v[222:225], v[66:69]
	v_mfma_i32_16x16x64_i8 v[122:125], v[186:189], v[202:205], v[122:125]
	v_mfma_i32_16x16x64_i8 v[114:117], v[194:197], v[202:205], v[114:117]
	v_mfma_i32_16x16x64_i8 v[106:109], v[186:189], v[210:213], v[106:109]
	v_mfma_i32_16x16x64_i8 v[98:101], v[194:197], v[210:213], v[98:101]
	v_mfma_i32_16x16x64_i8 v[90:93], v[186:189], v[218:221], v[90:93]
	v_mfma_i32_16x16x64_i8 v[82:85], v[194:197], v[218:221], v[82:85]
	v_mfma_i32_16x16x64_i8 v[74:77], v[186:189], v[226:229], v[74:77]
	v_mfma_i32_16x16x64_i8 v[66:69], v[194:197], v[226:229], v[66:69]
	s_setprio 0
	s_barrier
	s_add_i32 s34, s63, s38
	v_lshl_add_u64 v[162:163], v[162:163], 0, s[8:9]
	s_mov_b32 m0, s34
	ds_read_b128 v[198:201], v180 offset:49152
	ds_read_b128 v[202:205], v180 offset:50176
	ds_read_b128 v[206:209], v180 offset:51200
	ds_read_b128 v[210:213], v180 offset:52224
	ds_read_b128 v[214:217], v180 offset:53248
	ds_read_b128 v[218:221], v180 offset:54272
	ds_read_b128 v[222:225], v180 offset:55296
	ds_read_b128 v[226:229], v180 offset:56320
	global_load_lds_dwordx4 v[162:163], off
	s_add_i32 m0, s34, 0x2000
	s_add_u32 s30, s30, 0x40080
	v_lshl_add_u64 v[162:163], v[230:231], 0, s[8:9]
	s_addc_u32 s31, s31, 0
	s_add_i32 s34, s48, s38
	global_load_lds_dwordx4 v[162:163], off
	v_lshl_add_u64 v[162:163], s[30:31], 0, v[134:135]
	s_mov_b32 m0, s34
	s_nop 0
	global_load_lds_dwordx4 v[162:163], off
	v_lshl_add_u64 v[162:163], s[30:31], 0, v[130:131]
	s_add_i32 m0, s34, 0x2000
	s_nop 0
	global_load_lds_dwordx4 v[162:163], off
	v_lshl_add_u64 v[162:163], v[232:233], 0, s[8:9]
	s_mov_b32 m0, s43
	s_nop 0
	global_load_lds_dwordx4 v[162:163], off
	v_lshl_add_u64 v[162:163], v[234:235], 0, s[8:9]
	s_mov_b32 m0, s44
	s_nop 0
	global_load_lds_dwordx4 v[162:163], off
	s_waitcnt vmcnt(8)
	s_waitcnt lgkmcnt(0)
	s_barrier
	s_setprio 1
	v_mfma_i32_16x16x64_i8 v[62:65], v[146:149], v[198:201], v[62:65]
	v_mfma_i32_16x16x64_i8 v[54:57], v[154:157], v[198:201], v[54:57]
	v_mfma_i32_16x16x64_i8 v[46:49], v[146:149], v[206:209], v[46:49]
	v_mfma_i32_16x16x64_i8 v[38:41], v[154:157], v[206:209], v[38:41]
	v_mfma_i32_16x16x64_i8 v[30:33], v[146:149], v[214:217], v[30:33]
	v_mfma_i32_16x16x64_i8 v[22:25], v[154:157], v[214:217], v[22:25]
	v_mfma_i32_16x16x64_i8 v[14:17], v[146:149], v[222:225], v[14:17]
	v_mfma_i32_16x16x64_i8 v[6:9], v[154:157], v[222:225], v[6:9]
	v_mfma_i32_16x16x64_i8 v[62:65], v[150:153], v[202:205], v[62:65]
	v_mfma_i32_16x16x64_i8 v[54:57], v[158:161], v[202:205], v[54:57]
	v_mfma_i32_16x16x64_i8 v[46:49], v[150:153], v[210:213], v[46:49]
	v_mfma_i32_16x16x64_i8 v[38:41], v[158:161], v[210:213], v[38:41]
	v_mfma_i32_16x16x64_i8 v[30:33], v[150:153], v[218:221], v[30:33]
	v_mfma_i32_16x16x64_i8 v[22:25], v[158:161], v[218:221], v[22:25]
	v_mfma_i32_16x16x64_i8 v[14:17], v[150:153], v[226:229], v[14:17]
	v_mfma_i32_16x16x64_i8 v[6:9], v[158:161], v[226:229], v[6:9]
	v_mfma_i32_16x16x64_i8 v[58:61], v[182:185], v[198:201], v[58:61]
	v_mfma_i32_16x16x64_i8 v[50:53], v[190:193], v[198:201], v[50:53]
	v_mfma_i32_16x16x64_i8 v[42:45], v[182:185], v[206:209], v[42:45]
	v_mfma_i32_16x16x64_i8 v[34:37], v[190:193], v[206:209], v[34:37]
	v_mfma_i32_16x16x64_i8 v[26:29], v[182:185], v[214:217], v[26:29]
	v_mfma_i32_16x16x64_i8 v[18:21], v[190:193], v[214:217], v[18:21]
	v_mfma_i32_16x16x64_i8 v[10:13], v[182:185], v[222:225], v[10:13]
	v_mfma_i32_16x16x64_i8 v[2:5], v[190:193], v[222:225], v[2:5]
	v_mfma_i32_16x16x64_i8 v[58:61], v[186:189], v[202:205], v[58:61]
	v_mfma_i32_16x16x64_i8 v[50:53], v[194:197], v[202:205], v[50:53]
	v_mfma_i32_16x16x64_i8 v[42:45], v[186:189], v[210:213], v[42:45]
	v_mfma_i32_16x16x64_i8 v[34:37], v[194:197], v[210:213], v[34:37]
	v_mfma_i32_16x16x64_i8 v[26:29], v[186:189], v[218:221], v[26:29]
	v_mfma_i32_16x16x64_i8 v[18:21], v[194:197], v[218:221], v[18:21]
	v_mfma_i32_16x16x64_i8 v[10:13], v[186:189], v[226:229], v[10:13]
	v_mfma_i32_16x16x64_i8 v[2:5], v[194:197], v[226:229], v[2:5]
	s_setprio 0
	s_barrier
	s_add_i32 s57, s57, 2
	s_add_u32 s28, s28, 0x100
	s_addc_u32 s29, s29, 0
	s_add_u32 s55, s55, 0x100
	s_addc_u32 s56, s56, 0
	s_cmp_gt_u32 s57, 13
	s_cbranch_scc0 .LBB0_2470
	s_and_b64 vcc, exec, s[12:13]
	s_cbranch_vccz .LBB0_2473
	s_barrier

.LBB0_2579:
	ds_read_b128 v[154:157], v149
	ds_read_b128 v[158:161], v149 offset:1024
	ds_read_b128 v[162:165], v149 offset:2048
	ds_read_b128 v[170:173], v149 offset:3072
	ds_read_b128 v[174:177], v150
	ds_read_b128 v[178:181], v150 offset:1024
	ds_read_b128 v[182:185], v150 offset:2048
	ds_read_b128 v[186:189], v150 offset:3072
	s_add_u32 s24, s22, 0xffea0080
	s_addc_u32 s25, s23, -1
	s_cmpk_eq_i32 s53, 0x54
	s_cselect_b32 s27, s5, s25
	s_cselect_b32 s26, s4, s24
	s_cselect_b32 s25, s21, s52
	s_cselect_b32 s24, s20, s51
	v_lshl_add_u64 v[146:147], s[22:23], 0, v[138:139]
	s_add_i32 m0, s30, 0xc000
	ds_read_b128 v[190:193], v151
	ds_read_b128 v[194:197], v151 offset:1024
	ds_read_b128 v[198:201], v151 offset:2048
	ds_read_b128 v[202:205], v151 offset:3072
	ds_read_b128 v[206:209], v151 offset:4096
	ds_read_b128 v[210:213], v151 offset:5120
	ds_read_b128 v[214:217], v151 offset:6144
	ds_read_b128 v[218:221], v151 offset:7168
	global_load_lds_dwordx4 v[146:147], off
	v_lshl_add_u64 v[146:147], s[22:23], 0, v[140:141]
	s_add_i32 m0, s30, 0xe000
	s_nop 0
	global_load_lds_dwordx4 v[146:147], off
	s_waitcnt vmcnt(8)
	s_waitcnt lgkmcnt(0)
	s_barrier
	s_setprio 1
	v_mfma_f32_16x16x32_bf16 v[126:129], v[154:157], v[190:193], v[126:129]
	v_mfma_f32_16x16x32_bf16 v[122:125], v[162:165], v[190:193], v[122:125]
	v_mfma_f32_16x16x32_bf16 v[118:121], v[154:157], v[198:201], v[118:121]
	v_mfma_f32_16x16x32_bf16 v[110:113], v[162:165], v[198:201], v[110:113]
	v_mfma_f32_16x16x32_bf16 v[102:105], v[154:157], v[206:209], v[102:105]
	v_mfma_f32_16x16x32_bf16 v[94:97], v[162:165], v[206:209], v[94:97]
	v_mfma_f32_16x16x32_bf16 v[86:89], v[154:157], v[214:217], v[86:89]
	v_mfma_f32_16x16x32_bf16 v[78:81], v[162:165], v[214:217], v[78:81]
	v_mfma_f32_16x16x32_bf16 v[126:129], v[158:161], v[194:197], v[126:129]
	v_mfma_f32_16x16x32_bf16 v[122:125], v[170:173], v[194:197], v[122:125]
	v_mfma_f32_16x16x32_bf16 v[118:121], v[158:161], v[202:205], v[118:121]
	v_mfma_f32_16x16x32_bf16 v[110:113], v[170:173], v[202:205], v[110:113]
	v_mfma_f32_16x16x32_bf16 v[102:105], v[158:161], v[210:213], v[102:105]
	v_mfma_f32_16x16x32_bf16 v[94:97], v[170:173], v[210:213], v[94:97]
	v_mfma_f32_16x16x32_bf16 v[86:89], v[158:161], v[218:221], v[86:89]
	v_mfma_f32_16x16x32_bf16 v[78:81], v[170:173], v[218:221], v[78:81]
	v_mfma_f32_16x16x32_bf16 v[114:117], v[174:177], v[190:193], v[114:117]
	v_mfma_f32_16x16x32_bf16 v[106:109], v[182:185], v[190:193], v[106:109]
	v_mfma_f32_16x16x32_bf16 v[98:101], v[174:177], v[198:201], v[98:101]
	v_mfma_f32_16x16x32_bf16 v[90:93], v[182:185], v[198:201], v[90:93]
	v_mfma_f32_16x16x32_bf16 v[82:85], v[174:177], v[206:209], v[82:85]
	v_mfma_f32_16x16x32_bf16 v[74:77], v[182:185], v[206:209], v[74:77]
	v_mfma_f32_16x16x32_bf16 v[70:73], v[174:177], v[214:217], v[70:73]
	v_mfma_f32_16x16x32_bf16 v[66:69], v[182:185], v[214:217], v[66:69]
	v_mfma_f32_16x16x32_bf16 v[114:117], v[178:181], v[194:197], v[114:117]
	v_mfma_f32_16x16x32_bf16 v[106:109], v[186:189], v[194:197], v[106:109]
	v_mfma_f32_16x16x32_bf16 v[98:101], v[178:181], v[202:205], v[98:101]
	v_mfma_f32_16x16x32_bf16 v[90:93], v[186:189], v[202:205], v[90:93]
	v_mfma_f32_16x16x32_bf16 v[82:85], v[178:181], v[210:213], v[82:85]
	v_mfma_f32_16x16x32_bf16 v[74:77], v[186:189], v[210:213], v[74:77]
	v_mfma_f32_16x16x32_bf16 v[70:73], v[178:181], v[218:221], v[70:73]
	v_mfma_f32_16x16x32_bf16 v[66:69], v[186:189], v[218:221], v[66:69]
	s_setprio 0
	s_barrier
	s_add_i32 s54, s40, s29
	v_lshl_add_u64 v[146:147], s[24:25], 0, v[132:133]
	s_mov_b32 m0, s54
	ds_read_b128 v[190:193], v151 offset:16384
	ds_read_b128 v[194:197], v151 offset:17408
	ds_read_b128 v[198:201], v151 offset:18432
	ds_read_b128 v[202:205], v151 offset:19456
	ds_read_b128 v[206:209], v151 offset:20480
	ds_read_b128 v[210:213], v151 offset:21504
	ds_read_b128 v[214:217], v151 offset:22528
	ds_read_b128 v[218:221], v151 offset:23552
	global_load_lds_dwordx4 v[146:147], off
	s_add_i32 m0, s54, 0x2000
	s_add_u32 s54, s24, 0x160000
	v_lshl_add_u64 v[222:223], s[24:25], 0, v[136:137]
	s_addc_u32 s55, s25, 0
	s_add_i32 s56, s41, s29
	global_load_lds_dwordx4 v[222:223], off
	v_lshl_add_u64 v[224:225], s[54:55], 0, v[132:133]
	s_mov_b32 m0, s56
	v_lshl_add_u64 v[226:227], s[26:27], 0, v[134:135]
	global_load_lds_dwordx4 v[224:225], off
	v_lshl_add_u64 v[224:225], s[54:55], 0, v[136:137]
	s_add_i32 m0, s56, 0x2000
	s_nop 0
	global_load_lds_dwordx4 v[224:225], off
	v_lshl_add_u64 v[224:225], s[26:27], 0, v[130:131]
	s_mov_b32 m0, s30
	s_nop 0
	global_load_lds_dwordx4 v[224:225], off
	s_mov_b32 m0, s31
	s_nop 0
	global_load_lds_dwordx4 v[226:227], off
	s_waitcnt vmcnt(8)
	s_waitcnt lgkmcnt(0)
	s_barrier
	s_setprio 1
	v_mfma_f32_16x16x32_bf16 v[62:65], v[154:157], v[190:193], v[62:65]
	v_mfma_f32_16x16x32_bf16 v[58:61], v[162:165], v[190:193], v[58:61]
	v_mfma_f32_16x16x32_bf16 v[54:57], v[154:157], v[198:201], v[54:57]
	v_mfma_f32_16x16x32_bf16 v[46:49], v[162:165], v[198:201], v[46:49]
	v_mfma_f32_16x16x32_bf16 v[38:41], v[154:157], v[206:209], v[38:41]
	v_mfma_f32_16x16x32_bf16 v[30:33], v[162:165], v[206:209], v[30:33]
	v_mfma_f32_16x16x32_bf16 v[22:25], v[154:157], v[214:217], v[22:25]
	v_mfma_f32_16x16x32_bf16 v[14:17], v[162:165], v[214:217], v[14:17]
	v_mfma_f32_16x16x32_bf16 v[62:65], v[158:161], v[194:197], v[62:65]
	v_mfma_f32_16x16x32_bf16 v[58:61], v[170:173], v[194:197], v[58:61]
	v_mfma_f32_16x16x32_bf16 v[54:57], v[158:161], v[202:205], v[54:57]
	v_mfma_f32_16x16x32_bf16 v[46:49], v[170:173], v[202:205], v[46:49]
	v_mfma_f32_16x16x32_bf16 v[38:41], v[158:161], v[210:213], v[38:41]
	v_mfma_f32_16x16x32_bf16 v[30:33], v[170:173], v[210:213], v[30:33]
	v_mfma_f32_16x16x32_bf16 v[22:25], v[158:161], v[218:221], v[22:25]
	v_mfma_f32_16x16x32_bf16 v[14:17], v[170:173], v[218:221], v[14:17]
	v_mfma_f32_16x16x32_bf16 v[50:53], v[174:177], v[190:193], v[50:53]
	v_mfma_f32_16x16x32_bf16 v[42:45], v[182:185], v[190:193], v[42:45]
	v_mfma_f32_16x16x32_bf16 v[34:37], v[174:177], v[198:201], v[34:37]
	v_mfma_f32_16x16x32_bf16 v[26:29], v[182:185], v[198:201], v[26:29]
	v_mfma_f32_16x16x32_bf16 v[18:21], v[174:177], v[206:209], v[18:21]
	v_mfma_f32_16x16x32_bf16 v[10:13], v[182:185], v[206:209], v[10:13]
	v_mfma_f32_16x16x32_bf16 v[6:9], v[174:177], v[214:217], v[6:9]
	v_mfma_f32_16x16x32_bf16 v[2:5], v[182:185], v[214:217], v[2:5]
	v_mfma_f32_16x16x32_bf16 v[50:53], v[178:181], v[194:197], v[50:53]
	v_mfma_f32_16x16x32_bf16 v[42:45], v[186:189], v[194:197], v[42:45]
	v_mfma_f32_16x16x32_bf16 v[34:37], v[178:181], v[202:205], v[34:37]
	v_mfma_f32_16x16x32_bf16 v[26:29], v[186:189], v[202:205], v[26:29]
	v_mfma_f32_16x16x32_bf16 v[18:21], v[178:181], v[210:213], v[18:21]
	v_mfma_f32_16x16x32_bf16 v[10:13], v[186:189], v[210:213], v[10:13]
	v_mfma_f32_16x16x32_bf16 v[6:9], v[178:181], v[218:221], v[6:9]
	v_mfma_f32_16x16x32_bf16 v[2:5], v[186:189], v[218:221], v[2:5]
	s_setprio 0
	s_barrier
	ds_read_b128 v[154:157], v152
	ds_read_b128 v[158:161], v152 offset:1024
	ds_read_b128 v[162:165], v152 offset:2048
	ds_read_b128 v[170:173], v152 offset:3072
	ds_read_b128 v[174:177], v153
	ds_read_b128 v[178:181], v153 offset:1024
	ds_read_b128 v[182:185], v153 offset:2048
	ds_read_b128 v[186:189], v153 offset:3072
	s_add_u32 s26, s26, 0x160000
	s_addc_u32 s27, s27, 0
	s_mov_b32 m0, s34
	v_lshl_add_u64 v[228:229], s[26:27], 0, v[130:131]
	ds_read_b128 v[190:193], v151 offset:32768
	ds_read_b128 v[194:197], v151 offset:33792
	ds_read_b128 v[198:201], v151 offset:34816
	ds_read_b128 v[202:205], v151 offset:35840
	ds_read_b128 v[206:209], v151 offset:36864
	ds_read_b128 v[210:213], v151 offset:37888
	ds_read_b128 v[214:217], v151 offset:38912
	ds_read_b128 v[218:221], v151 offset:39936
	global_load_lds_dwordx4 v[228:229], off
	v_lshl_add_u64 v[228:229], s[26:27], 0, v[134:135]
	s_mov_b32 m0, s35
	s_nop 0
	global_load_lds_dwordx4 v[228:229], off
	s_waitcnt vmcnt(8)
	s_waitcnt lgkmcnt(0)
	s_barrier
	s_setprio 1
	v_mfma_f32_16x16x32_bf16 v[126:129], v[154:157], v[190:193], v[126:129]
	v_mfma_f32_16x16x32_bf16 v[122:125], v[162:165], v[190:193], v[122:125]
	v_mfma_f32_16x16x32_bf16 v[118:121], v[154:157], v[198:201], v[118:121]
	v_mfma_f32_16x16x32_bf16 v[110:113], v[162:165], v[198:201], v[110:113]
	v_mfma_f32_16x16x32_bf16 v[102:105], v[154:157], v[206:209], v[102:105]
	v_mfma_f32_16x16x32_bf16 v[94:97], v[162:165], v[206:209], v[94:97]
	v_mfma_f32_16x16x32_bf16 v[86:89], v[154:157], v[214:217], v[86:89]
	v_mfma_f32_16x16x32_bf16 v[78:81], v[162:165], v[214:217], v[78:81]
	v_mfma_f32_16x16x32_bf16 v[126:129], v[158:161], v[194:197], v[126:129]
	v_mfma_f32_16x16x32_bf16 v[122:125], v[170:173], v[194:197], v[122:125]
	v_mfma_f32_16x16x32_bf16 v[118:121], v[158:161], v[202:205], v[118:121]
	v_mfma_f32_16x16x32_bf16 v[110:113], v[170:173], v[202:205], v[110:113]
	v_mfma_f32_16x16x32_bf16 v[102:105], v[158:161], v[210:213], v[102:105]
	v_mfma_f32_16x16x32_bf16 v[94:97], v[170:173], v[210:213], v[94:97]
	v_mfma_f32_16x16x32_bf16 v[86:89], v[158:161], v[218:221], v[86:89]
	v_mfma_f32_16x16x32_bf16 v[78:81], v[170:173], v[218:221], v[78:81]
	v_mfma_f32_16x16x32_bf16 v[114:117], v[174:177], v[190:193], v[114:117]
	v_mfma_f32_16x16x32_bf16 v[106:109], v[182:185], v[190:193], v[106:109]
	v_mfma_f32_16x16x32_bf16 v[98:101], v[174:177], v[198:201], v[98:101]
	v_mfma_f32_16x16x32_bf16 v[90:93], v[182:185], v[198:201], v[90:93]
	v_mfma_f32_16x16x32_bf16 v[82:85], v[174:177], v[206:209], v[82:85]
	v_mfma_f32_16x16x32_bf16 v[74:77], v[182:185], v[206:209], v[74:77]
	v_mfma_f32_16x16x32_bf16 v[70:73], v[174:177], v[214:217], v[70:73]
	v_mfma_f32_16x16x32_bf16 v[66:69], v[182:185], v[214:217], v[66:69]
	v_mfma_f32_16x16x32_bf16 v[114:117], v[178:181], v[194:197], v[114:117]
	v_mfma_f32_16x16x32_bf16 v[106:109], v[186:189], v[194:197], v[106:109]
	v_mfma_f32_16x16x32_bf16 v[98:101], v[178:181], v[202:205], v[98:101]
	v_mfma_f32_16x16x32_bf16 v[90:93], v[186:189], v[202:205], v[90:93]
	v_mfma_f32_16x16x32_bf16 v[82:85], v[178:181], v[210:213], v[82:85]
	v_mfma_f32_16x16x32_bf16 v[74:77], v[186:189], v[210:213], v[74:77]
	v_mfma_f32_16x16x32_bf16 v[70:73], v[178:181], v[218:221], v[70:73]
	v_mfma_f32_16x16x32_bf16 v[66:69], v[186:189], v[218:221], v[66:69]
	s_setprio 0
	s_barrier
	s_add_i32 s26, s42, s29
	v_lshl_add_u64 v[146:147], v[146:147], 0, s[6:7]
	s_mov_b32 m0, s26
	ds_read_b128 v[190:193], v151 offset:49152
	ds_read_b128 v[194:197], v151 offset:50176
	ds_read_b128 v[198:201], v151 offset:51200
	ds_read_b128 v[202:205], v151 offset:52224
	ds_read_b128 v[206:209], v151 offset:53248
	ds_read_b128 v[210:213], v151 offset:54272
	ds_read_b128 v[214:217], v151 offset:55296
	ds_read_b128 v[218:221], v151 offset:56320
	global_load_lds_dwordx4 v[146:147], off
	s_add_i32 m0, s26, 0x2000
	s_add_u32 s24, s24, 0x160080
	v_lshl_add_u64 v[146:147], v[222:223], 0, s[6:7]
	s_addc_u32 s25, s25, 0
	s_add_i32 s26, s43, s29
	global_load_lds_dwordx4 v[146:147], off
	v_lshl_add_u64 v[146:147], s[24:25], 0, v[132:133]
	s_mov_b32 m0, s26
	s_nop 0
	global_load_lds_dwordx4 v[146:147], off
	v_lshl_add_u64 v[146:147], s[24:25], 0, v[136:137]
	s_add_i32 m0, s26, 0x2000
	s_nop 0
	global_load_lds_dwordx4 v[146:147], off
	v_lshl_add_u64 v[146:147], v[224:225], 0, s[6:7]
	s_mov_b32 m0, s36
	s_nop 0
	global_load_lds_dwordx4 v[146:147], off
	v_lshl_add_u64 v[146:147], v[226:227], 0, s[6:7]
	s_mov_b32 m0, s37
	s_nop 0
	global_load_lds_dwordx4 v[146:147], off
	s_waitcnt vmcnt(8)
	s_waitcnt lgkmcnt(0)
	s_barrier
	s_setprio 1
	v_mfma_f32_16x16x32_bf16 v[62:65], v[154:157], v[190:193], v[62:65]
	v_mfma_f32_16x16x32_bf16 v[58:61], v[162:165], v[190:193], v[58:61]
	v_mfma_f32_16x16x32_bf16 v[54:57], v[154:157], v[198:201], v[54:57]
	v_mfma_f32_16x16x32_bf16 v[46:49], v[162:165], v[198:201], v[46:49]
	v_mfma_f32_16x16x32_bf16 v[38:41], v[154:157], v[206:209], v[38:41]
	v_mfma_f32_16x16x32_bf16 v[30:33], v[162:165], v[206:209], v[30:33]
	v_mfma_f32_16x16x32_bf16 v[22:25], v[154:157], v[214:217], v[22:25]
	v_mfma_f32_16x16x32_bf16 v[14:17], v[162:165], v[214:217], v[14:17]
	v_mfma_f32_16x16x32_bf16 v[62:65], v[158:161], v[194:197], v[62:65]
	v_mfma_f32_16x16x32_bf16 v[58:61], v[170:173], v[194:197], v[58:61]
	v_mfma_f32_16x16x32_bf16 v[54:57], v[158:161], v[202:205], v[54:57]
	v_mfma_f32_16x16x32_bf16 v[46:49], v[170:173], v[202:205], v[46:49]
	v_mfma_f32_16x16x32_bf16 v[38:41], v[158:161], v[210:213], v[38:41]
	v_mfma_f32_16x16x32_bf16 v[30:33], v[170:173], v[210:213], v[30:33]
	v_mfma_f32_16x16x32_bf16 v[22:25], v[158:161], v[218:221], v[22:25]
	v_mfma_f32_16x16x32_bf16 v[14:17], v[170:173], v[218:221], v[14:17]
	v_mfma_f32_16x16x32_bf16 v[50:53], v[174:177], v[190:193], v[50:53]
	v_mfma_f32_16x16x32_bf16 v[42:45], v[182:185], v[190:193], v[42:45]
	v_mfma_f32_16x16x32_bf16 v[34:37], v[174:177], v[198:201], v[34:37]
	v_mfma_f32_16x16x32_bf16 v[26:29], v[182:185], v[198:201], v[26:29]
	v_mfma_f32_16x16x32_bf16 v[18:21], v[174:177], v[206:209], v[18:21]
	v_mfma_f32_16x16x32_bf16 v[10:13], v[182:185], v[206:209], v[10:13]
	v_mfma_f32_16x16x32_bf16 v[6:9], v[174:177], v[214:217], v[6:9]
	v_mfma_f32_16x16x32_bf16 v[2:5], v[182:185], v[214:217], v[2:5]
	v_mfma_f32_16x16x32_bf16 v[50:53], v[178:181], v[194:197], v[50:53]
	v_mfma_f32_16x16x32_bf16 v[42:45], v[186:189], v[194:197], v[42:45]
	v_mfma_f32_16x16x32_bf16 v[34:37], v[178:181], v[202:205], v[34:37]
	v_mfma_f32_16x16x32_bf16 v[26:29], v[186:189], v[202:205], v[26:29]
	v_mfma_f32_16x16x32_bf16 v[18:21], v[178:181], v[210:213], v[18:21]
	v_mfma_f32_16x16x32_bf16 v[10:13], v[186:189], v[210:213], v[10:13]
	v_mfma_f32_16x16x32_bf16 v[6:9], v[178:181], v[218:221], v[6:9]
	v_mfma_f32_16x16x32_bf16 v[2:5], v[186:189], v[218:221], v[2:5]
	s_setprio 0
	s_barrier
	s_add_i32 s53, s53, 2
	s_add_u32 s22, s22, 0x100
	s_addc_u32 s23, s23, 0
	s_add_u32 s51, s51, 0x100
	s_addc_u32 s52, s52, 0
	s_cmpk_gt_u32 s53, 0x55
	s_cbranch_scc0 .LBB0_2579
	s_and_b64 vcc, exec, s[12:13]
	s_cbranch_vccz .LBB0_2582
	s_barrier

.LBB0_3015:
	ds_read_b128 v[146:149], v151
	ds_read_b128 v[156:159], v151 offset:1024
	ds_read_b128 v[160:163], v151 offset:2048
	ds_read_b128 v[170:173], v151 offset:3072
	ds_read_b128 v[174:177], v152
	ds_read_b128 v[178:181], v152 offset:1024
	ds_read_b128 v[182:185], v152 offset:2048
	ds_read_b128 v[186:189], v152 offset:3072
	s_add_u32 s30, s28, 0xfff80080
	s_addc_u32 s31, s29, -1
	s_cmp_eq_u32 s52, 28
	s_cselect_b32 s35, s21, s31
	s_cselect_b32 s34, s48, s30
	s_cselect_b32 s31, s17, s51
	s_cselect_b32 s30, s49, s50
	v_lshl_add_u64 v[164:165], s[28:29], 0, v[138:139]
	s_add_i32 m0, s27, 0xc000
	ds_read_b128 v[190:193], v153
	ds_read_b128 v[194:197], v153 offset:1024
	ds_read_b128 v[198:201], v153 offset:2048
	ds_read_b128 v[202:205], v153 offset:3072
	ds_read_b128 v[206:209], v153 offset:4096
	ds_read_b128 v[210:213], v153 offset:5120
	ds_read_b128 v[214:217], v153 offset:6144
	ds_read_b128 v[218:221], v153 offset:7168
	global_load_lds_dwordx4 v[164:165], off
	v_lshl_add_u64 v[164:165], s[28:29], 0, v[140:141]
	s_add_i32 m0, s27, 0xe000
	s_nop 0
	global_load_lds_dwordx4 v[164:165], off
	s_waitcnt vmcnt(8)
	s_waitcnt lgkmcnt(0)
	s_barrier
	s_setprio 1
	v_mfma_f32_16x16x32_bf16 v[126:129], v[146:149], v[190:193], v[126:129]
	v_mfma_f32_16x16x32_bf16 v[122:125], v[160:163], v[190:193], v[122:125]
	v_mfma_f32_16x16x32_bf16 v[110:113], v[146:149], v[198:201], v[110:113]
	v_mfma_f32_16x16x32_bf16 v[106:109], v[160:163], v[198:201], v[106:109]
	v_mfma_f32_16x16x32_bf16 v[94:97], v[146:149], v[206:209], v[94:97]
	v_mfma_f32_16x16x32_bf16 v[90:93], v[160:163], v[206:209], v[90:93]
	v_mfma_f32_16x16x32_bf16 v[78:81], v[146:149], v[214:217], v[78:81]
	v_mfma_f32_16x16x32_bf16 v[74:77], v[160:163], v[214:217], v[74:77]
	v_mfma_f32_16x16x32_bf16 v[126:129], v[156:159], v[194:197], v[126:129]
	v_mfma_f32_16x16x32_bf16 v[122:125], v[170:173], v[194:197], v[122:125]
	v_mfma_f32_16x16x32_bf16 v[110:113], v[156:159], v[202:205], v[110:113]
	v_mfma_f32_16x16x32_bf16 v[106:109], v[170:173], v[202:205], v[106:109]
	v_mfma_f32_16x16x32_bf16 v[94:97], v[156:159], v[210:213], v[94:97]
	v_mfma_f32_16x16x32_bf16 v[90:93], v[170:173], v[210:213], v[90:93]
	v_mfma_f32_16x16x32_bf16 v[78:81], v[156:159], v[218:221], v[78:81]
	v_mfma_f32_16x16x32_bf16 v[74:77], v[170:173], v[218:221], v[74:77]
	v_mfma_f32_16x16x32_bf16 v[118:121], v[174:177], v[190:193], v[118:121]
	v_mfma_f32_16x16x32_bf16 v[114:117], v[182:185], v[190:193], v[114:117]
	v_mfma_f32_16x16x32_bf16 v[102:105], v[174:177], v[198:201], v[102:105]
	v_mfma_f32_16x16x32_bf16 v[98:101], v[182:185], v[198:201], v[98:101]
	v_mfma_f32_16x16x32_bf16 v[86:89], v[174:177], v[206:209], v[86:89]
	v_mfma_f32_16x16x32_bf16 v[82:85], v[182:185], v[206:209], v[82:85]
	v_mfma_f32_16x16x32_bf16 v[70:73], v[174:177], v[214:217], v[70:73]
	v_mfma_f32_16x16x32_bf16 v[66:69], v[182:185], v[214:217], v[66:69]
	v_mfma_f32_16x16x32_bf16 v[118:121], v[178:181], v[194:197], v[118:121]
	v_mfma_f32_16x16x32_bf16 v[114:117], v[186:189], v[194:197], v[114:117]
	v_mfma_f32_16x16x32_bf16 v[102:105], v[178:181], v[202:205], v[102:105]
	v_mfma_f32_16x16x32_bf16 v[98:101], v[186:189], v[202:205], v[98:101]
	v_mfma_f32_16x16x32_bf16 v[86:89], v[178:181], v[210:213], v[86:89]
	v_mfma_f32_16x16x32_bf16 v[82:85], v[186:189], v[210:213], v[82:85]
	v_mfma_f32_16x16x32_bf16 v[70:73], v[178:181], v[218:221], v[70:73]
	v_mfma_f32_16x16x32_bf16 v[66:69], v[186:189], v[218:221], v[66:69]
	s_setprio 0
	s_barrier
	s_add_i32 s53, s43, s15
	v_lshl_add_u64 v[164:165], s[30:31], 0, v[132:133]
	s_mov_b32 m0, s53
	ds_read_b128 v[190:193], v153 offset:16384
	ds_read_b128 v[194:197], v153 offset:17408
	ds_read_b128 v[198:201], v153 offset:18432
	ds_read_b128 v[202:205], v153 offset:19456
	ds_read_b128 v[206:209], v153 offset:20480
	ds_read_b128 v[210:213], v153 offset:21504
	ds_read_b128 v[214:217], v153 offset:22528
	ds_read_b128 v[218:221], v153 offset:23552
	global_load_lds_dwordx4 v[164:165], off
	s_add_i32 m0, s53, 0x2000
	s_add_u32 s54, s30, 0x80000
	v_lshl_add_u64 v[222:223], s[30:31], 0, v[136:137]
	s_addc_u32 s55, s31, 0
	s_add_i32 s53, s44, s15
	global_load_lds_dwordx4 v[222:223], off
	v_lshl_add_u64 v[224:225], s[54:55], 0, v[132:133]
	s_mov_b32 m0, s53
	v_lshl_add_u64 v[226:227], s[34:35], 0, v[134:135]
	global_load_lds_dwordx4 v[224:225], off
	v_lshl_add_u64 v[224:225], s[54:55], 0, v[136:137]
	s_add_i32 m0, s53, 0x2000
	s_nop 0
	global_load_lds_dwordx4 v[224:225], off
	v_lshl_add_u64 v[224:225], s[34:35], 0, v[130:131]
	s_mov_b32 m0, s27
	s_nop 0
	global_load_lds_dwordx4 v[224:225], off
	s_mov_b32 m0, s36
	s_nop 0
	global_load_lds_dwordx4 v[226:227], off
	s_waitcnt vmcnt(8)
	s_waitcnt lgkmcnt(0)
	s_barrier
	s_setprio 1
	v_mfma_f32_16x16x32_bf16 v[62:65], v[146:149], v[190:193], v[62:65]
	v_mfma_f32_16x16x32_bf16 v[58:61], v[160:163], v[190:193], v[58:61]
	v_mfma_f32_16x16x32_bf16 v[46:49], v[146:149], v[198:201], v[46:49]
	v_mfma_f32_16x16x32_bf16 v[42:45], v[160:163], v[198:201], v[42:45]
	v_mfma_f32_16x16x32_bf16 v[30:33], v[146:149], v[206:209], v[30:33]
	v_mfma_f32_16x16x32_bf16 v[26:29], v[160:163], v[206:209], v[26:29]
	v_mfma_f32_16x16x32_bf16 v[14:17], v[146:149], v[214:217], v[14:17]
	v_mfma_f32_16x16x32_bf16 v[10:13], v[160:163], v[214:217], v[10:13]
	v_mfma_f32_16x16x32_bf16 v[62:65], v[156:159], v[194:197], v[62:65]
	v_mfma_f32_16x16x32_bf16 v[58:61], v[170:173], v[194:197], v[58:61]
	v_mfma_f32_16x16x32_bf16 v[46:49], v[156:159], v[202:205], v[46:49]
	v_mfma_f32_16x16x32_bf16 v[42:45], v[170:173], v[202:205], v[42:45]
	v_mfma_f32_16x16x32_bf16 v[30:33], v[156:159], v[210:213], v[30:33]
	v_mfma_f32_16x16x32_bf16 v[26:29], v[170:173], v[210:213], v[26:29]
	v_mfma_f32_16x16x32_bf16 v[14:17], v[156:159], v[218:221], v[14:17]
	v_mfma_f32_16x16x32_bf16 v[10:13], v[170:173], v[218:221], v[10:13]
	v_mfma_f32_16x16x32_bf16 v[54:57], v[174:177], v[190:193], v[54:57]
	v_mfma_f32_16x16x32_bf16 v[50:53], v[182:185], v[190:193], v[50:53]
	v_mfma_f32_16x16x32_bf16 v[38:41], v[174:177], v[198:201], v[38:41]
	v_mfma_f32_16x16x32_bf16 v[34:37], v[182:185], v[198:201], v[34:37]
	v_mfma_f32_16x16x32_bf16 v[22:25], v[174:177], v[206:209], v[22:25]
	v_mfma_f32_16x16x32_bf16 v[18:21], v[182:185], v[206:209], v[18:21]
	v_mfma_f32_16x16x32_bf16 v[6:9], v[174:177], v[214:217], v[6:9]
	v_mfma_f32_16x16x32_bf16 v[2:5], v[182:185], v[214:217], v[2:5]
	v_mfma_f32_16x16x32_bf16 v[54:57], v[178:181], v[194:197], v[54:57]
	v_mfma_f32_16x16x32_bf16 v[50:53], v[186:189], v[194:197], v[50:53]
	v_mfma_f32_16x16x32_bf16 v[38:41], v[178:181], v[202:205], v[38:41]
	v_mfma_f32_16x16x32_bf16 v[34:37], v[186:189], v[202:205], v[34:37]
	v_mfma_f32_16x16x32_bf16 v[22:25], v[178:181], v[210:213], v[22:25]
	v_mfma_f32_16x16x32_bf16 v[18:21], v[186:189], v[210:213], v[18:21]
	v_mfma_f32_16x16x32_bf16 v[6:9], v[178:181], v[218:221], v[6:9]
	v_mfma_f32_16x16x32_bf16 v[2:5], v[186:189], v[218:221], v[2:5]
	s_setprio 0
	s_barrier
	ds_read_b128 v[146:149], v154
	ds_read_b128 v[156:159], v154 offset:1024
	ds_read_b128 v[160:163], v154 offset:2048
	ds_read_b128 v[170:173], v154 offset:3072
	ds_read_b128 v[174:177], v155
	ds_read_b128 v[178:181], v155 offset:1024
	ds_read_b128 v[182:185], v155 offset:2048
	ds_read_b128 v[186:189], v155 offset:3072
	s_add_u32 s34, s34, 0x80000
	s_addc_u32 s35, s35, 0
	s_mov_b32 m0, s37
	v_lshl_add_u64 v[228:229], s[34:35], 0, v[130:131]
	ds_read_b128 v[190:193], v153 offset:32768
	ds_read_b128 v[194:197], v153 offset:33792
	ds_read_b128 v[198:201], v153 offset:34816
	ds_read_b128 v[202:205], v153 offset:35840
	ds_read_b128 v[206:209], v153 offset:36864
	ds_read_b128 v[210:213], v153 offset:37888
	ds_read_b128 v[214:217], v153 offset:38912
	ds_read_b128 v[218:221], v153 offset:39936
	global_load_lds_dwordx4 v[228:229], off
	v_lshl_add_u64 v[228:229], s[34:35], 0, v[134:135]
	s_mov_b32 m0, s38
	s_nop 0
	global_load_lds_dwordx4 v[228:229], off
	s_waitcnt vmcnt(8)
	s_waitcnt lgkmcnt(0)
	s_barrier
	s_setprio 1
	v_mfma_f32_16x16x32_bf16 v[126:129], v[146:149], v[190:193], v[126:129]
	v_mfma_f32_16x16x32_bf16 v[122:125], v[160:163], v[190:193], v[122:125]
	v_mfma_f32_16x16x32_bf16 v[110:113], v[146:149], v[198:201], v[110:113]
	v_mfma_f32_16x16x32_bf16 v[106:109], v[160:163], v[198:201], v[106:109]
	v_mfma_f32_16x16x32_bf16 v[94:97], v[146:149], v[206:209], v[94:97]
	v_mfma_f32_16x16x32_bf16 v[90:93], v[160:163], v[206:209], v[90:93]
	v_mfma_f32_16x16x32_bf16 v[78:81], v[146:149], v[214:217], v[78:81]
	v_mfma_f32_16x16x32_bf16 v[74:77], v[160:163], v[214:217], v[74:77]
	v_mfma_f32_16x16x32_bf16 v[126:129], v[156:159], v[194:197], v[126:129]
	v_mfma_f32_16x16x32_bf16 v[122:125], v[170:173], v[194:197], v[122:125]
	v_mfma_f32_16x16x32_bf16 v[110:113], v[156:159], v[202:205], v[110:113]
	v_mfma_f32_16x16x32_bf16 v[106:109], v[170:173], v[202:205], v[106:109]
	v_mfma_f32_16x16x32_bf16 v[94:97], v[156:159], v[210:213], v[94:97]
	v_mfma_f32_16x16x32_bf16 v[90:93], v[170:173], v[210:213], v[90:93]
	v_mfma_f32_16x16x32_bf16 v[78:81], v[156:159], v[218:221], v[78:81]
	v_mfma_f32_16x16x32_bf16 v[74:77], v[170:173], v[218:221], v[74:77]
	v_mfma_f32_16x16x32_bf16 v[118:121], v[174:177], v[190:193], v[118:121]
	v_mfma_f32_16x16x32_bf16 v[114:117], v[182:185], v[190:193], v[114:117]
	v_mfma_f32_16x16x32_bf16 v[102:105], v[174:177], v[198:201], v[102:105]
	v_mfma_f32_16x16x32_bf16 v[98:101], v[182:185], v[198:201], v[98:101]
	v_mfma_f32_16x16x32_bf16 v[86:89], v[174:177], v[206:209], v[86:89]
	v_mfma_f32_16x16x32_bf16 v[82:85], v[182:185], v[206:209], v[82:85]
	v_mfma_f32_16x16x32_bf16 v[70:73], v[174:177], v[214:217], v[70:73]
	v_mfma_f32_16x16x32_bf16 v[66:69], v[182:185], v[214:217], v[66:69]
	v_mfma_f32_16x16x32_bf16 v[118:121], v[178:181], v[194:197], v[118:121]
	v_mfma_f32_16x16x32_bf16 v[114:117], v[186:189], v[194:197], v[114:117]
	v_mfma_f32_16x16x32_bf16 v[102:105], v[178:181], v[202:205], v[102:105]
	v_mfma_f32_16x16x32_bf16 v[98:101], v[186:189], v[202:205], v[98:101]
	v_mfma_f32_16x16x32_bf16 v[86:89], v[178:181], v[210:213], v[86:89]
	v_mfma_f32_16x16x32_bf16 v[82:85], v[186:189], v[210:213], v[82:85]
	v_mfma_f32_16x16x32_bf16 v[70:73], v[178:181], v[218:221], v[70:73]
	v_mfma_f32_16x16x32_bf16 v[66:69], v[186:189], v[218:221], v[66:69]
	s_setprio 0
	s_barrier
	s_add_i32 s34, s45, s15
	v_lshl_add_u64 v[164:165], v[164:165], 0, s[4:5]
	s_mov_b32 m0, s34
	ds_read_b128 v[190:193], v153 offset:49152
	ds_read_b128 v[194:197], v153 offset:50176
	ds_read_b128 v[198:201], v153 offset:51200
	ds_read_b128 v[202:205], v153 offset:52224
	ds_read_b128 v[206:209], v153 offset:53248
	ds_read_b128 v[210:213], v153 offset:54272
	ds_read_b128 v[214:217], v153 offset:55296
	ds_read_b128 v[218:221], v153 offset:56320
	global_load_lds_dwordx4 v[164:165], off
	s_add_i32 m0, s34, 0x2000
	s_add_u32 s30, s30, 0x80080
	v_lshl_add_u64 v[164:165], v[222:223], 0, s[4:5]
	s_addc_u32 s31, s31, 0
	s_add_i32 s34, s46, s15
	global_load_lds_dwordx4 v[164:165], off
	v_lshl_add_u64 v[164:165], s[30:31], 0, v[132:133]
	s_mov_b32 m0, s34
	s_nop 0
	global_load_lds_dwordx4 v[164:165], off
	v_lshl_add_u64 v[164:165], s[30:31], 0, v[136:137]
	s_add_i32 m0, s34, 0x2000
	s_nop 0
	global_load_lds_dwordx4 v[164:165], off
	v_lshl_add_u64 v[164:165], v[224:225], 0, s[4:5]
	s_mov_b32 m0, s39
	s_nop 0
	global_load_lds_dwordx4 v[164:165], off
	v_lshl_add_u64 v[164:165], v[226:227], 0, s[4:5]
	s_mov_b32 m0, s40
	s_nop 0
	global_load_lds_dwordx4 v[164:165], off
	s_waitcnt vmcnt(8)
	s_waitcnt lgkmcnt(0)
	s_barrier
	s_setprio 1
	v_mfma_f32_16x16x32_bf16 v[62:65], v[146:149], v[190:193], v[62:65]
	v_mfma_f32_16x16x32_bf16 v[58:61], v[160:163], v[190:193], v[58:61]
	v_mfma_f32_16x16x32_bf16 v[46:49], v[146:149], v[198:201], v[46:49]
	v_mfma_f32_16x16x32_bf16 v[42:45], v[160:163], v[198:201], v[42:45]
	v_mfma_f32_16x16x32_bf16 v[30:33], v[146:149], v[206:209], v[30:33]
	v_mfma_f32_16x16x32_bf16 v[26:29], v[160:163], v[206:209], v[26:29]
	v_mfma_f32_16x16x32_bf16 v[14:17], v[146:149], v[214:217], v[14:17]
	v_mfma_f32_16x16x32_bf16 v[10:13], v[160:163], v[214:217], v[10:13]
	v_mfma_f32_16x16x32_bf16 v[62:65], v[156:159], v[194:197], v[62:65]
	v_mfma_f32_16x16x32_bf16 v[58:61], v[170:173], v[194:197], v[58:61]
	v_mfma_f32_16x16x32_bf16 v[46:49], v[156:159], v[202:205], v[46:49]
	v_mfma_f32_16x16x32_bf16 v[42:45], v[170:173], v[202:205], v[42:45]
	v_mfma_f32_16x16x32_bf16 v[30:33], v[156:159], v[210:213], v[30:33]
	v_mfma_f32_16x16x32_bf16 v[26:29], v[170:173], v[210:213], v[26:29]
	v_mfma_f32_16x16x32_bf16 v[14:17], v[156:159], v[218:221], v[14:17]
	v_mfma_f32_16x16x32_bf16 v[10:13], v[170:173], v[218:221], v[10:13]
	v_mfma_f32_16x16x32_bf16 v[54:57], v[174:177], v[190:193], v[54:57]
	v_mfma_f32_16x16x32_bf16 v[50:53], v[182:185], v[190:193], v[50:53]
	v_mfma_f32_16x16x32_bf16 v[38:41], v[174:177], v[198:201], v[38:41]
	v_mfma_f32_16x16x32_bf16 v[34:37], v[182:185], v[198:201], v[34:37]
	v_mfma_f32_16x16x32_bf16 v[22:25], v[174:177], v[206:209], v[22:25]
	v_mfma_f32_16x16x32_bf16 v[18:21], v[182:185], v[206:209], v[18:21]
	v_mfma_f32_16x16x32_bf16 v[6:9], v[174:177], v[214:217], v[6:9]
	v_mfma_f32_16x16x32_bf16 v[2:5], v[182:185], v[214:217], v[2:5]
	v_mfma_f32_16x16x32_bf16 v[54:57], v[178:181], v[194:197], v[54:57]
	v_mfma_f32_16x16x32_bf16 v[50:53], v[186:189], v[194:197], v[50:53]
	v_mfma_f32_16x16x32_bf16 v[38:41], v[178:181], v[202:205], v[38:41]
	v_mfma_f32_16x16x32_bf16 v[34:37], v[186:189], v[202:205], v[34:37]
	v_mfma_f32_16x16x32_bf16 v[22:25], v[178:181], v[210:213], v[22:25]
	v_mfma_f32_16x16x32_bf16 v[18:21], v[186:189], v[210:213], v[18:21]
	v_mfma_f32_16x16x32_bf16 v[6:9], v[178:181], v[218:221], v[6:9]
	v_mfma_f32_16x16x32_bf16 v[2:5], v[186:189], v[218:221], v[2:5]
	s_setprio 0
	s_barrier
	s_add_i32 s52, s52, 2
	s_add_u32 s28, s28, 0x100
	s_addc_u32 s29, s29, 0
	s_add_u32 s50, s50, 0x100
	s_addc_u32 s51, s51, 0
	s_cmp_gt_u32 s52, 29
	s_cbranch_scc0 .LBB0_3015
	s_and_b64 vcc, exec, s[10:11]
	s_cbranch_vccz .LBB0_3018
	s_barrier

.LBB0_3225:
	ds_read_b128 v[154:157], v149
	ds_read_b128 v[158:161], v149 offset:1024
	ds_read_b128 v[162:165], v149 offset:2048
	ds_read_b128 v[170:173], v149 offset:3072
	ds_read_b128 v[174:177], v150
	ds_read_b128 v[178:181], v150 offset:1024
	ds_read_b128 v[182:185], v150 offset:2048
	ds_read_b128 v[186:189], v150 offset:3072
	s_add_u32 s34, s30, 0xfff80080
	s_addc_u32 s35, s31, -1
	s_cmp_eq_u32 s67, 28
	s_cselect_b32 s37, s23, s35
	s_cselect_b32 s36, s56, s34
	s_cselect_b32 s35, s21, s66
	s_cselect_b32 s34, s57, s63
	v_lshl_add_u64 v[146:147], s[30:31], 0, v[138:139]
	s_add_i32 m0, s29, 0xc000
	ds_read_b128 v[190:193], v151
	ds_read_b128 v[194:197], v151 offset:1024
	ds_read_b128 v[198:201], v151 offset:2048
	ds_read_b128 v[202:205], v151 offset:3072
	ds_read_b128 v[206:209], v151 offset:4096
	ds_read_b128 v[210:213], v151 offset:5120
	ds_read_b128 v[214:217], v151 offset:6144
	ds_read_b128 v[218:221], v151 offset:7168
	global_load_lds_dwordx4 v[146:147], off
	v_lshl_add_u64 v[146:147], s[30:31], 0, v[140:141]
	s_add_i32 m0, s29, 0xe000
	s_nop 0
	global_load_lds_dwordx4 v[146:147], off
	s_waitcnt vmcnt(8)
	s_waitcnt lgkmcnt(0)
	s_barrier
	s_setprio 1
	v_mfma_f32_16x16x32_bf16 v[126:129], v[154:157], v[190:193], v[126:129]
	v_mfma_f32_16x16x32_bf16 v[122:125], v[162:165], v[190:193], v[122:125]
	v_mfma_f32_16x16x32_bf16 v[118:121], v[154:157], v[198:201], v[118:121]
	v_mfma_f32_16x16x32_bf16 v[110:113], v[162:165], v[198:201], v[110:113]
	v_mfma_f32_16x16x32_bf16 v[102:105], v[154:157], v[206:209], v[102:105]
	v_mfma_f32_16x16x32_bf16 v[94:97], v[162:165], v[206:209], v[94:97]
	v_mfma_f32_16x16x32_bf16 v[86:89], v[154:157], v[214:217], v[86:89]
	v_mfma_f32_16x16x32_bf16 v[78:81], v[162:165], v[214:217], v[78:81]
	v_mfma_f32_16x16x32_bf16 v[126:129], v[158:161], v[194:197], v[126:129]
	v_mfma_f32_16x16x32_bf16 v[122:125], v[170:173], v[194:197], v[122:125]
	v_mfma_f32_16x16x32_bf16 v[118:121], v[158:161], v[202:205], v[118:121]
	v_mfma_f32_16x16x32_bf16 v[110:113], v[170:173], v[202:205], v[110:113]
	v_mfma_f32_16x16x32_bf16 v[102:105], v[158:161], v[210:213], v[102:105]
	v_mfma_f32_16x16x32_bf16 v[94:97], v[170:173], v[210:213], v[94:97]
	v_mfma_f32_16x16x32_bf16 v[86:89], v[158:161], v[218:221], v[86:89]
	v_mfma_f32_16x16x32_bf16 v[78:81], v[170:173], v[218:221], v[78:81]
	v_mfma_f32_16x16x32_bf16 v[114:117], v[174:177], v[190:193], v[114:117]
	v_mfma_f32_16x16x32_bf16 v[106:109], v[182:185], v[190:193], v[106:109]
	v_mfma_f32_16x16x32_bf16 v[98:101], v[174:177], v[198:201], v[98:101]
	v_mfma_f32_16x16x32_bf16 v[90:93], v[182:185], v[198:201], v[90:93]
	v_mfma_f32_16x16x32_bf16 v[82:85], v[174:177], v[206:209], v[82:85]
	v_mfma_f32_16x16x32_bf16 v[74:77], v[182:185], v[206:209], v[74:77]
	v_mfma_f32_16x16x32_bf16 v[70:73], v[174:177], v[214:217], v[70:73]
	v_mfma_f32_16x16x32_bf16 v[66:69], v[182:185], v[214:217], v[66:69]
	v_mfma_f32_16x16x32_bf16 v[114:117], v[178:181], v[194:197], v[114:117]
	v_mfma_f32_16x16x32_bf16 v[106:109], v[186:189], v[194:197], v[106:109]
	v_mfma_f32_16x16x32_bf16 v[98:101], v[178:181], v[202:205], v[98:101]
	v_mfma_f32_16x16x32_bf16 v[90:93], v[186:189], v[202:205], v[90:93]
	v_mfma_f32_16x16x32_bf16 v[82:85], v[178:181], v[210:213], v[82:85]
	v_mfma_f32_16x16x32_bf16 v[74:77], v[186:189], v[210:213], v[74:77]
	v_mfma_f32_16x16x32_bf16 v[70:73], v[178:181], v[218:221], v[70:73]
	v_mfma_f32_16x16x32_bf16 v[66:69], v[186:189], v[218:221], v[66:69]
	s_setprio 0
	s_barrier
	s_add_i32 s68, s47, s39
	v_lshl_add_u64 v[146:147], s[34:35], 0, v[132:133]
	s_mov_b32 m0, s68
	ds_read_b128 v[190:193], v151 offset:16384
	ds_read_b128 v[194:197], v151 offset:17408
	ds_read_b128 v[198:201], v151 offset:18432
	ds_read_b128 v[202:205], v151 offset:19456
	ds_read_b128 v[206:209], v151 offset:20480
	ds_read_b128 v[210:213], v151 offset:21504
	ds_read_b128 v[214:217], v151 offset:22528
	ds_read_b128 v[218:221], v151 offset:23552
	global_load_lds_dwordx4 v[146:147], off
	s_add_i32 m0, s68, 0x2000
	s_add_u32 s68, s34, 0x80000
	v_lshl_add_u64 v[222:223], s[34:35], 0, v[136:137]
	s_addc_u32 s69, s35, 0
	s_add_i32 s70, s48, s39
	global_load_lds_dwordx4 v[222:223], off
	v_lshl_add_u64 v[224:225], s[68:69], 0, v[132:133]
	s_mov_b32 m0, s70
	v_lshl_add_u64 v[226:227], s[36:37], 0, v[134:135]
	global_load_lds_dwordx4 v[224:225], off
	v_lshl_add_u64 v[224:225], s[68:69], 0, v[136:137]
	s_add_i32 m0, s70, 0x2000
	s_nop 0
	global_load_lds_dwordx4 v[224:225], off
	v_lshl_add_u64 v[224:225], s[36:37], 0, v[130:131]
	s_mov_b32 m0, s29
	s_nop 0
	global_load_lds_dwordx4 v[224:225], off
	s_mov_b32 m0, s40
	s_nop 0
	global_load_lds_dwordx4 v[226:227], off
	s_waitcnt vmcnt(8)
	s_waitcnt lgkmcnt(0)
	s_barrier
	s_setprio 1
	v_mfma_f32_16x16x32_bf16 v[62:65], v[154:157], v[190:193], v[62:65]
	v_mfma_f32_16x16x32_bf16 v[58:61], v[162:165], v[190:193], v[58:61]
	v_mfma_f32_16x16x32_bf16 v[54:57], v[154:157], v[198:201], v[54:57]
	v_mfma_f32_16x16x32_bf16 v[46:49], v[162:165], v[198:201], v[46:49]
	v_mfma_f32_16x16x32_bf16 v[38:41], v[154:157], v[206:209], v[38:41]
	v_mfma_f32_16x16x32_bf16 v[30:33], v[162:165], v[206:209], v[30:33]
	v_mfma_f32_16x16x32_bf16 v[22:25], v[154:157], v[214:217], v[22:25]
	v_mfma_f32_16x16x32_bf16 v[14:17], v[162:165], v[214:217], v[14:17]
	v_mfma_f32_16x16x32_bf16 v[62:65], v[158:161], v[194:197], v[62:65]
	v_mfma_f32_16x16x32_bf16 v[58:61], v[170:173], v[194:197], v[58:61]
	v_mfma_f32_16x16x32_bf16 v[54:57], v[158:161], v[202:205], v[54:57]
	v_mfma_f32_16x16x32_bf16 v[46:49], v[170:173], v[202:205], v[46:49]
	v_mfma_f32_16x16x32_bf16 v[38:41], v[158:161], v[210:213], v[38:41]
	v_mfma_f32_16x16x32_bf16 v[30:33], v[170:173], v[210:213], v[30:33]
	v_mfma_f32_16x16x32_bf16 v[22:25], v[158:161], v[218:221], v[22:25]
	v_mfma_f32_16x16x32_bf16 v[14:17], v[170:173], v[218:221], v[14:17]
	v_mfma_f32_16x16x32_bf16 v[50:53], v[174:177], v[190:193], v[50:53]
	v_mfma_f32_16x16x32_bf16 v[42:45], v[182:185], v[190:193], v[42:45]
	v_mfma_f32_16x16x32_bf16 v[34:37], v[174:177], v[198:201], v[34:37]
	v_mfma_f32_16x16x32_bf16 v[26:29], v[182:185], v[198:201], v[26:29]
	v_mfma_f32_16x16x32_bf16 v[18:21], v[174:177], v[206:209], v[18:21]
	v_mfma_f32_16x16x32_bf16 v[10:13], v[182:185], v[206:209], v[10:13]
	v_mfma_f32_16x16x32_bf16 v[6:9], v[174:177], v[214:217], v[6:9]
	v_mfma_f32_16x16x32_bf16 v[2:5], v[182:185], v[214:217], v[2:5]
	v_mfma_f32_16x16x32_bf16 v[50:53], v[178:181], v[194:197], v[50:53]
	v_mfma_f32_16x16x32_bf16 v[42:45], v[186:189], v[194:197], v[42:45]
	v_mfma_f32_16x16x32_bf16 v[34:37], v[178:181], v[202:205], v[34:37]
	v_mfma_f32_16x16x32_bf16 v[26:29], v[186:189], v[202:205], v[26:29]
	v_mfma_f32_16x16x32_bf16 v[18:21], v[178:181], v[210:213], v[18:21]
	v_mfma_f32_16x16x32_bf16 v[10:13], v[186:189], v[210:213], v[10:13]
	v_mfma_f32_16x16x32_bf16 v[6:9], v[178:181], v[218:221], v[6:9]
	v_mfma_f32_16x16x32_bf16 v[2:5], v[186:189], v[218:221], v[2:5]
	s_setprio 0
	s_barrier
	ds_read_b128 v[154:157], v152
	ds_read_b128 v[158:161], v152 offset:1024
	ds_read_b128 v[162:165], v152 offset:2048
	ds_read_b128 v[170:173], v152 offset:3072
	ds_read_b128 v[174:177], v153
	ds_read_b128 v[178:181], v153 offset:1024
	ds_read_b128 v[182:185], v153 offset:2048
	ds_read_b128 v[186:189], v153 offset:3072
	s_add_u32 s36, s36, 0x80000
	s_addc_u32 s37, s37, 0
	s_mov_b32 m0, s41
	v_lshl_add_u64 v[228:229], s[36:37], 0, v[130:131]
	ds_read_b128 v[190:193], v151 offset:32768
	ds_read_b128 v[194:197], v151 offset:33792
	ds_read_b128 v[198:201], v151 offset:34816
	ds_read_b128 v[202:205], v151 offset:35840
	ds_read_b128 v[206:209], v151 offset:36864
	ds_read_b128 v[210:213], v151 offset:37888
	ds_read_b128 v[214:217], v151 offset:38912
	ds_read_b128 v[218:221], v151 offset:39936
	global_load_lds_dwordx4 v[228:229], off
	v_lshl_add_u64 v[228:229], s[36:37], 0, v[134:135]
	s_mov_b32 m0, s42
	s_nop 0
	global_load_lds_dwordx4 v[228:229], off
	s_waitcnt vmcnt(8)
	s_waitcnt lgkmcnt(0)
	s_barrier
	s_setprio 1
	v_mfma_f32_16x16x32_bf16 v[126:129], v[154:157], v[190:193], v[126:129]
	v_mfma_f32_16x16x32_bf16 v[122:125], v[162:165], v[190:193], v[122:125]
	v_mfma_f32_16x16x32_bf16 v[118:121], v[154:157], v[198:201], v[118:121]
	v_mfma_f32_16x16x32_bf16 v[110:113], v[162:165], v[198:201], v[110:113]
	v_mfma_f32_16x16x32_bf16 v[102:105], v[154:157], v[206:209], v[102:105]
	v_mfma_f32_16x16x32_bf16 v[94:97], v[162:165], v[206:209], v[94:97]
	v_mfma_f32_16x16x32_bf16 v[86:89], v[154:157], v[214:217], v[86:89]
	v_mfma_f32_16x16x32_bf16 v[78:81], v[162:165], v[214:217], v[78:81]
	v_mfma_f32_16x16x32_bf16 v[126:129], v[158:161], v[194:197], v[126:129]
	v_mfma_f32_16x16x32_bf16 v[122:125], v[170:173], v[194:197], v[122:125]
	v_mfma_f32_16x16x32_bf16 v[118:121], v[158:161], v[202:205], v[118:121]
	v_mfma_f32_16x16x32_bf16 v[110:113], v[170:173], v[202:205], v[110:113]
	v_mfma_f32_16x16x32_bf16 v[102:105], v[158:161], v[210:213], v[102:105]
	v_mfma_f32_16x16x32_bf16 v[94:97], v[170:173], v[210:213], v[94:97]
	v_mfma_f32_16x16x32_bf16 v[86:89], v[158:161], v[218:221], v[86:89]
	v_mfma_f32_16x16x32_bf16 v[78:81], v[170:173], v[218:221], v[78:81]
	v_mfma_f32_16x16x32_bf16 v[114:117], v[174:177], v[190:193], v[114:117]
	v_mfma_f32_16x16x32_bf16 v[106:109], v[182:185], v[190:193], v[106:109]
	v_mfma_f32_16x16x32_bf16 v[98:101], v[174:177], v[198:201], v[98:101]
	v_mfma_f32_16x16x32_bf16 v[90:93], v[182:185], v[198:201], v[90:93]
	v_mfma_f32_16x16x32_bf16 v[82:85], v[174:177], v[206:209], v[82:85]
	v_mfma_f32_16x16x32_bf16 v[74:77], v[182:185], v[206:209], v[74:77]
	v_mfma_f32_16x16x32_bf16 v[70:73], v[174:177], v[214:217], v[70:73]
	v_mfma_f32_16x16x32_bf16 v[66:69], v[182:185], v[214:217], v[66:69]
	v_mfma_f32_16x16x32_bf16 v[114:117], v[178:181], v[194:197], v[114:117]
	v_mfma_f32_16x16x32_bf16 v[106:109], v[186:189], v[194:197], v[106:109]
	v_mfma_f32_16x16x32_bf16 v[98:101], v[178:181], v[202:205], v[98:101]
	v_mfma_f32_16x16x32_bf16 v[90:93], v[186:189], v[202:205], v[90:93]
	v_mfma_f32_16x16x32_bf16 v[82:85], v[178:181], v[210:213], v[82:85]
	v_mfma_f32_16x16x32_bf16 v[74:77], v[186:189], v[210:213], v[74:77]
	v_mfma_f32_16x16x32_bf16 v[70:73], v[178:181], v[218:221], v[70:73]
	v_mfma_f32_16x16x32_bf16 v[66:69], v[186:189], v[218:221], v[66:69]
	s_setprio 0
	s_barrier
	s_add_i32 s36, s49, s39
	v_lshl_add_u64 v[146:147], v[146:147], 0, s[6:7]
	s_mov_b32 m0, s36
	ds_read_b128 v[190:193], v151 offset:49152
	ds_read_b128 v[194:197], v151 offset:50176
	ds_read_b128 v[198:201], v151 offset:51200
	ds_read_b128 v[202:205], v151 offset:52224
	ds_read_b128 v[206:209], v151 offset:53248
	ds_read_b128 v[210:213], v151 offset:54272
	ds_read_b128 v[214:217], v151 offset:55296
	ds_read_b128 v[218:221], v151 offset:56320
	global_load_lds_dwordx4 v[146:147], off
	s_add_i32 m0, s36, 0x2000
	s_add_u32 s34, s34, 0x80080
	v_lshl_add_u64 v[146:147], v[222:223], 0, s[6:7]
	s_addc_u32 s35, s35, 0
	s_add_i32 s36, s50, s39
	global_load_lds_dwordx4 v[146:147], off
	v_lshl_add_u64 v[146:147], s[34:35], 0, v[132:133]
	s_mov_b32 m0, s36
	s_nop 0
	global_load_lds_dwordx4 v[146:147], off
	v_lshl_add_u64 v[146:147], s[34:35], 0, v[136:137]
	s_add_i32 m0, s36, 0x2000
	s_nop 0
	global_load_lds_dwordx4 v[146:147], off
	v_lshl_add_u64 v[146:147], v[224:225], 0, s[6:7]
	s_mov_b32 m0, s43
	s_nop 0
	global_load_lds_dwordx4 v[146:147], off
	v_lshl_add_u64 v[146:147], v[226:227], 0, s[6:7]
	s_mov_b32 m0, s44
	s_nop 0
	global_load_lds_dwordx4 v[146:147], off
	s_waitcnt vmcnt(8)
	s_waitcnt lgkmcnt(0)
	s_barrier
	s_setprio 1
	v_mfma_f32_16x16x32_bf16 v[62:65], v[154:157], v[190:193], v[62:65]
	v_mfma_f32_16x16x32_bf16 v[58:61], v[162:165], v[190:193], v[58:61]
	v_mfma_f32_16x16x32_bf16 v[54:57], v[154:157], v[198:201], v[54:57]
	v_mfma_f32_16x16x32_bf16 v[46:49], v[162:165], v[198:201], v[46:49]
	v_mfma_f32_16x16x32_bf16 v[38:41], v[154:157], v[206:209], v[38:41]
	v_mfma_f32_16x16x32_bf16 v[30:33], v[162:165], v[206:209], v[30:33]
	v_mfma_f32_16x16x32_bf16 v[22:25], v[154:157], v[214:217], v[22:25]
	v_mfma_f32_16x16x32_bf16 v[14:17], v[162:165], v[214:217], v[14:17]
	v_mfma_f32_16x16x32_bf16 v[62:65], v[158:161], v[194:197], v[62:65]
	v_mfma_f32_16x16x32_bf16 v[58:61], v[170:173], v[194:197], v[58:61]
	v_mfma_f32_16x16x32_bf16 v[54:57], v[158:161], v[202:205], v[54:57]
	v_mfma_f32_16x16x32_bf16 v[46:49], v[170:173], v[202:205], v[46:49]
	v_mfma_f32_16x16x32_bf16 v[38:41], v[158:161], v[210:213], v[38:41]
	v_mfma_f32_16x16x32_bf16 v[30:33], v[170:173], v[210:213], v[30:33]
	v_mfma_f32_16x16x32_bf16 v[22:25], v[158:161], v[218:221], v[22:25]
	v_mfma_f32_16x16x32_bf16 v[14:17], v[170:173], v[218:221], v[14:17]
	v_mfma_f32_16x16x32_bf16 v[50:53], v[174:177], v[190:193], v[50:53]
	v_mfma_f32_16x16x32_bf16 v[42:45], v[182:185], v[190:193], v[42:45]
	v_mfma_f32_16x16x32_bf16 v[34:37], v[174:177], v[198:201], v[34:37]
	v_mfma_f32_16x16x32_bf16 v[26:29], v[182:185], v[198:201], v[26:29]
	v_mfma_f32_16x16x32_bf16 v[18:21], v[174:177], v[206:209], v[18:21]
	v_mfma_f32_16x16x32_bf16 v[10:13], v[182:185], v[206:209], v[10:13]
	v_mfma_f32_16x16x32_bf16 v[6:9], v[174:177], v[214:217], v[6:9]
	v_mfma_f32_16x16x32_bf16 v[2:5], v[182:185], v[214:217], v[2:5]
	v_mfma_f32_16x16x32_bf16 v[50:53], v[178:181], v[194:197], v[50:53]
	v_mfma_f32_16x16x32_bf16 v[42:45], v[186:189], v[194:197], v[42:45]
	v_mfma_f32_16x16x32_bf16 v[34:37], v[178:181], v[202:205], v[34:37]
	v_mfma_f32_16x16x32_bf16 v[26:29], v[186:189], v[202:205], v[26:29]
	v_mfma_f32_16x16x32_bf16 v[18:21], v[178:181], v[210:213], v[18:21]
	v_mfma_f32_16x16x32_bf16 v[10:13], v[186:189], v[210:213], v[10:13]
	v_mfma_f32_16x16x32_bf16 v[6:9], v[178:181], v[218:221], v[6:9]
	v_mfma_f32_16x16x32_bf16 v[2:5], v[186:189], v[218:221], v[2:5]
	s_setprio 0
	s_barrier
	s_add_i32 s67, s67, 2
	s_add_u32 s30, s30, 0x100
	s_addc_u32 s31, s31, 0
	s_add_u32 s63, s63, 0x100
	s_addc_u32 s66, s66, 0
	s_cmp_gt_u32 s67, 29
	s_cbranch_scc0 .LBB0_3225
	s_and_b64 vcc, exec, s[12:13]
	s_cbranch_vccz .LBB0_3228
	s_barrier

.LBB0_3387:
	ds_read_b128 v[146:149], v177
	ds_read_b128 v[150:153], v177 offset:1024
	ds_read_b128 v[154:157], v177 offset:2048
	ds_read_b128 v[158:161], v177 offset:3072
	ds_read_b128 v[182:185], v178
	ds_read_b128 v[186:189], v178 offset:1024
	ds_read_b128 v[190:193], v178 offset:2048
	ds_read_b128 v[194:197], v178 offset:3072
	s_add_u32 s28, s26, 0xfffc0080
	s_addc_u32 s29, s27, -1
	s_cmp_eq_u32 s54, 12
	s_cselect_b32 s31, s19, s29
	s_cselect_b32 s30, s50, s28
	s_cselect_b32 s29, s17, s53
	s_cselect_b32 s28, s51, s52
	v_lshl_add_u64 v[162:163], s[26:27], 0, v[138:139]
	s_add_i32 m0, s25, 0xc000
	ds_read_b128 v[198:201], v179
	ds_read_b128 v[202:205], v179 offset:1024
	ds_read_b128 v[206:209], v179 offset:2048
	ds_read_b128 v[210:213], v179 offset:3072
	ds_read_b128 v[214:217], v179 offset:4096
	ds_read_b128 v[218:221], v179 offset:5120
	ds_read_b128 v[222:225], v179 offset:6144
	ds_read_b128 v[226:229], v179 offset:7168
	global_load_lds_dwordx4 v[162:163], off
	v_lshl_add_u64 v[162:163], s[26:27], 0, v[140:141]
	s_add_i32 m0, s25, 0xe000
	s_nop 0
	global_load_lds_dwordx4 v[162:163], off
	s_waitcnt vmcnt(8)
	s_waitcnt lgkmcnt(0)
	s_barrier
	s_setprio 1
	v_mfma_i32_16x16x64_i8 v[126:129], v[146:149], v[198:201], v[126:129]
	v_mfma_i32_16x16x64_i8 v[118:121], v[154:157], v[198:201], v[118:121]
	v_mfma_i32_16x16x64_i8 v[110:113], v[146:149], v[206:209], v[110:113]
	v_mfma_i32_16x16x64_i8 v[102:105], v[154:157], v[206:209], v[102:105]
	v_mfma_i32_16x16x64_i8 v[94:97], v[146:149], v[214:217], v[94:97]
	v_mfma_i32_16x16x64_i8 v[86:89], v[154:157], v[214:217], v[86:89]
	v_mfma_i32_16x16x64_i8 v[78:81], v[146:149], v[222:225], v[78:81]
	v_mfma_i32_16x16x64_i8 v[70:73], v[154:157], v[222:225], v[70:73]
	v_mfma_i32_16x16x64_i8 v[126:129], v[150:153], v[202:205], v[126:129]
	v_mfma_i32_16x16x64_i8 v[118:121], v[158:161], v[202:205], v[118:121]
	v_mfma_i32_16x16x64_i8 v[110:113], v[150:153], v[210:213], v[110:113]
	v_mfma_i32_16x16x64_i8 v[102:105], v[158:161], v[210:213], v[102:105]
	v_mfma_i32_16x16x64_i8 v[94:97], v[150:153], v[218:221], v[94:97]
	v_mfma_i32_16x16x64_i8 v[86:89], v[158:161], v[218:221], v[86:89]
	v_mfma_i32_16x16x64_i8 v[78:81], v[150:153], v[226:229], v[78:81]
	v_mfma_i32_16x16x64_i8 v[70:73], v[158:161], v[226:229], v[70:73]
	v_mfma_i32_16x16x64_i8 v[122:125], v[182:185], v[198:201], v[122:125]
	v_mfma_i32_16x16x64_i8 v[114:117], v[190:193], v[198:201], v[114:117]
	v_mfma_i32_16x16x64_i8 v[106:109], v[182:185], v[206:209], v[106:109]
	v_mfma_i32_16x16x64_i8 v[98:101], v[190:193], v[206:209], v[98:101]
	v_mfma_i32_16x16x64_i8 v[90:93], v[182:185], v[214:217], v[90:93]
	v_mfma_i32_16x16x64_i8 v[82:85], v[190:193], v[214:217], v[82:85]
	v_mfma_i32_16x16x64_i8 v[74:77], v[182:185], v[222:225], v[74:77]
	v_mfma_i32_16x16x64_i8 v[66:69], v[190:193], v[222:225], v[66:69]
	v_mfma_i32_16x16x64_i8 v[122:125], v[186:189], v[202:205], v[122:125]
	v_mfma_i32_16x16x64_i8 v[114:117], v[194:197], v[202:205], v[114:117]
	v_mfma_i32_16x16x64_i8 v[106:109], v[186:189], v[210:213], v[106:109]
	v_mfma_i32_16x16x64_i8 v[98:101], v[194:197], v[210:213], v[98:101]
	v_mfma_i32_16x16x64_i8 v[90:93], v[186:189], v[218:221], v[90:93]
	v_mfma_i32_16x16x64_i8 v[82:85], v[194:197], v[218:221], v[82:85]
	v_mfma_i32_16x16x64_i8 v[74:77], v[186:189], v[226:229], v[74:77]
	v_mfma_i32_16x16x64_i8 v[66:69], v[194:197], v[226:229], v[66:69]
	s_setprio 0
	s_barrier
	s_add_i32 s55, s43, s35
	v_lshl_add_u64 v[162:163], s[28:29], 0, v[134:135]
	s_mov_b32 m0, s55
	ds_read_b128 v[198:201], v179 offset:16384
	ds_read_b128 v[202:205], v179 offset:17408
	ds_read_b128 v[206:209], v179 offset:18432
	ds_read_b128 v[210:213], v179 offset:19456
	ds_read_b128 v[214:217], v179 offset:20480
	ds_read_b128 v[218:221], v179 offset:21504
	ds_read_b128 v[222:225], v179 offset:22528
	ds_read_b128 v[226:229], v179 offset:23552
	global_load_lds_dwordx4 v[162:163], off
	s_add_i32 m0, s55, 0x2000
	s_add_u32 s56, s28, 0x40000
	v_lshl_add_u64 v[230:231], s[28:29], 0, v[130:131]
	s_addc_u32 s57, s29, 0
	s_add_i32 s55, s44, s35
	global_load_lds_dwordx4 v[230:231], off
	v_lshl_add_u64 v[232:233], s[56:57], 0, v[134:135]
	s_mov_b32 m0, s55
	v_lshl_add_u64 v[234:235], s[30:31], 0, v[132:133]
	global_load_lds_dwordx4 v[232:233], off
	v_lshl_add_u64 v[232:233], s[56:57], 0, v[130:131]
	s_add_i32 m0, s55, 0x2000
	s_nop 0
	global_load_lds_dwordx4 v[232:233], off
	v_lshl_add_u64 v[232:233], s[30:31], 0, v[136:137]
	s_mov_b32 m0, s25
	s_nop 0
	global_load_lds_dwordx4 v[232:233], off
	s_mov_b32 m0, s37
	s_nop 0
	global_load_lds_dwordx4 v[234:235], off
	s_waitcnt vmcnt(8)
	s_waitcnt lgkmcnt(0)
	s_barrier
	s_setprio 1
	v_mfma_i32_16x16x64_i8 v[62:65], v[146:149], v[198:201], v[62:65]
	v_mfma_i32_16x16x64_i8 v[54:57], v[154:157], v[198:201], v[54:57]
	v_mfma_i32_16x16x64_i8 v[46:49], v[146:149], v[206:209], v[46:49]
	v_mfma_i32_16x16x64_i8 v[38:41], v[154:157], v[206:209], v[38:41]
	v_mfma_i32_16x16x64_i8 v[30:33], v[146:149], v[214:217], v[30:33]
	v_mfma_i32_16x16x64_i8 v[22:25], v[154:157], v[214:217], v[22:25]
	v_mfma_i32_16x16x64_i8 v[14:17], v[146:149], v[222:225], v[14:17]
	v_mfma_i32_16x16x64_i8 v[6:9], v[154:157], v[222:225], v[6:9]
	v_mfma_i32_16x16x64_i8 v[62:65], v[150:153], v[202:205], v[62:65]
	v_mfma_i32_16x16x64_i8 v[54:57], v[158:161], v[202:205], v[54:57]
	v_mfma_i32_16x16x64_i8 v[46:49], v[150:153], v[210:213], v[46:49]
	v_mfma_i32_16x16x64_i8 v[38:41], v[158:161], v[210:213], v[38:41]
	v_mfma_i32_16x16x64_i8 v[30:33], v[150:153], v[218:221], v[30:33]
	v_mfma_i32_16x16x64_i8 v[22:25], v[158:161], v[218:221], v[22:25]
	v_mfma_i32_16x16x64_i8 v[14:17], v[150:153], v[226:229], v[14:17]
	v_mfma_i32_16x16x64_i8 v[6:9], v[158:161], v[226:229], v[6:9]
	v_mfma_i32_16x16x64_i8 v[58:61], v[182:185], v[198:201], v[58:61]
	v_mfma_i32_16x16x64_i8 v[50:53], v[190:193], v[198:201], v[50:53]
	v_mfma_i32_16x16x64_i8 v[42:45], v[182:185], v[206:209], v[42:45]
	v_mfma_i32_16x16x64_i8 v[34:37], v[190:193], v[206:209], v[34:37]
	v_mfma_i32_16x16x64_i8 v[26:29], v[182:185], v[214:217], v[26:29]
	v_mfma_i32_16x16x64_i8 v[18:21], v[190:193], v[214:217], v[18:21]
	v_mfma_i32_16x16x64_i8 v[10:13], v[182:185], v[222:225], v[10:13]
	v_mfma_i32_16x16x64_i8 v[2:5], v[190:193], v[222:225], v[2:5]
	v_mfma_i32_16x16x64_i8 v[58:61], v[186:189], v[202:205], v[58:61]
	v_mfma_i32_16x16x64_i8 v[50:53], v[194:197], v[202:205], v[50:53]
	v_mfma_i32_16x16x64_i8 v[42:45], v[186:189], v[210:213], v[42:45]
	v_mfma_i32_16x16x64_i8 v[34:37], v[194:197], v[210:213], v[34:37]
	v_mfma_i32_16x16x64_i8 v[26:29], v[186:189], v[218:221], v[26:29]
	v_mfma_i32_16x16x64_i8 v[18:21], v[194:197], v[218:221], v[18:21]
	v_mfma_i32_16x16x64_i8 v[10:13], v[186:189], v[226:229], v[10:13]
	v_mfma_i32_16x16x64_i8 v[2:5], v[194:197], v[226:229], v[2:5]
	s_setprio 0
	s_barrier
	s_add_i32 s55, 0, 0x18000
	v_add_u32_e32 v158, s55, v168
	ds_read_b128 v[146:149], v158
	ds_read_b128 v[150:153], v158 offset:1024
	ds_read_b128 v[154:157], v158 offset:2048
	ds_read_b128 v[158:161], v158 offset:3072
	ds_read_b128 v[182:185], v180
	ds_read_b128 v[186:189], v180 offset:1024
	ds_read_b128 v[190:193], v180 offset:2048
	ds_read_b128 v[194:197], v180 offset:3072
	s_add_u32 s30, s30, 0x40000
	s_addc_u32 s31, s31, 0
	s_mov_b32 m0, s38
	v_lshl_add_u64 v[236:237], s[30:31], 0, v[136:137]
	ds_read_b128 v[198:201], v179 offset:32768
	ds_read_b128 v[202:205], v179 offset:33792
	ds_read_b128 v[206:209], v179 offset:34816
	ds_read_b128 v[210:213], v179 offset:35840
	ds_read_b128 v[214:217], v179 offset:36864
	ds_read_b128 v[218:221], v179 offset:37888
	ds_read_b128 v[222:225], v179 offset:38912
	ds_read_b128 v[226:229], v179 offset:39936
	global_load_lds_dwordx4 v[236:237], off
	v_lshl_add_u64 v[236:237], s[30:31], 0, v[132:133]
	s_mov_b32 m0, s39
	s_nop 0
	global_load_lds_dwordx4 v[236:237], off
	s_waitcnt vmcnt(8)
	s_waitcnt lgkmcnt(0)
	s_barrier
	s_setprio 1
	v_mfma_i32_16x16x64_i8 v[126:129], v[146:149], v[198:201], v[126:129]
	v_mfma_i32_16x16x64_i8 v[118:121], v[154:157], v[198:201], v[118:121]
	v_mfma_i32_16x16x64_i8 v[110:113], v[146:149], v[206:209], v[110:113]
	v_mfma_i32_16x16x64_i8 v[102:105], v[154:157], v[206:209], v[102:105]
	v_mfma_i32_16x16x64_i8 v[94:97], v[146:149], v[214:217], v[94:97]
	v_mfma_i32_16x16x64_i8 v[86:89], v[154:157], v[214:217], v[86:89]
	v_mfma_i32_16x16x64_i8 v[78:81], v[146:149], v[222:225], v[78:81]
	v_mfma_i32_16x16x64_i8 v[70:73], v[154:157], v[222:225], v[70:73]
	v_mfma_i32_16x16x64_i8 v[126:129], v[150:153], v[202:205], v[126:129]
	v_mfma_i32_16x16x64_i8 v[118:121], v[158:161], v[202:205], v[118:121]
	v_mfma_i32_16x16x64_i8 v[110:113], v[150:153], v[210:213], v[110:113]
	v_mfma_i32_16x16x64_i8 v[102:105], v[158:161], v[210:213], v[102:105]
	v_mfma_i32_16x16x64_i8 v[94:97], v[150:153], v[218:221], v[94:97]
	v_mfma_i32_16x16x64_i8 v[86:89], v[158:161], v[218:221], v[86:89]
	v_mfma_i32_16x16x64_i8 v[78:81], v[150:153], v[226:229], v[78:81]
	v_mfma_i32_16x16x64_i8 v[70:73], v[158:161], v[226:229], v[70:73]
	v_mfma_i32_16x16x64_i8 v[122:125], v[182:185], v[198:201], v[122:125]
	v_mfma_i32_16x16x64_i8 v[114:117], v[190:193], v[198:201], v[114:117]
	v_mfma_i32_16x16x64_i8 v[106:109], v[182:185], v[206:209], v[106:109]
	v_mfma_i32_16x16x64_i8 v[98:101], v[190:193], v[206:209], v[98:101]
	v_mfma_i32_16x16x64_i8 v[90:93], v[182:185], v[214:217], v[90:93]
	v_mfma_i32_16x16x64_i8 v[82:85], v[190:193], v[214:217], v[82:85]
	v_mfma_i32_16x16x64_i8 v[74:77], v[182:185], v[222:225], v[74:77]
	v_mfma_i32_16x16x64_i8 v[66:69], v[190:193], v[222:225], v[66:69]
	v_mfma_i32_16x16x64_i8 v[122:125], v[186:189], v[202:205], v[122:125]
	v_mfma_i32_16x16x64_i8 v[114:117], v[194:197], v[202:205], v[114:117]
	v_mfma_i32_16x16x64_i8 v[106:109], v[186:189], v[210:213], v[106:109]
	v_mfma_i32_16x16x64_i8 v[98:101], v[194:197], v[210:213], v[98:101]
	v_mfma_i32_16x16x64_i8 v[90:93], v[186:189], v[218:221], v[90:93]
	v_mfma_i32_16x16x64_i8 v[82:85], v[194:197], v[218:221], v[82:85]
	v_mfma_i32_16x16x64_i8 v[74:77], v[186:189], v[226:229], v[74:77]
	v_mfma_i32_16x16x64_i8 v[66:69], v[194:197], v[226:229], v[66:69]
	s_setprio 0
	s_barrier
	s_add_i32 s30, s55, s35
	v_lshl_add_u64 v[162:163], v[162:163], 0, s[8:9]
	s_mov_b32 m0, s30
	ds_read_b128 v[198:201], v179 offset:49152
	ds_read_b128 v[202:205], v179 offset:50176
	ds_read_b128 v[206:209], v179 offset:51200
	ds_read_b128 v[210:213], v179 offset:52224
	ds_read_b128 v[214:217], v179 offset:53248
	ds_read_b128 v[218:221], v179 offset:54272
	ds_read_b128 v[222:225], v179 offset:55296
	ds_read_b128 v[226:229], v179 offset:56320
	global_load_lds_dwordx4 v[162:163], off
	s_add_i32 m0, s30, 0x2000
	s_add_u32 s28, s28, 0x40080
	v_lshl_add_u64 v[162:163], v[230:231], 0, s[8:9]
	s_addc_u32 s29, s29, 0
	s_add_i32 s30, s45, s35
	global_load_lds_dwordx4 v[162:163], off
	v_lshl_add_u64 v[162:163], s[28:29], 0, v[134:135]
	s_mov_b32 m0, s30
	s_nop 0
	global_load_lds_dwordx4 v[162:163], off
	v_lshl_add_u64 v[162:163], s[28:29], 0, v[130:131]
	s_add_i32 m0, s30, 0x2000
	s_nop 0
	global_load_lds_dwordx4 v[162:163], off
	v_lshl_add_u64 v[162:163], v[232:233], 0, s[8:9]
	s_mov_b32 m0, s40
	s_nop 0
	global_load_lds_dwordx4 v[162:163], off
	v_lshl_add_u64 v[162:163], v[234:235], 0, s[8:9]
	s_mov_b32 m0, s41
	s_nop 0
	global_load_lds_dwordx4 v[162:163], off
	s_waitcnt vmcnt(8)
	s_waitcnt lgkmcnt(0)
	s_barrier
	s_setprio 1
	v_mfma_i32_16x16x64_i8 v[62:65], v[146:149], v[198:201], v[62:65]
	v_mfma_i32_16x16x64_i8 v[54:57], v[154:157], v[198:201], v[54:57]
	v_mfma_i32_16x16x64_i8 v[46:49], v[146:149], v[206:209], v[46:49]
	v_mfma_i32_16x16x64_i8 v[38:41], v[154:157], v[206:209], v[38:41]
	v_mfma_i32_16x16x64_i8 v[30:33], v[146:149], v[214:217], v[30:33]
	v_mfma_i32_16x16x64_i8 v[22:25], v[154:157], v[214:217], v[22:25]
	v_mfma_i32_16x16x64_i8 v[14:17], v[146:149], v[222:225], v[14:17]
	v_mfma_i32_16x16x64_i8 v[6:9], v[154:157], v[222:225], v[6:9]
	v_mfma_i32_16x16x64_i8 v[62:65], v[150:153], v[202:205], v[62:65]
	v_mfma_i32_16x16x64_i8 v[54:57], v[158:161], v[202:205], v[54:57]
	v_mfma_i32_16x16x64_i8 v[46:49], v[150:153], v[210:213], v[46:49]
	v_mfma_i32_16x16x64_i8 v[38:41], v[158:161], v[210:213], v[38:41]
	v_mfma_i32_16x16x64_i8 v[30:33], v[150:153], v[218:221], v[30:33]
	v_mfma_i32_16x16x64_i8 v[22:25], v[158:161], v[218:221], v[22:25]
	v_mfma_i32_16x16x64_i8 v[14:17], v[150:153], v[226:229], v[14:17]
	v_mfma_i32_16x16x64_i8 v[6:9], v[158:161], v[226:229], v[6:9]
	v_mfma_i32_16x16x64_i8 v[58:61], v[182:185], v[198:201], v[58:61]
	v_mfma_i32_16x16x64_i8 v[50:53], v[190:193], v[198:201], v[50:53]
	v_mfma_i32_16x16x64_i8 v[42:45], v[182:185], v[206:209], v[42:45]
	v_mfma_i32_16x16x64_i8 v[34:37], v[190:193], v[206:209], v[34:37]
	v_mfma_i32_16x16x64_i8 v[26:29], v[182:185], v[214:217], v[26:29]
	v_mfma_i32_16x16x64_i8 v[18:21], v[190:193], v[214:217], v[18:21]
	v_mfma_i32_16x16x64_i8 v[10:13], v[182:185], v[222:225], v[10:13]
	v_mfma_i32_16x16x64_i8 v[2:5], v[190:193], v[222:225], v[2:5]
	v_mfma_i32_16x16x64_i8 v[58:61], v[186:189], v[202:205], v[58:61]
	v_mfma_i32_16x16x64_i8 v[50:53], v[194:197], v[202:205], v[50:53]
	v_mfma_i32_16x16x64_i8 v[42:45], v[186:189], v[210:213], v[42:45]
	v_mfma_i32_16x16x64_i8 v[34:37], v[194:197], v[210:213], v[34:37]
	v_mfma_i32_16x16x64_i8 v[26:29], v[186:189], v[218:221], v[26:29]
	v_mfma_i32_16x16x64_i8 v[18:21], v[194:197], v[218:221], v[18:21]
	v_mfma_i32_16x16x64_i8 v[10:13], v[186:189], v[226:229], v[10:13]
	v_mfma_i32_16x16x64_i8 v[2:5], v[194:197], v[226:229], v[2:5]
	s_setprio 0
	s_barrier
	s_add_i32 s54, s54, 2
	s_add_u32 s26, s26, 0x100
	s_addc_u32 s27, s27, 0
	s_add_u32 s52, s52, 0x100
	s_addc_u32 s53, s53, 0
	s_cmp_gt_u32 s54, 13
	s_cbranch_scc0 .LBB0_3387
	s_and_b64 vcc, exec, s[12:13]
	s_cbranch_vccz .LBB0_3390
	s_barrier

.LBB0_3496:
	ds_read_b128 v[154:157], v149
	ds_read_b128 v[158:161], v149 offset:1024
	ds_read_b128 v[162:165], v149 offset:2048
	ds_read_b128 v[168:171], v149 offset:3072
	ds_read_b128 v[172:175], v150
	ds_read_b128 v[176:179], v150 offset:1024
	ds_read_b128 v[180:183], v150 offset:2048
	ds_read_b128 v[184:187], v150 offset:3072
	s_add_u32 s26, s24, 0xffea0080
	s_addc_u32 s27, s25, -1
	s_cmpk_eq_i32 s55, 0x54
	s_cselect_b32 s29, s5, s27
	s_cselect_b32 s28, s4, s26
	s_cselect_b32 s27, s23, s54
	s_cselect_b32 s26, s22, s53
	v_lshl_add_u64 v[146:147], s[24:25], 0, v[138:139]
	s_add_i32 m0, s31, 0xc000
	ds_read_b128 v[188:191], v151
	ds_read_b128 v[192:195], v151 offset:1024
	ds_read_b128 v[196:199], v151 offset:2048
	ds_read_b128 v[200:203], v151 offset:3072
	ds_read_b128 v[204:207], v151 offset:4096
	ds_read_b128 v[208:211], v151 offset:5120
	ds_read_b128 v[212:215], v151 offset:6144
	ds_read_b128 v[216:219], v151 offset:7168
	global_load_lds_dwordx4 v[146:147], off
	v_lshl_add_u64 v[146:147], s[24:25], 0, v[140:141]
	s_add_i32 m0, s31, 0xe000
	s_nop 0
	global_load_lds_dwordx4 v[146:147], off
	s_waitcnt vmcnt(8)
	s_waitcnt lgkmcnt(0)
	s_barrier
	s_setprio 1
	v_mfma_f32_16x16x32_bf16 v[126:129], v[154:157], v[188:191], v[126:129]
	v_mfma_f32_16x16x32_bf16 v[122:125], v[162:165], v[188:191], v[122:125]
	v_mfma_f32_16x16x32_bf16 v[118:121], v[154:157], v[196:199], v[118:121]
	v_mfma_f32_16x16x32_bf16 v[110:113], v[162:165], v[196:199], v[110:113]
	v_mfma_f32_16x16x32_bf16 v[102:105], v[154:157], v[204:207], v[102:105]
	v_mfma_f32_16x16x32_bf16 v[94:97], v[162:165], v[204:207], v[94:97]
	v_mfma_f32_16x16x32_bf16 v[86:89], v[154:157], v[212:215], v[86:89]
	v_mfma_f32_16x16x32_bf16 v[78:81], v[162:165], v[212:215], v[78:81]
	v_mfma_f32_16x16x32_bf16 v[126:129], v[158:161], v[192:195], v[126:129]
	v_mfma_f32_16x16x32_bf16 v[122:125], v[168:171], v[192:195], v[122:125]
	v_mfma_f32_16x16x32_bf16 v[118:121], v[158:161], v[200:203], v[118:121]
	v_mfma_f32_16x16x32_bf16 v[110:113], v[168:171], v[200:203], v[110:113]
	v_mfma_f32_16x16x32_bf16 v[102:105], v[158:161], v[208:211], v[102:105]
	v_mfma_f32_16x16x32_bf16 v[94:97], v[168:171], v[208:211], v[94:97]
	v_mfma_f32_16x16x32_bf16 v[86:89], v[158:161], v[216:219], v[86:89]
	v_mfma_f32_16x16x32_bf16 v[78:81], v[168:171], v[216:219], v[78:81]
	v_mfma_f32_16x16x32_bf16 v[114:117], v[172:175], v[188:191], v[114:117]
	v_mfma_f32_16x16x32_bf16 v[106:109], v[180:183], v[188:191], v[106:109]
	v_mfma_f32_16x16x32_bf16 v[98:101], v[172:175], v[196:199], v[98:101]
	v_mfma_f32_16x16x32_bf16 v[90:93], v[180:183], v[196:199], v[90:93]
	v_mfma_f32_16x16x32_bf16 v[82:85], v[172:175], v[204:207], v[82:85]
	v_mfma_f32_16x16x32_bf16 v[74:77], v[180:183], v[204:207], v[74:77]
	v_mfma_f32_16x16x32_bf16 v[70:73], v[172:175], v[212:215], v[70:73]
	v_mfma_f32_16x16x32_bf16 v[66:69], v[180:183], v[212:215], v[66:69]
	v_mfma_f32_16x16x32_bf16 v[114:117], v[176:179], v[192:195], v[114:117]
	v_mfma_f32_16x16x32_bf16 v[106:109], v[184:187], v[192:195], v[106:109]
	v_mfma_f32_16x16x32_bf16 v[98:101], v[176:179], v[200:203], v[98:101]
	v_mfma_f32_16x16x32_bf16 v[90:93], v[184:187], v[200:203], v[90:93]
	v_mfma_f32_16x16x32_bf16 v[82:85], v[176:179], v[208:211], v[82:85]
	v_mfma_f32_16x16x32_bf16 v[74:77], v[184:187], v[208:211], v[74:77]
	v_mfma_f32_16x16x32_bf16 v[70:73], v[176:179], v[216:219], v[70:73]
	v_mfma_f32_16x16x32_bf16 v[66:69], v[184:187], v[216:219], v[66:69]
	s_setprio 0
	s_barrier
	s_add_i32 s56, s41, s30
	v_lshl_add_u64 v[146:147], s[26:27], 0, v[132:133]
	s_mov_b32 m0, s56
	ds_read_b128 v[188:191], v151 offset:16384
	ds_read_b128 v[192:195], v151 offset:17408
	ds_read_b128 v[196:199], v151 offset:18432
	ds_read_b128 v[200:203], v151 offset:19456
	ds_read_b128 v[204:207], v151 offset:20480
	ds_read_b128 v[208:211], v151 offset:21504
	ds_read_b128 v[212:215], v151 offset:22528
	ds_read_b128 v[216:219], v151 offset:23552
	global_load_lds_dwordx4 v[146:147], off
	s_add_i32 m0, s56, 0x2000
	s_add_u32 s56, s26, 0x160000
	v_lshl_add_u64 v[220:221], s[26:27], 0, v[136:137]
	s_addc_u32 s57, s27, 0
	s_add_i32 s63, s42, s30
	global_load_lds_dwordx4 v[220:221], off
	v_lshl_add_u64 v[222:223], s[56:57], 0, v[132:133]
	s_mov_b32 m0, s63
	v_lshl_add_u64 v[224:225], s[28:29], 0, v[134:135]
	global_load_lds_dwordx4 v[222:223], off
	v_lshl_add_u64 v[222:223], s[56:57], 0, v[136:137]
	s_add_i32 m0, s63, 0x2000
	s_nop 0
	global_load_lds_dwordx4 v[222:223], off
	v_lshl_add_u64 v[222:223], s[28:29], 0, v[130:131]
	s_mov_b32 m0, s31
	s_nop 0
	global_load_lds_dwordx4 v[222:223], off
	s_mov_b32 m0, s34
	s_nop 0
	global_load_lds_dwordx4 v[224:225], off
	s_waitcnt vmcnt(8)
	s_waitcnt lgkmcnt(0)
	s_barrier
	s_setprio 1
	v_mfma_f32_16x16x32_bf16 v[62:65], v[154:157], v[188:191], v[62:65]
	v_mfma_f32_16x16x32_bf16 v[58:61], v[162:165], v[188:191], v[58:61]
	v_mfma_f32_16x16x32_bf16 v[54:57], v[154:157], v[196:199], v[54:57]
	v_mfma_f32_16x16x32_bf16 v[46:49], v[162:165], v[196:199], v[46:49]
	v_mfma_f32_16x16x32_bf16 v[38:41], v[154:157], v[204:207], v[38:41]
	v_mfma_f32_16x16x32_bf16 v[30:33], v[162:165], v[204:207], v[30:33]
	v_mfma_f32_16x16x32_bf16 v[22:25], v[154:157], v[212:215], v[22:25]
	v_mfma_f32_16x16x32_bf16 v[14:17], v[162:165], v[212:215], v[14:17]
	v_mfma_f32_16x16x32_bf16 v[62:65], v[158:161], v[192:195], v[62:65]
	v_mfma_f32_16x16x32_bf16 v[58:61], v[168:171], v[192:195], v[58:61]
	v_mfma_f32_16x16x32_bf16 v[54:57], v[158:161], v[200:203], v[54:57]
	v_mfma_f32_16x16x32_bf16 v[46:49], v[168:171], v[200:203], v[46:49]
	v_mfma_f32_16x16x32_bf16 v[38:41], v[158:161], v[208:211], v[38:41]
	v_mfma_f32_16x16x32_bf16 v[30:33], v[168:171], v[208:211], v[30:33]
	v_mfma_f32_16x16x32_bf16 v[22:25], v[158:161], v[216:219], v[22:25]
	v_mfma_f32_16x16x32_bf16 v[14:17], v[168:171], v[216:219], v[14:17]
	v_mfma_f32_16x16x32_bf16 v[50:53], v[172:175], v[188:191], v[50:53]
	v_mfma_f32_16x16x32_bf16 v[42:45], v[180:183], v[188:191], v[42:45]
	v_mfma_f32_16x16x32_bf16 v[34:37], v[172:175], v[196:199], v[34:37]
	v_mfma_f32_16x16x32_bf16 v[26:29], v[180:183], v[196:199], v[26:29]
	v_mfma_f32_16x16x32_bf16 v[18:21], v[172:175], v[204:207], v[18:21]
	v_mfma_f32_16x16x32_bf16 v[10:13], v[180:183], v[204:207], v[10:13]
	v_mfma_f32_16x16x32_bf16 v[6:9], v[172:175], v[212:215], v[6:9]
	v_mfma_f32_16x16x32_bf16 v[2:5], v[180:183], v[212:215], v[2:5]
	v_mfma_f32_16x16x32_bf16 v[50:53], v[176:179], v[192:195], v[50:53]
	v_mfma_f32_16x16x32_bf16 v[42:45], v[184:187], v[192:195], v[42:45]
	v_mfma_f32_16x16x32_bf16 v[34:37], v[176:179], v[200:203], v[34:37]
	v_mfma_f32_16x16x32_bf16 v[26:29], v[184:187], v[200:203], v[26:29]
	v_mfma_f32_16x16x32_bf16 v[18:21], v[176:179], v[208:211], v[18:21]
	v_mfma_f32_16x16x32_bf16 v[10:13], v[184:187], v[208:211], v[10:13]
	v_mfma_f32_16x16x32_bf16 v[6:9], v[176:179], v[216:219], v[6:9]
	v_mfma_f32_16x16x32_bf16 v[2:5], v[184:187], v[216:219], v[2:5]
	s_setprio 0
	s_barrier
	ds_read_b128 v[154:157], v152
	ds_read_b128 v[158:161], v152 offset:1024
	ds_read_b128 v[162:165], v152 offset:2048
	ds_read_b128 v[168:171], v152 offset:3072
	ds_read_b128 v[172:175], v153
	ds_read_b128 v[176:179], v153 offset:1024
	ds_read_b128 v[180:183], v153 offset:2048
	ds_read_b128 v[184:187], v153 offset:3072
	s_add_u32 s28, s28, 0x160000
	s_addc_u32 s29, s29, 0
	s_mov_b32 m0, s35
	v_lshl_add_u64 v[226:227], s[28:29], 0, v[130:131]
	ds_read_b128 v[188:191], v151 offset:32768
	ds_read_b128 v[192:195], v151 offset:33792
	ds_read_b128 v[196:199], v151 offset:34816
	ds_read_b128 v[200:203], v151 offset:35840
	ds_read_b128 v[204:207], v151 offset:36864
	ds_read_b128 v[208:211], v151 offset:37888
	ds_read_b128 v[212:215], v151 offset:38912
	ds_read_b128 v[216:219], v151 offset:39936
	global_load_lds_dwordx4 v[226:227], off
	v_lshl_add_u64 v[226:227], s[28:29], 0, v[134:135]
	s_mov_b32 m0, s36
	s_nop 0
	global_load_lds_dwordx4 v[226:227], off
	s_waitcnt vmcnt(8)
	s_waitcnt lgkmcnt(0)
	s_barrier
	s_setprio 1
	v_mfma_f32_16x16x32_bf16 v[126:129], v[154:157], v[188:191], v[126:129]
	v_mfma_f32_16x16x32_bf16 v[122:125], v[162:165], v[188:191], v[122:125]
	v_mfma_f32_16x16x32_bf16 v[118:121], v[154:157], v[196:199], v[118:121]
	v_mfma_f32_16x16x32_bf16 v[110:113], v[162:165], v[196:199], v[110:113]
	v_mfma_f32_16x16x32_bf16 v[102:105], v[154:157], v[204:207], v[102:105]
	v_mfma_f32_16x16x32_bf16 v[94:97], v[162:165], v[204:207], v[94:97]
	v_mfma_f32_16x16x32_bf16 v[86:89], v[154:157], v[212:215], v[86:89]
	v_mfma_f32_16x16x32_bf16 v[78:81], v[162:165], v[212:215], v[78:81]
	v_mfma_f32_16x16x32_bf16 v[126:129], v[158:161], v[192:195], v[126:129]
	v_mfma_f32_16x16x32_bf16 v[122:125], v[168:171], v[192:195], v[122:125]
	v_mfma_f32_16x16x32_bf16 v[118:121], v[158:161], v[200:203], v[118:121]
	v_mfma_f32_16x16x32_bf16 v[110:113], v[168:171], v[200:203], v[110:113]
	v_mfma_f32_16x16x32_bf16 v[102:105], v[158:161], v[208:211], v[102:105]
	v_mfma_f32_16x16x32_bf16 v[94:97], v[168:171], v[208:211], v[94:97]
	v_mfma_f32_16x16x32_bf16 v[86:89], v[158:161], v[216:219], v[86:89]
	v_mfma_f32_16x16x32_bf16 v[78:81], v[168:171], v[216:219], v[78:81]
	v_mfma_f32_16x16x32_bf16 v[114:117], v[172:175], v[188:191], v[114:117]
	v_mfma_f32_16x16x32_bf16 v[106:109], v[180:183], v[188:191], v[106:109]
	v_mfma_f32_16x16x32_bf16 v[98:101], v[172:175], v[196:199], v[98:101]
	v_mfma_f32_16x16x32_bf16 v[90:93], v[180:183], v[196:199], v[90:93]
	v_mfma_f32_16x16x32_bf16 v[82:85], v[172:175], v[204:207], v[82:85]
	v_mfma_f32_16x16x32_bf16 v[74:77], v[180:183], v[204:207], v[74:77]
	v_mfma_f32_16x16x32_bf16 v[70:73], v[172:175], v[212:215], v[70:73]
	v_mfma_f32_16x16x32_bf16 v[66:69], v[180:183], v[212:215], v[66:69]
	v_mfma_f32_16x16x32_bf16 v[114:117], v[176:179], v[192:195], v[114:117]
	v_mfma_f32_16x16x32_bf16 v[106:109], v[184:187], v[192:195], v[106:109]
	v_mfma_f32_16x16x32_bf16 v[98:101], v[176:179], v[200:203], v[98:101]
	v_mfma_f32_16x16x32_bf16 v[90:93], v[184:187], v[200:203], v[90:93]
	v_mfma_f32_16x16x32_bf16 v[82:85], v[176:179], v[208:211], v[82:85]
	v_mfma_f32_16x16x32_bf16 v[74:77], v[184:187], v[208:211], v[74:77]
	v_mfma_f32_16x16x32_bf16 v[70:73], v[176:179], v[216:219], v[70:73]
	v_mfma_f32_16x16x32_bf16 v[66:69], v[184:187], v[216:219], v[66:69]
	s_setprio 0
	s_barrier
	s_add_i32 s28, s43, s30
	v_lshl_add_u64 v[146:147], v[146:147], 0, s[6:7]
	s_mov_b32 m0, s28
	ds_read_b128 v[188:191], v151 offset:49152
	ds_read_b128 v[192:195], v151 offset:50176
	ds_read_b128 v[196:199], v151 offset:51200
	ds_read_b128 v[200:203], v151 offset:52224
	ds_read_b128 v[204:207], v151 offset:53248
	ds_read_b128 v[208:211], v151 offset:54272
	ds_read_b128 v[212:215], v151 offset:55296
	ds_read_b128 v[216:219], v151 offset:56320
	global_load_lds_dwordx4 v[146:147], off
	s_add_i32 m0, s28, 0x2000
	s_add_u32 s26, s26, 0x160080
	v_lshl_add_u64 v[146:147], v[220:221], 0, s[6:7]
	s_addc_u32 s27, s27, 0
	s_add_i32 s28, s44, s30
	global_load_lds_dwordx4 v[146:147], off
	v_lshl_add_u64 v[146:147], s[26:27], 0, v[132:133]
	s_mov_b32 m0, s28
	s_nop 0
	global_load_lds_dwordx4 v[146:147], off
	v_lshl_add_u64 v[146:147], s[26:27], 0, v[136:137]
	s_add_i32 m0, s28, 0x2000
	s_nop 0
	global_load_lds_dwordx4 v[146:147], off
	v_lshl_add_u64 v[146:147], v[222:223], 0, s[6:7]
	s_mov_b32 m0, s37
	s_nop 0
	global_load_lds_dwordx4 v[146:147], off
	v_lshl_add_u64 v[146:147], v[224:225], 0, s[6:7]
	s_mov_b32 m0, s38
	s_nop 0
	global_load_lds_dwordx4 v[146:147], off
	s_waitcnt vmcnt(8)
	s_waitcnt lgkmcnt(0)
	s_barrier
	s_setprio 1
	v_mfma_f32_16x16x32_bf16 v[62:65], v[154:157], v[188:191], v[62:65]
	v_mfma_f32_16x16x32_bf16 v[58:61], v[162:165], v[188:191], v[58:61]
	v_mfma_f32_16x16x32_bf16 v[54:57], v[154:157], v[196:199], v[54:57]
	v_mfma_f32_16x16x32_bf16 v[46:49], v[162:165], v[196:199], v[46:49]
	v_mfma_f32_16x16x32_bf16 v[38:41], v[154:157], v[204:207], v[38:41]
	v_mfma_f32_16x16x32_bf16 v[30:33], v[162:165], v[204:207], v[30:33]
	v_mfma_f32_16x16x32_bf16 v[22:25], v[154:157], v[212:215], v[22:25]
	v_mfma_f32_16x16x32_bf16 v[14:17], v[162:165], v[212:215], v[14:17]
	v_mfma_f32_16x16x32_bf16 v[62:65], v[158:161], v[192:195], v[62:65]
	v_mfma_f32_16x16x32_bf16 v[58:61], v[168:171], v[192:195], v[58:61]
	v_mfma_f32_16x16x32_bf16 v[54:57], v[158:161], v[200:203], v[54:57]
	v_mfma_f32_16x16x32_bf16 v[46:49], v[168:171], v[200:203], v[46:49]
	v_mfma_f32_16x16x32_bf16 v[38:41], v[158:161], v[208:211], v[38:41]
	v_mfma_f32_16x16x32_bf16 v[30:33], v[168:171], v[208:211], v[30:33]
	v_mfma_f32_16x16x32_bf16 v[22:25], v[158:161], v[216:219], v[22:25]
	v_mfma_f32_16x16x32_bf16 v[14:17], v[168:171], v[216:219], v[14:17]
	v_mfma_f32_16x16x32_bf16 v[50:53], v[172:175], v[188:191], v[50:53]
	v_mfma_f32_16x16x32_bf16 v[42:45], v[180:183], v[188:191], v[42:45]
	v_mfma_f32_16x16x32_bf16 v[34:37], v[172:175], v[196:199], v[34:37]
	v_mfma_f32_16x16x32_bf16 v[26:29], v[180:183], v[196:199], v[26:29]
	v_mfma_f32_16x16x32_bf16 v[18:21], v[172:175], v[204:207], v[18:21]
	v_mfma_f32_16x16x32_bf16 v[10:13], v[180:183], v[204:207], v[10:13]
	v_mfma_f32_16x16x32_bf16 v[6:9], v[172:175], v[212:215], v[6:9]
	v_mfma_f32_16x16x32_bf16 v[2:5], v[180:183], v[212:215], v[2:5]
	v_mfma_f32_16x16x32_bf16 v[50:53], v[176:179], v[192:195], v[50:53]
	v_mfma_f32_16x16x32_bf16 v[42:45], v[184:187], v[192:195], v[42:45]
	v_mfma_f32_16x16x32_bf16 v[34:37], v[176:179], v[200:203], v[34:37]
	v_mfma_f32_16x16x32_bf16 v[26:29], v[184:187], v[200:203], v[26:29]
	v_mfma_f32_16x16x32_bf16 v[18:21], v[176:179], v[208:211], v[18:21]
	v_mfma_f32_16x16x32_bf16 v[10:13], v[184:187], v[208:211], v[10:13]
	v_mfma_f32_16x16x32_bf16 v[6:9], v[176:179], v[216:219], v[6:9]
	v_mfma_f32_16x16x32_bf16 v[2:5], v[184:187], v[216:219], v[2:5]
	s_setprio 0
	s_barrier
	s_add_i32 s55, s55, 2
	s_add_u32 s24, s24, 0x100
	s_addc_u32 s25, s25, 0
	s_add_u32 s53, s53, 0x100
	s_addc_u32 s54, s54, 0
	s_cmpk_gt_u32 s55, 0x55
	s_cbranch_scc0 .LBB0_3496
	s_and_b64 vcc, exec, s[12:13]
	s_cbranch_vccz .LBB0_3499
	s_barrier
